# MFMA segments: accumulator pairs ordered so consecutive pairs share the first operand registers
# speedup vs baseline: 1.0086x; 1.0086x over previous
.Lmid1_446:
	s_add_i32 s22, 0, 0x10000
	s_add_i32 s23, 0, 0x14000
	s_add_u32 s20, s56, 0xfff50080
	s_addc_u32 s21, s57, -1
	s_cmp_eq_u32 s84, 40
	s_cselect_b32 s61, s49, s21
	s_cselect_b32 s60, s48, s20
	s_cselect_b32 s21, s51, s63
	s_cselect_b32 s20, s50, s62
	s_add_i32 m0, s47, 0xc000
	v_lshl_add_u64 v[162:163], s[56:57], 0, v[156:157]
	global_load_lds_dwordx4 v[162:163], off
	v_lshl_add_u64 v[162:163], v[162:163], 0, s[2:3]
	s_add_i32 m0, s47, 0xe000
	s_nop 0
	global_load_lds_dwordx4 v[162:163], off
	s_waitcnt vmcnt(8)
	s_waitcnt lgkmcnt(0)
	s_barrier
	s_setprio 1
	s_waitcnt lgkmcnt(0)
	v_mfma_f32_16x16x32_bf16 v[142:145], v[114:117], v[186:189], 0
	v_mfma_f32_16x16x32_bf16 v[142:145], v[126:129], v[194:197], v[142:145]
	v_mfma_f32_16x16x32_bf16 v[110:113], v[114:117], v[198:201], 0
	v_mfma_f32_16x16x32_bf16 v[110:113], v[126:129], v[214:217], v[110:113]
	v_mfma_f32_16x16x32_bf16 v[94:97], v[114:117], v[218:221], 0
	v_mfma_f32_16x16x32_bf16 v[94:97], v[126:129], v[222:225], v[94:97]
	v_mfma_f32_16x16x32_bf16 v[78:81], v[114:117], v[226:229], 0
	v_mfma_f32_16x16x32_bf16 v[78:81], v[126:129], v[230:233], v[78:81]
	v_mfma_f32_16x16x32_bf16 v[138:141], v[130:133], v[186:189], 0
	v_mfma_f32_16x16x32_bf16 v[138:141], v[134:137], v[194:197], v[138:141]
	v_mfma_f32_16x16x32_bf16 v[106:109], v[130:133], v[198:201], 0
	v_mfma_f32_16x16x32_bf16 v[106:109], v[134:137], v[214:217], v[106:109]
	v_mfma_f32_16x16x32_bf16 v[90:93], v[130:133], v[218:221], 0
	v_mfma_f32_16x16x32_bf16 v[90:93], v[134:137], v[222:225], v[90:93]
	v_mfma_f32_16x16x32_bf16 v[74:77], v[130:133], v[226:229], 0
	v_mfma_f32_16x16x32_bf16 v[74:77], v[134:137], v[230:233], v[74:77]
	s_setprio 0
	s_setprio 1
	v_mfma_f32_16x16x32_bf16 v[122:125], v[146:149], v[186:189], 0
	v_mfma_f32_16x16x32_bf16 v[122:125], v[150:153], v[194:197], v[122:125]
	v_mfma_f32_16x16x32_bf16 v[102:105], v[146:149], v[198:201], 0
	v_mfma_f32_16x16x32_bf16 v[102:105], v[150:153], v[214:217], v[102:105]
	v_mfma_f32_16x16x32_bf16 v[86:89], v[146:149], v[218:221], 0
	v_mfma_f32_16x16x32_bf16 v[86:89], v[150:153], v[222:225], v[86:89]
	v_mfma_f32_16x16x32_bf16 v[70:73], v[146:149], v[226:229], 0
	v_mfma_f32_16x16x32_bf16 v[70:73], v[150:153], v[230:233], v[70:73]
	v_mfma_f32_16x16x32_bf16 v[118:121], v[158:161], v[186:189], 0
	v_mfma_f32_16x16x32_bf16 v[118:121], v[182:185], v[194:197], v[118:121]
	v_mfma_f32_16x16x32_bf16 v[98:101], v[158:161], v[198:201], 0
	v_mfma_f32_16x16x32_bf16 v[98:101], v[182:185], v[214:217], v[98:101]
	v_mfma_f32_16x16x32_bf16 v[82:85], v[158:161], v[218:221], 0
	v_mfma_f32_16x16x32_bf16 v[82:85], v[182:185], v[222:225], v[82:85]
	v_mfma_f32_16x16x32_bf16 v[66:69], v[158:161], v[226:229], 0
	v_mfma_f32_16x16x32_bf16 v[66:69], v[182:185], v[230:233], v[66:69]
	s_setprio 0
	s_barrier
	ds_read_b128 v[186:189], v193 offset:16384
	ds_read_b128 v[194:197], v193 offset:17408
	ds_read_b128 v[198:201], v193 offset:18432
	ds_read_b128 v[214:217], v193 offset:19456
	ds_read_b128 v[218:221], v193 offset:20480
	ds_read_b128 v[222:225], v193 offset:21504
	ds_read_b128 v[226:229], v193 offset:22528
	ds_read_b128 v[230:233], v193 offset:23552
	v_lshl_add_u64 v[162:163], s[20:21], 0, v[0:1]
	s_add_i32 s20, s22, s46
	s_mov_b32 m0, s20
	s_nop 0
	s_nop 0
	global_load_lds_dwordx4 v[162:163], off
	v_lshl_add_u64 v[202:203], v[162:163], 0, s[2:3]
	s_add_i32 m0, s20, 0x2000
	s_add_i32 s20, s23, s46
	global_load_lds_dwordx4 v[202:203], off
	v_lshl_add_u64 v[202:203], v[162:163], 0, s[12:13]
	s_mov_b32 m0, s20
	s_nop 0
	global_load_lds_dwordx4 v[202:203], off
	v_lshl_add_u64 v[202:203], v[162:163], 0, s[86:87]
	s_add_i32 m0, s20, 0x2000
	s_nop 0
	global_load_lds_dwordx4 v[202:203], off
	v_lshl_add_u64 v[202:203], s[60:61], 0, v[154:155]
	s_mov_b32 m0, s47
	v_lshl_add_u64 v[234:235], v[202:203], 0, s[2:3]
	global_load_lds_dwordx4 v[202:203], off
	s_mov_b32 m0, s68
	s_nop 0
	global_load_lds_dwordx4 v[234:235], off
	s_waitcnt vmcnt(8)
	s_waitcnt lgkmcnt(0)
	s_barrier
	s_setprio 1
	s_waitcnt lgkmcnt(0)
	v_mfma_f32_16x16x32_bf16 v[62:65], v[114:117], v[186:189], 0
	v_mfma_f32_16x16x32_bf16 v[62:65], v[126:129], v[194:197], v[62:65]
	v_mfma_f32_16x16x32_bf16 v[46:49], v[114:117], v[198:201], 0
	v_mfma_f32_16x16x32_bf16 v[46:49], v[126:129], v[214:217], v[46:49]
	v_mfma_f32_16x16x32_bf16 v[30:33], v[114:117], v[218:221], 0
	v_mfma_f32_16x16x32_bf16 v[30:33], v[126:129], v[222:225], v[30:33]
	v_mfma_f32_16x16x32_bf16 v[14:17], v[114:117], v[226:229], 0
	v_mfma_f32_16x16x32_bf16 v[14:17], v[126:129], v[230:233], v[14:17]
	v_mfma_f32_16x16x32_bf16 v[58:61], v[130:133], v[186:189], 0
	v_mfma_f32_16x16x32_bf16 v[58:61], v[134:137], v[194:197], v[58:61]
	v_mfma_f32_16x16x32_bf16 v[42:45], v[130:133], v[198:201], 0
	v_mfma_f32_16x16x32_bf16 v[42:45], v[134:137], v[214:217], v[42:45]
	v_mfma_f32_16x16x32_bf16 v[26:29], v[130:133], v[218:221], 0
	v_mfma_f32_16x16x32_bf16 v[26:29], v[134:137], v[222:225], v[26:29]
	v_mfma_f32_16x16x32_bf16 v[10:13], v[130:133], v[226:229], 0
	v_mfma_f32_16x16x32_bf16 v[10:13], v[134:137], v[230:233], v[10:13]
	s_setprio 0
	s_setprio 1
	v_mfma_f32_16x16x32_bf16 v[54:57], v[146:149], v[186:189], 0
	v_mfma_f32_16x16x32_bf16 v[54:57], v[150:153], v[194:197], v[54:57]
	v_mfma_f32_16x16x32_bf16 v[38:41], v[146:149], v[198:201], 0
	v_mfma_f32_16x16x32_bf16 v[38:41], v[150:153], v[214:217], v[38:41]
	v_mfma_f32_16x16x32_bf16 v[22:25], v[146:149], v[218:221], 0
	v_mfma_f32_16x16x32_bf16 v[22:25], v[150:153], v[222:225], v[22:25]
	v_mfma_f32_16x16x32_bf16 v[6:9], v[146:149], v[226:229], 0
	v_mfma_f32_16x16x32_bf16 v[6:9], v[150:153], v[230:233], v[6:9]
	v_mfma_f32_16x16x32_bf16 v[50:53], v[158:161], v[186:189], 0
	v_mfma_f32_16x16x32_bf16 v[50:53], v[182:185], v[194:197], v[50:53]
	v_mfma_f32_16x16x32_bf16 v[34:37], v[158:161], v[198:201], 0
	v_mfma_f32_16x16x32_bf16 v[34:37], v[182:185], v[214:217], v[34:37]
	v_mfma_f32_16x16x32_bf16 v[18:21], v[158:161], v[218:221], 0
	v_mfma_f32_16x16x32_bf16 v[18:21], v[182:185], v[222:225], v[18:21]
	v_mfma_f32_16x16x32_bf16 v[2:5], v[158:161], v[226:229], 0
	v_mfma_f32_16x16x32_bf16 v[2:5], v[182:185], v[230:233], v[2:5]
	s_setprio 0
	s_barrier
	s_add_i32 s20, 0, 0x18000
	s_add_i32 s21, 0, 0x1c000
	v_add_u32_e32 v134, s20, v191
	v_add_u32_e32 v182, s21, v191
	ds_read_b128 v[114:117], v134
	ds_read_b128 v[126:129], v134 offset:1024
	ds_read_b128 v[130:133], v134 offset:2048
	ds_read_b128 v[134:137], v134 offset:3072
	ds_read_b128 v[146:149], v182
	ds_read_b128 v[150:153], v182 offset:1024
	ds_read_b128 v[158:161], v182 offset:2048
	ds_read_b128 v[182:185], v182 offset:3072
	ds_read_b128 v[186:189], v193 offset:32768
	ds_read_b128 v[194:197], v193 offset:33792
	ds_read_b128 v[198:201], v193 offset:34816
	ds_read_b128 v[214:217], v193 offset:35840
	ds_read_b128 v[218:221], v193 offset:36864
	ds_read_b128 v[222:225], v193 offset:37888
	ds_read_b128 v[226:229], v193 offset:38912
	ds_read_b128 v[230:233], v193 offset:39936
	s_mov_b32 m0, s69
	v_lshl_add_u64 v[234:235], v[202:203], 0, s[12:13]
	global_load_lds_dwordx4 v[234:235], off
	v_lshl_add_u64 v[234:235], v[202:203], 0, s[86:87]
	s_mov_b32 m0, s76
	s_nop 0
	global_load_lds_dwordx4 v[234:235], off
	s_waitcnt vmcnt(8)
	s_waitcnt lgkmcnt(0)
	s_barrier
	s_setprio 1
	s_waitcnt lgkmcnt(0)
	v_mfma_f32_16x16x32_bf16 v[142:145], v[114:117], v[186:189], v[142:145]
	v_mfma_f32_16x16x32_bf16 v[142:145], v[126:129], v[194:197], v[142:145]
	v_mfma_f32_16x16x32_bf16 v[110:113], v[114:117], v[198:201], v[110:113]
	v_mfma_f32_16x16x32_bf16 v[110:113], v[126:129], v[214:217], v[110:113]
	v_mfma_f32_16x16x32_bf16 v[94:97], v[114:117], v[218:221], v[94:97]
	v_mfma_f32_16x16x32_bf16 v[94:97], v[126:129], v[222:225], v[94:97]
	v_mfma_f32_16x16x32_bf16 v[78:81], v[114:117], v[226:229], v[78:81]
	v_mfma_f32_16x16x32_bf16 v[78:81], v[126:129], v[230:233], v[78:81]
	v_mfma_f32_16x16x32_bf16 v[138:141], v[130:133], v[186:189], v[138:141]
	v_mfma_f32_16x16x32_bf16 v[138:141], v[134:137], v[194:197], v[138:141]
	v_mfma_f32_16x16x32_bf16 v[106:109], v[130:133], v[198:201], v[106:109]
	v_mfma_f32_16x16x32_bf16 v[106:109], v[134:137], v[214:217], v[106:109]
	v_mfma_f32_16x16x32_bf16 v[90:93], v[130:133], v[218:221], v[90:93]
	v_mfma_f32_16x16x32_bf16 v[90:93], v[134:137], v[222:225], v[90:93]
	v_mfma_f32_16x16x32_bf16 v[74:77], v[130:133], v[226:229], v[74:77]
	v_mfma_f32_16x16x32_bf16 v[74:77], v[134:137], v[230:233], v[74:77]
	s_setprio 0
	s_setprio 1
	v_mfma_f32_16x16x32_bf16 v[122:125], v[146:149], v[186:189], v[122:125]
	v_mfma_f32_16x16x32_bf16 v[122:125], v[150:153], v[194:197], v[122:125]
	v_mfma_f32_16x16x32_bf16 v[102:105], v[146:149], v[198:201], v[102:105]
	v_mfma_f32_16x16x32_bf16 v[102:105], v[150:153], v[214:217], v[102:105]
	v_mfma_f32_16x16x32_bf16 v[86:89], v[146:149], v[218:221], v[86:89]
	v_mfma_f32_16x16x32_bf16 v[86:89], v[150:153], v[222:225], v[86:89]
	v_mfma_f32_16x16x32_bf16 v[70:73], v[146:149], v[226:229], v[70:73]
	v_mfma_f32_16x16x32_bf16 v[70:73], v[150:153], v[230:233], v[70:73]
	v_mfma_f32_16x16x32_bf16 v[118:121], v[158:161], v[186:189], v[118:121]
	v_mfma_f32_16x16x32_bf16 v[118:121], v[182:185], v[194:197], v[118:121]
	v_mfma_f32_16x16x32_bf16 v[98:101], v[158:161], v[198:201], v[98:101]
	v_mfma_f32_16x16x32_bf16 v[98:101], v[182:185], v[214:217], v[98:101]
	v_mfma_f32_16x16x32_bf16 v[82:85], v[158:161], v[218:221], v[82:85]
	v_mfma_f32_16x16x32_bf16 v[82:85], v[182:185], v[222:225], v[82:85]
	v_mfma_f32_16x16x32_bf16 v[66:69], v[158:161], v[226:229], v[66:69]
	v_mfma_f32_16x16x32_bf16 v[66:69], v[182:185], v[230:233], v[66:69]
	s_setprio 0
	s_barrier
	ds_read_b128 v[186:189], v193 offset:49152
	ds_read_b128 v[194:197], v193 offset:50176
	ds_read_b128 v[198:201], v193 offset:51200
	ds_read_b128 v[214:217], v193 offset:52224
	ds_read_b128 v[218:221], v193 offset:53248
	ds_read_b128 v[222:225], v193 offset:54272
	ds_read_b128 v[226:229], v193 offset:55296
	ds_read_b128 v[230:233], v193 offset:56320
	s_add_i32 s20, s20, s46
	s_mov_b32 m0, s20
	v_lshl_add_u64 v[234:235], v[162:163], 0, s[34:35]
	global_load_lds_dwordx4 v[234:235], off
	v_lshl_add_u64 v[234:235], v[162:163], 0, s[96:97]
	s_add_i32 m0, s20, 0x2000
	s_add_i32 s20, s21, s46
	global_load_lds_dwordx4 v[234:235], off
	v_lshl_add_u64 v[234:235], v[162:163], 0, vcc
	s_mov_b32 m0, s20
	v_lshl_add_u64 v[162:163], v[162:163], 0, s[0:1]
	global_load_lds_dwordx4 v[234:235], off
	s_add_i32 m0, s20, 0x2000
	s_nop 0
	global_load_lds_dwordx4 v[162:163], off
	v_lshl_add_u64 v[162:163], v[202:203], 0, s[34:35]
	s_mov_b32 m0, s77
	s_nop 0
	global_load_lds_dwordx4 v[162:163], off
	v_lshl_add_u64 v[162:163], v[202:203], 0, s[96:97]
	s_mov_b32 m0, s78
	s_nop 0
	global_load_lds_dwordx4 v[162:163], off
	s_waitcnt vmcnt(8)
	s_waitcnt lgkmcnt(0)
	s_barrier
	s_setprio 1
	s_waitcnt lgkmcnt(0)
	v_mfma_f32_16x16x32_bf16 v[62:65], v[114:117], v[186:189], v[62:65]
	v_mfma_f32_16x16x32_bf16 v[62:65], v[126:129], v[194:197], v[62:65]
	v_mfma_f32_16x16x32_bf16 v[46:49], v[114:117], v[198:201], v[46:49]
	v_mfma_f32_16x16x32_bf16 v[46:49], v[126:129], v[214:217], v[46:49]
	v_mfma_f32_16x16x32_bf16 v[30:33], v[114:117], v[218:221], v[30:33]
	v_mfma_f32_16x16x32_bf16 v[30:33], v[126:129], v[222:225], v[30:33]
	v_mfma_f32_16x16x32_bf16 v[14:17], v[114:117], v[226:229], v[14:17]
	v_mfma_f32_16x16x32_bf16 v[14:17], v[126:129], v[230:233], v[14:17]
	v_mfma_f32_16x16x32_bf16 v[58:61], v[130:133], v[186:189], v[58:61]
	v_mfma_f32_16x16x32_bf16 v[58:61], v[134:137], v[194:197], v[58:61]
	v_mfma_f32_16x16x32_bf16 v[42:45], v[130:133], v[198:201], v[42:45]
	v_mfma_f32_16x16x32_bf16 v[42:45], v[134:137], v[214:217], v[42:45]
	v_mfma_f32_16x16x32_bf16 v[26:29], v[130:133], v[218:221], v[26:29]
	v_mfma_f32_16x16x32_bf16 v[26:29], v[134:137], v[222:225], v[26:29]
	v_mfma_f32_16x16x32_bf16 v[10:13], v[130:133], v[226:229], v[10:13]
	v_mfma_f32_16x16x32_bf16 v[10:13], v[134:137], v[230:233], v[10:13]
	s_add_i32 s84, s84, 2
	s_add_u32 s56, s56, 0x100
	s_addc_u32 s57, s57, 0
	s_add_u32 s62, s62, 0x100
	s_addc_u32 s63, s63, 0
	s_setprio 0
	s_setprio 1
	v_mfma_f32_16x16x32_bf16 v[54:57], v[146:149], v[186:189], v[54:57]
	v_mfma_f32_16x16x32_bf16 v[54:57], v[150:153], v[194:197], v[54:57]
	v_mfma_f32_16x16x32_bf16 v[38:41], v[146:149], v[198:201], v[38:41]
	v_mfma_f32_16x16x32_bf16 v[38:41], v[150:153], v[214:217], v[38:41]
	v_mfma_f32_16x16x32_bf16 v[22:25], v[146:149], v[218:221], v[22:25]
	v_mfma_f32_16x16x32_bf16 v[22:25], v[150:153], v[222:225], v[22:25]
	v_mfma_f32_16x16x32_bf16 v[6:9], v[146:149], v[226:229], v[6:9]
	v_mfma_f32_16x16x32_bf16 v[6:9], v[150:153], v[230:233], v[6:9]
	v_mfma_f32_16x16x32_bf16 v[50:53], v[158:161], v[186:189], v[50:53]
	v_mfma_f32_16x16x32_bf16 v[50:53], v[182:185], v[194:197], v[50:53]
	v_mfma_f32_16x16x32_bf16 v[34:37], v[158:161], v[198:201], v[34:37]
	v_mfma_f32_16x16x32_bf16 v[34:37], v[182:185], v[214:217], v[34:37]
	v_mfma_f32_16x16x32_bf16 v[18:21], v[158:161], v[218:221], v[18:21]
	v_mfma_f32_16x16x32_bf16 v[18:21], v[182:185], v[222:225], v[18:21]
	v_mfma_f32_16x16x32_bf16 v[2:5], v[158:161], v[226:229], v[2:5]
	v_mfma_f32_16x16x32_bf16 v[2:5], v[182:185], v[230:233], v[2:5]
	s_setprio 0
	s_barrier
	s_branch .LBB0_446
	.p2alignl 6, 3212836864
.LBB0_446:
	s_add_i32 s22, 0, 0x10000
	s_add_i32 s23, 0, 0x14000
	v_add_u32_e32 v134, s22, v191
	v_add_u32_e32 v162, s23, v191
	ds_read_b128 v[114:117], v134
	ds_read_b128 v[126:129], v134 offset:1024
	ds_read_b128 v[130:133], v134 offset:2048
	ds_read_b128 v[134:137], v134 offset:3072
	ds_read_b128 v[146:149], v162
	ds_read_b128 v[150:153], v162 offset:1024
	ds_read_b128 v[158:161], v162 offset:2048
	ds_read_b128 v[182:185], v162 offset:3072
	ds_read_b128 v[186:189], v193
	ds_read_b128 v[194:197], v193 offset:1024
	ds_read_b128 v[198:201], v193 offset:2048
	ds_read_b128 v[214:217], v193 offset:3072
	ds_read_b128 v[218:221], v193 offset:4096
	ds_read_b128 v[222:225], v193 offset:5120
	ds_read_b128 v[226:229], v193 offset:6144
	ds_read_b128 v[230:233], v193 offset:7168
	s_add_u32 s20, s56, 0xfff50080
	s_addc_u32 s21, s57, -1
	s_cmp_eq_u32 s84, 40
	s_cselect_b32 s61, s49, s21
	s_cselect_b32 s60, s48, s20
	s_cselect_b32 s21, s51, s63
	s_cselect_b32 s20, s50, s62
	s_add_i32 m0, s47, 0xc000
	v_lshl_add_u64 v[162:163], s[56:57], 0, v[156:157]
	global_load_lds_dwordx4 v[162:163], off
	v_lshl_add_u64 v[162:163], v[162:163], 0, s[2:3]
	s_add_i32 m0, s47, 0xe000
	s_nop 0
	global_load_lds_dwordx4 v[162:163], off
	s_waitcnt vmcnt(8)
	s_waitcnt lgkmcnt(0)
	s_barrier
	s_setprio 1
	s_waitcnt lgkmcnt(0)
	v_mfma_f32_16x16x32_bf16 v[142:145], v[114:117], v[186:189], v[142:145]
	v_mfma_f32_16x16x32_bf16 v[142:145], v[126:129], v[194:197], v[142:145]
	v_mfma_f32_16x16x32_bf16 v[110:113], v[114:117], v[198:201], v[110:113]
	v_mfma_f32_16x16x32_bf16 v[110:113], v[126:129], v[214:217], v[110:113]
	v_mfma_f32_16x16x32_bf16 v[94:97], v[114:117], v[218:221], v[94:97]
	v_mfma_f32_16x16x32_bf16 v[94:97], v[126:129], v[222:225], v[94:97]
	v_mfma_f32_16x16x32_bf16 v[78:81], v[114:117], v[226:229], v[78:81]
	v_mfma_f32_16x16x32_bf16 v[78:81], v[126:129], v[230:233], v[78:81]
	v_mfma_f32_16x16x32_bf16 v[138:141], v[130:133], v[186:189], v[138:141]
	v_mfma_f32_16x16x32_bf16 v[138:141], v[134:137], v[194:197], v[138:141]
	v_mfma_f32_16x16x32_bf16 v[106:109], v[130:133], v[198:201], v[106:109]
	v_mfma_f32_16x16x32_bf16 v[106:109], v[134:137], v[214:217], v[106:109]
	v_mfma_f32_16x16x32_bf16 v[90:93], v[130:133], v[218:221], v[90:93]
	v_mfma_f32_16x16x32_bf16 v[90:93], v[134:137], v[222:225], v[90:93]
	v_mfma_f32_16x16x32_bf16 v[74:77], v[130:133], v[226:229], v[74:77]
	v_mfma_f32_16x16x32_bf16 v[74:77], v[134:137], v[230:233], v[74:77]
	s_setprio 0
	s_setprio 1
	v_mfma_f32_16x16x32_bf16 v[122:125], v[146:149], v[186:189], v[122:125]
	v_mfma_f32_16x16x32_bf16 v[122:125], v[150:153], v[194:197], v[122:125]
	v_mfma_f32_16x16x32_bf16 v[102:105], v[146:149], v[198:201], v[102:105]
	v_mfma_f32_16x16x32_bf16 v[102:105], v[150:153], v[214:217], v[102:105]
	v_mfma_f32_16x16x32_bf16 v[86:89], v[146:149], v[218:221], v[86:89]
	v_mfma_f32_16x16x32_bf16 v[86:89], v[150:153], v[222:225], v[86:89]
	v_mfma_f32_16x16x32_bf16 v[70:73], v[146:149], v[226:229], v[70:73]
	v_mfma_f32_16x16x32_bf16 v[70:73], v[150:153], v[230:233], v[70:73]
	v_mfma_f32_16x16x32_bf16 v[118:121], v[158:161], v[186:189], v[118:121]
	v_mfma_f32_16x16x32_bf16 v[118:121], v[182:185], v[194:197], v[118:121]
	v_mfma_f32_16x16x32_bf16 v[98:101], v[158:161], v[198:201], v[98:101]
	v_mfma_f32_16x16x32_bf16 v[98:101], v[182:185], v[214:217], v[98:101]
	v_mfma_f32_16x16x32_bf16 v[82:85], v[158:161], v[218:221], v[82:85]
	v_mfma_f32_16x16x32_bf16 v[82:85], v[182:185], v[222:225], v[82:85]
	v_mfma_f32_16x16x32_bf16 v[66:69], v[158:161], v[226:229], v[66:69]
	v_mfma_f32_16x16x32_bf16 v[66:69], v[182:185], v[230:233], v[66:69]
	s_setprio 0
	s_barrier
	ds_read_b128 v[186:189], v193 offset:16384
	ds_read_b128 v[194:197], v193 offset:17408
	ds_read_b128 v[198:201], v193 offset:18432
	ds_read_b128 v[214:217], v193 offset:19456
	ds_read_b128 v[218:221], v193 offset:20480
	ds_read_b128 v[222:225], v193 offset:21504
	ds_read_b128 v[226:229], v193 offset:22528
	ds_read_b128 v[230:233], v193 offset:23552
	v_lshl_add_u64 v[162:163], s[20:21], 0, v[0:1]
	s_add_i32 s20, s22, s46
	s_mov_b32 m0, s20
	s_nop 0
	s_nop 0
	global_load_lds_dwordx4 v[162:163], off
	v_lshl_add_u64 v[202:203], v[162:163], 0, s[2:3]
	s_add_i32 m0, s20, 0x2000
	s_add_i32 s20, s23, s46
	global_load_lds_dwordx4 v[202:203], off
	v_lshl_add_u64 v[202:203], v[162:163], 0, s[12:13]
	s_mov_b32 m0, s20
	s_nop 0
	global_load_lds_dwordx4 v[202:203], off
	v_lshl_add_u64 v[202:203], v[162:163], 0, s[86:87]
	s_add_i32 m0, s20, 0x2000
	s_nop 0
	global_load_lds_dwordx4 v[202:203], off
	v_lshl_add_u64 v[202:203], s[60:61], 0, v[154:155]
	s_mov_b32 m0, s47
	v_lshl_add_u64 v[234:235], v[202:203], 0, s[2:3]
	global_load_lds_dwordx4 v[202:203], off
	s_mov_b32 m0, s68
	s_nop 0
	global_load_lds_dwordx4 v[234:235], off
	s_waitcnt vmcnt(8)
	s_waitcnt lgkmcnt(0)
	s_barrier
	s_setprio 1
	s_waitcnt lgkmcnt(0)
	v_mfma_f32_16x16x32_bf16 v[62:65], v[114:117], v[186:189], v[62:65]
	v_mfma_f32_16x16x32_bf16 v[62:65], v[126:129], v[194:197], v[62:65]
	v_mfma_f32_16x16x32_bf16 v[46:49], v[114:117], v[198:201], v[46:49]
	v_mfma_f32_16x16x32_bf16 v[46:49], v[126:129], v[214:217], v[46:49]
	v_mfma_f32_16x16x32_bf16 v[30:33], v[114:117], v[218:221], v[30:33]
	v_mfma_f32_16x16x32_bf16 v[30:33], v[126:129], v[222:225], v[30:33]
	v_mfma_f32_16x16x32_bf16 v[14:17], v[114:117], v[226:229], v[14:17]
	v_mfma_f32_16x16x32_bf16 v[14:17], v[126:129], v[230:233], v[14:17]
	v_mfma_f32_16x16x32_bf16 v[58:61], v[130:133], v[186:189], v[58:61]
	v_mfma_f32_16x16x32_bf16 v[58:61], v[134:137], v[194:197], v[58:61]
	v_mfma_f32_16x16x32_bf16 v[42:45], v[130:133], v[198:201], v[42:45]
	v_mfma_f32_16x16x32_bf16 v[42:45], v[134:137], v[214:217], v[42:45]
	v_mfma_f32_16x16x32_bf16 v[26:29], v[130:133], v[218:221], v[26:29]
	v_mfma_f32_16x16x32_bf16 v[26:29], v[134:137], v[222:225], v[26:29]
	v_mfma_f32_16x16x32_bf16 v[10:13], v[130:133], v[226:229], v[10:13]
	v_mfma_f32_16x16x32_bf16 v[10:13], v[134:137], v[230:233], v[10:13]
	s_setprio 0
	s_setprio 1
	v_mfma_f32_16x16x32_bf16 v[54:57], v[146:149], v[186:189], v[54:57]
	v_mfma_f32_16x16x32_bf16 v[54:57], v[150:153], v[194:197], v[54:57]
	v_mfma_f32_16x16x32_bf16 v[38:41], v[146:149], v[198:201], v[38:41]
	v_mfma_f32_16x16x32_bf16 v[38:41], v[150:153], v[214:217], v[38:41]
	v_mfma_f32_16x16x32_bf16 v[22:25], v[146:149], v[218:221], v[22:25]
	v_mfma_f32_16x16x32_bf16 v[22:25], v[150:153], v[222:225], v[22:25]
	v_mfma_f32_16x16x32_bf16 v[6:9], v[146:149], v[226:229], v[6:9]
	v_mfma_f32_16x16x32_bf16 v[6:9], v[150:153], v[230:233], v[6:9]
	v_mfma_f32_16x16x32_bf16 v[50:53], v[158:161], v[186:189], v[50:53]
	v_mfma_f32_16x16x32_bf16 v[50:53], v[182:185], v[194:197], v[50:53]
	v_mfma_f32_16x16x32_bf16 v[34:37], v[158:161], v[198:201], v[34:37]
	v_mfma_f32_16x16x32_bf16 v[34:37], v[182:185], v[214:217], v[34:37]
	v_mfma_f32_16x16x32_bf16 v[18:21], v[158:161], v[218:221], v[18:21]
	v_mfma_f32_16x16x32_bf16 v[18:21], v[182:185], v[222:225], v[18:21]
	v_mfma_f32_16x16x32_bf16 v[2:5], v[158:161], v[226:229], v[2:5]
	v_mfma_f32_16x16x32_bf16 v[2:5], v[182:185], v[230:233], v[2:5]
	s_setprio 0
	s_barrier
	s_add_i32 s20, 0, 0x18000
	s_add_i32 s21, 0, 0x1c000
	v_add_u32_e32 v134, s20, v191
	v_add_u32_e32 v182, s21, v191
	ds_read_b128 v[114:117], v134
	ds_read_b128 v[126:129], v134 offset:1024
	ds_read_b128 v[130:133], v134 offset:2048
	ds_read_b128 v[134:137], v134 offset:3072
	ds_read_b128 v[146:149], v182
	ds_read_b128 v[150:153], v182 offset:1024
	ds_read_b128 v[158:161], v182 offset:2048
	ds_read_b128 v[182:185], v182 offset:3072
	ds_read_b128 v[186:189], v193 offset:32768
	ds_read_b128 v[194:197], v193 offset:33792
	ds_read_b128 v[198:201], v193 offset:34816
	ds_read_b128 v[214:217], v193 offset:35840
	ds_read_b128 v[218:221], v193 offset:36864
	ds_read_b128 v[222:225], v193 offset:37888
	ds_read_b128 v[226:229], v193 offset:38912
	ds_read_b128 v[230:233], v193 offset:39936
	s_mov_b32 m0, s69
	v_lshl_add_u64 v[234:235], v[202:203], 0, s[12:13]
	global_load_lds_dwordx4 v[234:235], off
	v_lshl_add_u64 v[234:235], v[202:203], 0, s[86:87]
	s_mov_b32 m0, s76
	s_nop 0
	global_load_lds_dwordx4 v[234:235], off
	s_waitcnt vmcnt(8)
	s_waitcnt lgkmcnt(0)
	s_barrier
	s_setprio 1
	s_waitcnt lgkmcnt(0)
	v_mfma_f32_16x16x32_bf16 v[142:145], v[114:117], v[186:189], v[142:145]
	v_mfma_f32_16x16x32_bf16 v[142:145], v[126:129], v[194:197], v[142:145]
	v_mfma_f32_16x16x32_bf16 v[110:113], v[114:117], v[198:201], v[110:113]
	v_mfma_f32_16x16x32_bf16 v[110:113], v[126:129], v[214:217], v[110:113]
	v_mfma_f32_16x16x32_bf16 v[94:97], v[114:117], v[218:221], v[94:97]
	v_mfma_f32_16x16x32_bf16 v[94:97], v[126:129], v[222:225], v[94:97]
	v_mfma_f32_16x16x32_bf16 v[78:81], v[114:117], v[226:229], v[78:81]
	v_mfma_f32_16x16x32_bf16 v[78:81], v[126:129], v[230:233], v[78:81]
	v_mfma_f32_16x16x32_bf16 v[138:141], v[130:133], v[186:189], v[138:141]
	v_mfma_f32_16x16x32_bf16 v[138:141], v[134:137], v[194:197], v[138:141]
	v_mfma_f32_16x16x32_bf16 v[106:109], v[130:133], v[198:201], v[106:109]
	v_mfma_f32_16x16x32_bf16 v[106:109], v[134:137], v[214:217], v[106:109]
	v_mfma_f32_16x16x32_bf16 v[90:93], v[130:133], v[218:221], v[90:93]
	v_mfma_f32_16x16x32_bf16 v[90:93], v[134:137], v[222:225], v[90:93]
	v_mfma_f32_16x16x32_bf16 v[74:77], v[130:133], v[226:229], v[74:77]
	v_mfma_f32_16x16x32_bf16 v[74:77], v[134:137], v[230:233], v[74:77]
	s_setprio 0
	s_setprio 1
	v_mfma_f32_16x16x32_bf16 v[122:125], v[146:149], v[186:189], v[122:125]
	v_mfma_f32_16x16x32_bf16 v[122:125], v[150:153], v[194:197], v[122:125]
	v_mfma_f32_16x16x32_bf16 v[102:105], v[146:149], v[198:201], v[102:105]
	v_mfma_f32_16x16x32_bf16 v[102:105], v[150:153], v[214:217], v[102:105]
	v_mfma_f32_16x16x32_bf16 v[86:89], v[146:149], v[218:221], v[86:89]
	v_mfma_f32_16x16x32_bf16 v[86:89], v[150:153], v[222:225], v[86:89]
	v_mfma_f32_16x16x32_bf16 v[70:73], v[146:149], v[226:229], v[70:73]
	v_mfma_f32_16x16x32_bf16 v[70:73], v[150:153], v[230:233], v[70:73]
	v_mfma_f32_16x16x32_bf16 v[118:121], v[158:161], v[186:189], v[118:121]
	v_mfma_f32_16x16x32_bf16 v[118:121], v[182:185], v[194:197], v[118:121]
	v_mfma_f32_16x16x32_bf16 v[98:101], v[158:161], v[198:201], v[98:101]
	v_mfma_f32_16x16x32_bf16 v[98:101], v[182:185], v[214:217], v[98:101]
	v_mfma_f32_16x16x32_bf16 v[82:85], v[158:161], v[218:221], v[82:85]
	v_mfma_f32_16x16x32_bf16 v[82:85], v[182:185], v[222:225], v[82:85]
	v_mfma_f32_16x16x32_bf16 v[66:69], v[158:161], v[226:229], v[66:69]
	v_mfma_f32_16x16x32_bf16 v[66:69], v[182:185], v[230:233], v[66:69]
	s_setprio 0
	s_barrier
	ds_read_b128 v[186:189], v193 offset:49152
	ds_read_b128 v[194:197], v193 offset:50176
	ds_read_b128 v[198:201], v193 offset:51200
	ds_read_b128 v[214:217], v193 offset:52224
	ds_read_b128 v[218:221], v193 offset:53248
	ds_read_b128 v[222:225], v193 offset:54272
	ds_read_b128 v[226:229], v193 offset:55296
	ds_read_b128 v[230:233], v193 offset:56320
	s_add_i32 s20, s20, s46
	s_mov_b32 m0, s20
	v_lshl_add_u64 v[234:235], v[162:163], 0, s[34:35]
	global_load_lds_dwordx4 v[234:235], off
	v_lshl_add_u64 v[234:235], v[162:163], 0, s[96:97]
	s_add_i32 m0, s20, 0x2000
	s_add_i32 s20, s21, s46
	global_load_lds_dwordx4 v[234:235], off
	v_lshl_add_u64 v[234:235], v[162:163], 0, vcc
	s_mov_b32 m0, s20
	v_lshl_add_u64 v[162:163], v[162:163], 0, s[0:1]
	global_load_lds_dwordx4 v[234:235], off
	s_add_i32 m0, s20, 0x2000
	s_nop 0
	global_load_lds_dwordx4 v[162:163], off
	v_lshl_add_u64 v[162:163], v[202:203], 0, s[34:35]
	s_mov_b32 m0, s77
	s_nop 0
	global_load_lds_dwordx4 v[162:163], off
	v_lshl_add_u64 v[162:163], v[202:203], 0, s[96:97]
	s_mov_b32 m0, s78
	s_nop 0
	global_load_lds_dwordx4 v[162:163], off
	s_waitcnt vmcnt(8)
	s_waitcnt lgkmcnt(0)
	s_barrier
	s_setprio 1
	s_waitcnt lgkmcnt(0)
	v_mfma_f32_16x16x32_bf16 v[62:65], v[114:117], v[186:189], v[62:65]
	v_mfma_f32_16x16x32_bf16 v[62:65], v[126:129], v[194:197], v[62:65]
	v_mfma_f32_16x16x32_bf16 v[46:49], v[114:117], v[198:201], v[46:49]
	v_mfma_f32_16x16x32_bf16 v[46:49], v[126:129], v[214:217], v[46:49]
	v_mfma_f32_16x16x32_bf16 v[30:33], v[114:117], v[218:221], v[30:33]
	v_mfma_f32_16x16x32_bf16 v[30:33], v[126:129], v[222:225], v[30:33]
	v_mfma_f32_16x16x32_bf16 v[14:17], v[114:117], v[226:229], v[14:17]
	v_mfma_f32_16x16x32_bf16 v[14:17], v[126:129], v[230:233], v[14:17]
	v_mfma_f32_16x16x32_bf16 v[58:61], v[130:133], v[186:189], v[58:61]
	v_mfma_f32_16x16x32_bf16 v[58:61], v[134:137], v[194:197], v[58:61]
	v_mfma_f32_16x16x32_bf16 v[42:45], v[130:133], v[198:201], v[42:45]
	v_mfma_f32_16x16x32_bf16 v[42:45], v[134:137], v[214:217], v[42:45]
	v_mfma_f32_16x16x32_bf16 v[26:29], v[130:133], v[218:221], v[26:29]
	v_mfma_f32_16x16x32_bf16 v[26:29], v[134:137], v[222:225], v[26:29]
	v_mfma_f32_16x16x32_bf16 v[10:13], v[130:133], v[226:229], v[10:13]
	v_mfma_f32_16x16x32_bf16 v[10:13], v[134:137], v[230:233], v[10:13]
	s_add_i32 s84, s84, 2
	s_add_u32 s56, s56, 0x100
	s_addc_u32 s57, s57, 0
	s_add_u32 s62, s62, 0x100
	s_addc_u32 s63, s63, 0
	s_setprio 0
	s_setprio 1
	v_mfma_f32_16x16x32_bf16 v[54:57], v[146:149], v[186:189], v[54:57]
	v_mfma_f32_16x16x32_bf16 v[54:57], v[150:153], v[194:197], v[54:57]
	v_mfma_f32_16x16x32_bf16 v[38:41], v[146:149], v[198:201], v[38:41]
	v_mfma_f32_16x16x32_bf16 v[38:41], v[150:153], v[214:217], v[38:41]
	v_mfma_f32_16x16x32_bf16 v[22:25], v[146:149], v[218:221], v[22:25]
	v_mfma_f32_16x16x32_bf16 v[22:25], v[150:153], v[222:225], v[22:25]
	v_mfma_f32_16x16x32_bf16 v[6:9], v[146:149], v[226:229], v[6:9]
	v_mfma_f32_16x16x32_bf16 v[6:9], v[150:153], v[230:233], v[6:9]
	v_mfma_f32_16x16x32_bf16 v[50:53], v[158:161], v[186:189], v[50:53]
	v_mfma_f32_16x16x32_bf16 v[50:53], v[182:185], v[194:197], v[50:53]
	v_mfma_f32_16x16x32_bf16 v[34:37], v[158:161], v[198:201], v[34:37]
	v_mfma_f32_16x16x32_bf16 v[34:37], v[182:185], v[214:217], v[34:37]
	v_mfma_f32_16x16x32_bf16 v[18:21], v[158:161], v[218:221], v[18:21]
	v_mfma_f32_16x16x32_bf16 v[18:21], v[182:185], v[222:225], v[18:21]
	v_mfma_f32_16x16x32_bf16 v[2:5], v[158:161], v[226:229], v[2:5]
	v_mfma_f32_16x16x32_bf16 v[2:5], v[182:185], v[230:233], v[2:5]
	s_setprio 0
	s_barrier
	s_cmp_gt_u32 s84, 41
	s_cbranch_scc0 .LBB0_446
	s_and_b64 vcc, exec, s[40:41]
	s_cbranch_vccz .LBB0_449
	s_barrier

.Lmid1_488:
	s_add_i32 s22, 0, 0x10000
	s_add_i32 s23, 0, 0x14000
	s_add_u32 s20, s68, 0xfffc0080
	s_addc_u32 s21, s69, -1
	s_cmp_eq_u32 s97, 12
	s_cselect_b32 s77, s57, s21
	s_cselect_b32 s76, s86, s20
	s_cselect_b32 s21, s51, s96
	s_cselect_b32 s20, s87, s91
	s_add_i32 m0, s43, 0xc000
	v_lshl_add_u64 v[202:203], s[68:69], 0, v[132:133]
	global_load_lds_dwordx4 v[202:203], off
	v_lshl_add_u64 v[202:203], v[202:203], 0, s[72:73]
	s_add_i32 m0, s43, 0xe000
	s_nop 0
	global_load_lds_dwordx4 v[202:203], off
	s_waitcnt vmcnt(8)
	s_waitcnt lgkmcnt(0)
	s_barrier
	s_setprio 1
	s_waitcnt lgkmcnt(0)
	v_mfma_f32_16x16x32_bf16 v[126:129], v[134:137], v[190:193], 0
	v_mfma_f32_16x16x32_bf16 v[126:129], v[144:147], v[194:197], v[126:129]
	v_mfma_f32_16x16x32_bf16 v[110:113], v[134:137], v[198:201], 0
	v_mfma_f32_16x16x32_bf16 v[110:113], v[144:147], v[214:217], v[110:113]
	v_mfma_f32_16x16x32_bf16 v[94:97], v[134:137], v[218:221], 0
	v_mfma_f32_16x16x32_bf16 v[94:97], v[144:147], v[222:225], v[94:97]
	v_mfma_f32_16x16x32_bf16 v[78:81], v[134:137], v[226:229], 0
	v_mfma_f32_16x16x32_bf16 v[78:81], v[144:147], v[230:233], v[78:81]
	v_mfma_f32_16x16x32_bf16 v[114:117], v[148:151], v[190:193], 0
	v_mfma_f32_16x16x32_bf16 v[114:117], v[152:155], v[194:197], v[114:117]
	v_mfma_f32_16x16x32_bf16 v[98:101], v[148:151], v[198:201], 0
	v_mfma_f32_16x16x32_bf16 v[98:101], v[152:155], v[214:217], v[98:101]
	v_mfma_f32_16x16x32_bf16 v[82:85], v[148:151], v[218:221], 0
	v_mfma_f32_16x16x32_bf16 v[82:85], v[152:155], v[222:225], v[82:85]
	v_mfma_f32_16x16x32_bf16 v[66:69], v[148:151], v[226:229], 0
	v_mfma_f32_16x16x32_bf16 v[66:69], v[152:155], v[230:233], v[66:69]
	s_setprio 0
	s_setprio 1
	v_mfma_f32_16x16x32_bf16 v[122:125], v[156:159], v[190:193], 0
	v_mfma_f32_16x16x32_bf16 v[122:125], v[160:163], v[194:197], v[122:125]
	v_mfma_f32_16x16x32_bf16 v[106:109], v[156:159], v[198:201], 0
	v_mfma_f32_16x16x32_bf16 v[106:109], v[160:163], v[214:217], v[106:109]
	v_mfma_f32_16x16x32_bf16 v[90:93], v[156:159], v[218:221], 0
	v_mfma_f32_16x16x32_bf16 v[90:93], v[160:163], v[222:225], v[90:93]
	v_mfma_f32_16x16x32_bf16 v[74:77], v[156:159], v[226:229], 0
	v_mfma_f32_16x16x32_bf16 v[74:77], v[160:163], v[230:233], v[74:77]
	v_mfma_f32_16x16x32_bf16 v[118:121], v[182:185], v[190:193], 0
	v_mfma_f32_16x16x32_bf16 v[118:121], v[186:189], v[194:197], v[118:121]
	v_mfma_f32_16x16x32_bf16 v[102:105], v[182:185], v[198:201], 0
	v_mfma_f32_16x16x32_bf16 v[102:105], v[186:189], v[214:217], v[102:105]
	v_mfma_f32_16x16x32_bf16 v[86:89], v[182:185], v[218:221], 0
	v_mfma_f32_16x16x32_bf16 v[86:89], v[186:189], v[222:225], v[86:89]
	v_mfma_f32_16x16x32_bf16 v[70:73], v[182:185], v[226:229], 0
	v_mfma_f32_16x16x32_bf16 v[70:73], v[186:189], v[230:233], v[70:73]
	s_setprio 0
	s_barrier
	ds_read_b128 v[190:193], v142 offset:16384
	ds_read_b128 v[194:197], v142 offset:17408
	ds_read_b128 v[198:201], v142 offset:18432
	ds_read_b128 v[214:217], v142 offset:19456
	ds_read_b128 v[218:221], v142 offset:20480
	ds_read_b128 v[222:225], v142 offset:21504
	ds_read_b128 v[226:229], v142 offset:22528
	ds_read_b128 v[230:233], v142 offset:23552
	v_lshl_add_u64 v[202:203], s[20:21], 0, v[0:1]
	s_add_i32 s20, s22, s14
	s_mov_b32 m0, s20
	s_nop 0
	s_nop 0
	global_load_lds_dwordx4 v[202:203], off
	v_lshl_add_u64 v[234:235], v[202:203], 0, s[72:73]
	s_add_i32 m0, s20, 0x2000
	s_add_i32 s20, s23, s14
	global_load_lds_dwordx4 v[234:235], off
	v_lshl_add_u64 v[234:235], v[202:203], 0, s[28:29]
	s_mov_b32 m0, s20
	s_nop 0
	global_load_lds_dwordx4 v[234:235], off
	v_lshl_add_u64 v[234:235], v[202:203], 0, s[82:83]
	s_add_i32 m0, s20, 0x2000
	s_nop 0
	global_load_lds_dwordx4 v[234:235], off
	v_lshl_add_u64 v[234:235], s[76:77], 0, v[130:131]
	s_mov_b32 m0, s43
	v_lshl_add_u64 v[236:237], v[234:235], 0, s[72:73]
	global_load_lds_dwordx4 v[234:235], off
	s_mov_b32 m0, s46
	s_nop 0
	global_load_lds_dwordx4 v[236:237], off
	s_waitcnt vmcnt(8)
	s_waitcnt lgkmcnt(0)
	s_barrier
	s_setprio 1
	s_waitcnt lgkmcnt(0)
	v_mfma_f32_16x16x32_bf16 v[62:65], v[134:137], v[190:193], 0
	v_mfma_f32_16x16x32_bf16 v[62:65], v[144:147], v[194:197], v[62:65]
	v_mfma_f32_16x16x32_bf16 v[46:49], v[134:137], v[198:201], 0
	v_mfma_f32_16x16x32_bf16 v[46:49], v[144:147], v[214:217], v[46:49]
	v_mfma_f32_16x16x32_bf16 v[30:33], v[134:137], v[218:221], 0
	v_mfma_f32_16x16x32_bf16 v[30:33], v[144:147], v[222:225], v[30:33]
	v_mfma_f32_16x16x32_bf16 v[14:17], v[134:137], v[226:229], 0
	v_mfma_f32_16x16x32_bf16 v[14:17], v[144:147], v[230:233], v[14:17]
	v_mfma_f32_16x16x32_bf16 v[50:53], v[148:151], v[190:193], 0
	v_mfma_f32_16x16x32_bf16 v[50:53], v[152:155], v[194:197], v[50:53]
	v_mfma_f32_16x16x32_bf16 v[34:37], v[148:151], v[198:201], 0
	v_mfma_f32_16x16x32_bf16 v[34:37], v[152:155], v[214:217], v[34:37]
	v_mfma_f32_16x16x32_bf16 v[18:21], v[148:151], v[218:221], 0
	v_mfma_f32_16x16x32_bf16 v[18:21], v[152:155], v[222:225], v[18:21]
	v_mfma_f32_16x16x32_bf16 v[6:9], v[148:151], v[226:229], 0
	v_mfma_f32_16x16x32_bf16 v[6:9], v[152:155], v[230:233], v[6:9]
	s_setprio 0
	s_setprio 1
	v_mfma_f32_16x16x32_bf16 v[58:61], v[156:159], v[190:193], 0
	v_mfma_f32_16x16x32_bf16 v[58:61], v[160:163], v[194:197], v[58:61]
	v_mfma_f32_16x16x32_bf16 v[42:45], v[156:159], v[198:201], 0
	v_mfma_f32_16x16x32_bf16 v[42:45], v[160:163], v[214:217], v[42:45]
	v_mfma_f32_16x16x32_bf16 v[26:29], v[156:159], v[218:221], 0
	v_mfma_f32_16x16x32_bf16 v[26:29], v[160:163], v[222:225], v[26:29]
	v_mfma_f32_16x16x32_bf16 v[10:13], v[156:159], v[226:229], 0
	v_mfma_f32_16x16x32_bf16 v[10:13], v[160:163], v[230:233], v[10:13]
	v_mfma_f32_16x16x32_bf16 v[54:57], v[182:185], v[190:193], 0
	v_mfma_f32_16x16x32_bf16 v[54:57], v[186:189], v[194:197], v[54:57]
	v_mfma_f32_16x16x32_bf16 v[38:41], v[182:185], v[198:201], 0
	v_mfma_f32_16x16x32_bf16 v[38:41], v[186:189], v[214:217], v[38:41]
	v_mfma_f32_16x16x32_bf16 v[22:25], v[182:185], v[218:221], 0
	v_mfma_f32_16x16x32_bf16 v[22:25], v[186:189], v[222:225], v[22:25]
	v_mfma_f32_16x16x32_bf16 v[2:5], v[182:185], v[226:229], 0
	v_mfma_f32_16x16x32_bf16 v[2:5], v[186:189], v[230:233], v[2:5]
	s_setprio 0
	s_barrier
	s_add_i32 s20, 0, 0x18000
	v_add_u32_e32 v143, s20, v139
	s_add_i32 s21, 0, 0x1c000
	ds_read_b128 v[134:137], v143
	ds_read_b128 v[144:147], v143 offset:1024
	ds_read_b128 v[148:151], v143 offset:2048
	ds_read_b128 v[152:155], v143 offset:3072
	v_add_u32_e32 v143, s21, v139
	ds_read_b128 v[156:159], v143
	ds_read_b128 v[160:163], v143 offset:1024
	ds_read_b128 v[182:185], v143 offset:2048
	ds_read_b128 v[186:189], v143 offset:3072
	ds_read_b128 v[190:193], v142 offset:32768
	ds_read_b128 v[194:197], v142 offset:33792
	ds_read_b128 v[198:201], v142 offset:34816
	ds_read_b128 v[214:217], v142 offset:35840
	ds_read_b128 v[218:221], v142 offset:36864
	ds_read_b128 v[222:225], v142 offset:37888
	ds_read_b128 v[226:229], v142 offset:38912
	ds_read_b128 v[230:233], v142 offset:39936
	s_mov_b32 m0, s47
	v_lshl_add_u64 v[236:237], v[234:235], 0, s[28:29]
	global_load_lds_dwordx4 v[236:237], off
	v_lshl_add_u64 v[236:237], v[234:235], 0, s[82:83]
	s_mov_b32 m0, s78
	s_nop 0
	global_load_lds_dwordx4 v[236:237], off
	s_waitcnt vmcnt(8)
	s_waitcnt lgkmcnt(0)
	s_barrier
	s_setprio 1
	s_waitcnt lgkmcnt(0)
	v_mfma_f32_16x16x32_bf16 v[126:129], v[134:137], v[190:193], v[126:129]
	v_mfma_f32_16x16x32_bf16 v[126:129], v[144:147], v[194:197], v[126:129]
	v_mfma_f32_16x16x32_bf16 v[110:113], v[134:137], v[198:201], v[110:113]
	v_mfma_f32_16x16x32_bf16 v[110:113], v[144:147], v[214:217], v[110:113]
	v_mfma_f32_16x16x32_bf16 v[94:97], v[134:137], v[218:221], v[94:97]
	v_mfma_f32_16x16x32_bf16 v[94:97], v[144:147], v[222:225], v[94:97]
	v_mfma_f32_16x16x32_bf16 v[78:81], v[134:137], v[226:229], v[78:81]
	v_mfma_f32_16x16x32_bf16 v[78:81], v[144:147], v[230:233], v[78:81]
	v_mfma_f32_16x16x32_bf16 v[114:117], v[148:151], v[190:193], v[114:117]
	v_mfma_f32_16x16x32_bf16 v[114:117], v[152:155], v[194:197], v[114:117]
	v_mfma_f32_16x16x32_bf16 v[98:101], v[148:151], v[198:201], v[98:101]
	v_mfma_f32_16x16x32_bf16 v[98:101], v[152:155], v[214:217], v[98:101]
	v_mfma_f32_16x16x32_bf16 v[82:85], v[148:151], v[218:221], v[82:85]
	v_mfma_f32_16x16x32_bf16 v[82:85], v[152:155], v[222:225], v[82:85]
	v_mfma_f32_16x16x32_bf16 v[66:69], v[148:151], v[226:229], v[66:69]
	v_mfma_f32_16x16x32_bf16 v[66:69], v[152:155], v[230:233], v[66:69]
	s_setprio 0
	s_setprio 1
	v_mfma_f32_16x16x32_bf16 v[122:125], v[156:159], v[190:193], v[122:125]
	v_mfma_f32_16x16x32_bf16 v[122:125], v[160:163], v[194:197], v[122:125]
	v_mfma_f32_16x16x32_bf16 v[106:109], v[156:159], v[198:201], v[106:109]
	v_mfma_f32_16x16x32_bf16 v[106:109], v[160:163], v[214:217], v[106:109]
	v_mfma_f32_16x16x32_bf16 v[90:93], v[156:159], v[218:221], v[90:93]
	v_mfma_f32_16x16x32_bf16 v[90:93], v[160:163], v[222:225], v[90:93]
	v_mfma_f32_16x16x32_bf16 v[74:77], v[156:159], v[226:229], v[74:77]
	v_mfma_f32_16x16x32_bf16 v[74:77], v[160:163], v[230:233], v[74:77]
	v_mfma_f32_16x16x32_bf16 v[118:121], v[182:185], v[190:193], v[118:121]
	v_mfma_f32_16x16x32_bf16 v[118:121], v[186:189], v[194:197], v[118:121]
	v_mfma_f32_16x16x32_bf16 v[102:105], v[182:185], v[198:201], v[102:105]
	v_mfma_f32_16x16x32_bf16 v[102:105], v[186:189], v[214:217], v[102:105]
	v_mfma_f32_16x16x32_bf16 v[86:89], v[182:185], v[218:221], v[86:89]
	v_mfma_f32_16x16x32_bf16 v[86:89], v[186:189], v[222:225], v[86:89]
	v_mfma_f32_16x16x32_bf16 v[70:73], v[182:185], v[226:229], v[70:73]
	v_mfma_f32_16x16x32_bf16 v[70:73], v[186:189], v[230:233], v[70:73]
	s_setprio 0
	s_barrier
	ds_read_b128 v[190:193], v142 offset:49152
	ds_read_b128 v[194:197], v142 offset:50176
	ds_read_b128 v[198:201], v142 offset:51200
	ds_read_b128 v[214:217], v142 offset:52224
	ds_read_b128 v[218:221], v142 offset:53248
	ds_read_b128 v[222:225], v142 offset:54272
	ds_read_b128 v[226:229], v142 offset:55296
	ds_read_b128 v[230:233], v142 offset:56320
	s_add_i32 s20, s20, s14
	s_mov_b32 m0, s20
	v_lshl_add_u64 v[236:237], v[202:203], 0, s[34:35]
	global_load_lds_dwordx4 v[236:237], off
	v_lshl_add_u64 v[236:237], v[202:203], 0, s[38:39]
	s_add_i32 m0, s20, 0x2000
	s_add_i32 s20, s21, s14
	global_load_lds_dwordx4 v[236:237], off
	v_lshl_add_u64 v[236:237], v[202:203], 0, s[44:45]
	s_mov_b32 m0, s20
	v_lshl_add_u64 v[202:203], v[202:203], 0, s[10:11]
	global_load_lds_dwordx4 v[236:237], off
	s_add_i32 m0, s20, 0x2000
	s_nop 0
	global_load_lds_dwordx4 v[202:203], off
	v_lshl_add_u64 v[202:203], v[234:235], 0, s[34:35]
	s_mov_b32 m0, s79
	s_nop 0
	global_load_lds_dwordx4 v[202:203], off
	v_lshl_add_u64 v[202:203], v[234:235], 0, s[38:39]
	s_mov_b32 m0, s88
	s_nop 0
	global_load_lds_dwordx4 v[202:203], off
	s_waitcnt vmcnt(8)
	s_waitcnt lgkmcnt(0)
	s_barrier
	s_setprio 1
	s_waitcnt lgkmcnt(0)
	v_mfma_f32_16x16x32_bf16 v[62:65], v[134:137], v[190:193], v[62:65]
	v_mfma_f32_16x16x32_bf16 v[62:65], v[144:147], v[194:197], v[62:65]
	v_mfma_f32_16x16x32_bf16 v[46:49], v[134:137], v[198:201], v[46:49]
	v_mfma_f32_16x16x32_bf16 v[46:49], v[144:147], v[214:217], v[46:49]
	v_mfma_f32_16x16x32_bf16 v[30:33], v[134:137], v[218:221], v[30:33]
	v_mfma_f32_16x16x32_bf16 v[30:33], v[144:147], v[222:225], v[30:33]
	v_mfma_f32_16x16x32_bf16 v[14:17], v[134:137], v[226:229], v[14:17]
	v_mfma_f32_16x16x32_bf16 v[14:17], v[144:147], v[230:233], v[14:17]
	v_mfma_f32_16x16x32_bf16 v[50:53], v[148:151], v[190:193], v[50:53]
	v_mfma_f32_16x16x32_bf16 v[50:53], v[152:155], v[194:197], v[50:53]
	v_mfma_f32_16x16x32_bf16 v[34:37], v[148:151], v[198:201], v[34:37]
	v_mfma_f32_16x16x32_bf16 v[34:37], v[152:155], v[214:217], v[34:37]
	v_mfma_f32_16x16x32_bf16 v[18:21], v[148:151], v[218:221], v[18:21]
	v_mfma_f32_16x16x32_bf16 v[18:21], v[152:155], v[222:225], v[18:21]
	v_mfma_f32_16x16x32_bf16 v[6:9], v[148:151], v[226:229], v[6:9]
	v_mfma_f32_16x16x32_bf16 v[6:9], v[152:155], v[230:233], v[6:9]
	s_add_i32 s97, s97, 2
	s_add_u32 s68, s68, 0x100
	s_addc_u32 s69, s69, 0
	s_add_u32 s91, s91, 0x100
	s_addc_u32 s96, s96, 0
	s_setprio 0
	s_setprio 1
	v_mfma_f32_16x16x32_bf16 v[58:61], v[156:159], v[190:193], v[58:61]
	v_mfma_f32_16x16x32_bf16 v[58:61], v[160:163], v[194:197], v[58:61]
	v_mfma_f32_16x16x32_bf16 v[42:45], v[156:159], v[198:201], v[42:45]
	v_mfma_f32_16x16x32_bf16 v[42:45], v[160:163], v[214:217], v[42:45]
	v_mfma_f32_16x16x32_bf16 v[26:29], v[156:159], v[218:221], v[26:29]
	v_mfma_f32_16x16x32_bf16 v[26:29], v[160:163], v[222:225], v[26:29]
	v_mfma_f32_16x16x32_bf16 v[10:13], v[156:159], v[226:229], v[10:13]
	v_mfma_f32_16x16x32_bf16 v[10:13], v[160:163], v[230:233], v[10:13]
	v_mfma_f32_16x16x32_bf16 v[54:57], v[182:185], v[190:193], v[54:57]
	v_mfma_f32_16x16x32_bf16 v[54:57], v[186:189], v[194:197], v[54:57]
	v_mfma_f32_16x16x32_bf16 v[38:41], v[182:185], v[198:201], v[38:41]
	v_mfma_f32_16x16x32_bf16 v[38:41], v[186:189], v[214:217], v[38:41]
	v_mfma_f32_16x16x32_bf16 v[22:25], v[182:185], v[218:221], v[22:25]
	v_mfma_f32_16x16x32_bf16 v[22:25], v[186:189], v[222:225], v[22:25]
	v_mfma_f32_16x16x32_bf16 v[2:5], v[182:185], v[226:229], v[2:5]
	v_mfma_f32_16x16x32_bf16 v[2:5], v[186:189], v[230:233], v[2:5]
	s_setprio 0
	s_barrier
	s_branch .LBB0_488
	.p2alignl 6, 3212836864
.LBB0_488:
	s_add_i32 s22, 0, 0x10000
	v_add_u32_e32 v143, s22, v139
	s_add_i32 s23, 0, 0x14000
	ds_read_b128 v[134:137], v143
	ds_read_b128 v[144:147], v143 offset:1024
	ds_read_b128 v[148:151], v143 offset:2048
	ds_read_b128 v[152:155], v143 offset:3072
	v_add_u32_e32 v143, s23, v139
	ds_read_b128 v[156:159], v143
	ds_read_b128 v[160:163], v143 offset:1024
	ds_read_b128 v[182:185], v143 offset:2048
	ds_read_b128 v[186:189], v143 offset:3072
	ds_read_b128 v[190:193], v142
	ds_read_b128 v[194:197], v142 offset:1024
	ds_read_b128 v[198:201], v142 offset:2048
	ds_read_b128 v[214:217], v142 offset:3072
	ds_read_b128 v[218:221], v142 offset:4096
	ds_read_b128 v[222:225], v142 offset:5120
	ds_read_b128 v[226:229], v142 offset:6144
	ds_read_b128 v[230:233], v142 offset:7168
	s_add_u32 s20, s68, 0xfffc0080
	s_addc_u32 s21, s69, -1
	s_cmp_eq_u32 s97, 12
	s_cselect_b32 s77, s57, s21
	s_cselect_b32 s76, s86, s20
	s_cselect_b32 s21, s51, s96
	s_cselect_b32 s20, s87, s91
	s_add_i32 m0, s43, 0xc000
	v_lshl_add_u64 v[202:203], s[68:69], 0, v[132:133]
	global_load_lds_dwordx4 v[202:203], off
	v_lshl_add_u64 v[202:203], v[202:203], 0, s[72:73]
	s_add_i32 m0, s43, 0xe000
	s_nop 0
	global_load_lds_dwordx4 v[202:203], off
	s_waitcnt vmcnt(8)
	s_waitcnt lgkmcnt(0)
	s_barrier
	s_setprio 1
	s_waitcnt lgkmcnt(0)
	v_mfma_f32_16x16x32_bf16 v[126:129], v[134:137], v[190:193], v[126:129]
	v_mfma_f32_16x16x32_bf16 v[126:129], v[144:147], v[194:197], v[126:129]
	v_mfma_f32_16x16x32_bf16 v[110:113], v[134:137], v[198:201], v[110:113]
	v_mfma_f32_16x16x32_bf16 v[110:113], v[144:147], v[214:217], v[110:113]
	v_mfma_f32_16x16x32_bf16 v[94:97], v[134:137], v[218:221], v[94:97]
	v_mfma_f32_16x16x32_bf16 v[94:97], v[144:147], v[222:225], v[94:97]
	v_mfma_f32_16x16x32_bf16 v[78:81], v[134:137], v[226:229], v[78:81]
	v_mfma_f32_16x16x32_bf16 v[78:81], v[144:147], v[230:233], v[78:81]
	v_mfma_f32_16x16x32_bf16 v[114:117], v[148:151], v[190:193], v[114:117]
	v_mfma_f32_16x16x32_bf16 v[114:117], v[152:155], v[194:197], v[114:117]
	v_mfma_f32_16x16x32_bf16 v[98:101], v[148:151], v[198:201], v[98:101]
	v_mfma_f32_16x16x32_bf16 v[98:101], v[152:155], v[214:217], v[98:101]
	v_mfma_f32_16x16x32_bf16 v[82:85], v[148:151], v[218:221], v[82:85]
	v_mfma_f32_16x16x32_bf16 v[82:85], v[152:155], v[222:225], v[82:85]
	v_mfma_f32_16x16x32_bf16 v[66:69], v[148:151], v[226:229], v[66:69]
	v_mfma_f32_16x16x32_bf16 v[66:69], v[152:155], v[230:233], v[66:69]
	s_setprio 0
	s_setprio 1
	v_mfma_f32_16x16x32_bf16 v[122:125], v[156:159], v[190:193], v[122:125]
	v_mfma_f32_16x16x32_bf16 v[122:125], v[160:163], v[194:197], v[122:125]
	v_mfma_f32_16x16x32_bf16 v[106:109], v[156:159], v[198:201], v[106:109]
	v_mfma_f32_16x16x32_bf16 v[106:109], v[160:163], v[214:217], v[106:109]
	v_mfma_f32_16x16x32_bf16 v[90:93], v[156:159], v[218:221], v[90:93]
	v_mfma_f32_16x16x32_bf16 v[90:93], v[160:163], v[222:225], v[90:93]
	v_mfma_f32_16x16x32_bf16 v[74:77], v[156:159], v[226:229], v[74:77]
	v_mfma_f32_16x16x32_bf16 v[74:77], v[160:163], v[230:233], v[74:77]
	v_mfma_f32_16x16x32_bf16 v[118:121], v[182:185], v[190:193], v[118:121]
	v_mfma_f32_16x16x32_bf16 v[118:121], v[186:189], v[194:197], v[118:121]
	v_mfma_f32_16x16x32_bf16 v[102:105], v[182:185], v[198:201], v[102:105]
	v_mfma_f32_16x16x32_bf16 v[102:105], v[186:189], v[214:217], v[102:105]
	v_mfma_f32_16x16x32_bf16 v[86:89], v[182:185], v[218:221], v[86:89]
	v_mfma_f32_16x16x32_bf16 v[86:89], v[186:189], v[222:225], v[86:89]
	v_mfma_f32_16x16x32_bf16 v[70:73], v[182:185], v[226:229], v[70:73]
	v_mfma_f32_16x16x32_bf16 v[70:73], v[186:189], v[230:233], v[70:73]
	s_setprio 0
	s_barrier
	ds_read_b128 v[190:193], v142 offset:16384
	ds_read_b128 v[194:197], v142 offset:17408
	ds_read_b128 v[198:201], v142 offset:18432
	ds_read_b128 v[214:217], v142 offset:19456
	ds_read_b128 v[218:221], v142 offset:20480
	ds_read_b128 v[222:225], v142 offset:21504
	ds_read_b128 v[226:229], v142 offset:22528
	ds_read_b128 v[230:233], v142 offset:23552
	v_lshl_add_u64 v[202:203], s[20:21], 0, v[0:1]
	s_add_i32 s20, s22, s14
	s_mov_b32 m0, s20
	s_nop 0
	s_nop 0
	global_load_lds_dwordx4 v[202:203], off
	v_lshl_add_u64 v[234:235], v[202:203], 0, s[72:73]
	s_add_i32 m0, s20, 0x2000
	s_add_i32 s20, s23, s14
	global_load_lds_dwordx4 v[234:235], off
	v_lshl_add_u64 v[234:235], v[202:203], 0, s[28:29]
	s_mov_b32 m0, s20
	s_nop 0
	global_load_lds_dwordx4 v[234:235], off
	v_lshl_add_u64 v[234:235], v[202:203], 0, s[82:83]
	s_add_i32 m0, s20, 0x2000
	s_nop 0
	global_load_lds_dwordx4 v[234:235], off
	v_lshl_add_u64 v[234:235], s[76:77], 0, v[130:131]
	s_mov_b32 m0, s43
	v_lshl_add_u64 v[236:237], v[234:235], 0, s[72:73]
	global_load_lds_dwordx4 v[234:235], off
	s_mov_b32 m0, s46
	s_nop 0
	global_load_lds_dwordx4 v[236:237], off
	s_waitcnt vmcnt(8)
	s_waitcnt lgkmcnt(0)
	s_barrier
	s_setprio 1
	s_waitcnt lgkmcnt(0)
	v_mfma_f32_16x16x32_bf16 v[62:65], v[134:137], v[190:193], v[62:65]
	v_mfma_f32_16x16x32_bf16 v[62:65], v[144:147], v[194:197], v[62:65]
	v_mfma_f32_16x16x32_bf16 v[46:49], v[134:137], v[198:201], v[46:49]
	v_mfma_f32_16x16x32_bf16 v[46:49], v[144:147], v[214:217], v[46:49]
	v_mfma_f32_16x16x32_bf16 v[30:33], v[134:137], v[218:221], v[30:33]
	v_mfma_f32_16x16x32_bf16 v[30:33], v[144:147], v[222:225], v[30:33]
	v_mfma_f32_16x16x32_bf16 v[14:17], v[134:137], v[226:229], v[14:17]
	v_mfma_f32_16x16x32_bf16 v[14:17], v[144:147], v[230:233], v[14:17]
	v_mfma_f32_16x16x32_bf16 v[50:53], v[148:151], v[190:193], v[50:53]
	v_mfma_f32_16x16x32_bf16 v[50:53], v[152:155], v[194:197], v[50:53]
	v_mfma_f32_16x16x32_bf16 v[34:37], v[148:151], v[198:201], v[34:37]
	v_mfma_f32_16x16x32_bf16 v[34:37], v[152:155], v[214:217], v[34:37]
	v_mfma_f32_16x16x32_bf16 v[18:21], v[148:151], v[218:221], v[18:21]
	v_mfma_f32_16x16x32_bf16 v[18:21], v[152:155], v[222:225], v[18:21]
	v_mfma_f32_16x16x32_bf16 v[6:9], v[148:151], v[226:229], v[6:9]
	v_mfma_f32_16x16x32_bf16 v[6:9], v[152:155], v[230:233], v[6:9]
	s_setprio 0
	s_setprio 1
	v_mfma_f32_16x16x32_bf16 v[58:61], v[156:159], v[190:193], v[58:61]
	v_mfma_f32_16x16x32_bf16 v[58:61], v[160:163], v[194:197], v[58:61]
	v_mfma_f32_16x16x32_bf16 v[42:45], v[156:159], v[198:201], v[42:45]
	v_mfma_f32_16x16x32_bf16 v[42:45], v[160:163], v[214:217], v[42:45]
	v_mfma_f32_16x16x32_bf16 v[26:29], v[156:159], v[218:221], v[26:29]
	v_mfma_f32_16x16x32_bf16 v[26:29], v[160:163], v[222:225], v[26:29]
	v_mfma_f32_16x16x32_bf16 v[10:13], v[156:159], v[226:229], v[10:13]
	v_mfma_f32_16x16x32_bf16 v[10:13], v[160:163], v[230:233], v[10:13]
	v_mfma_f32_16x16x32_bf16 v[54:57], v[182:185], v[190:193], v[54:57]
	v_mfma_f32_16x16x32_bf16 v[54:57], v[186:189], v[194:197], v[54:57]
	v_mfma_f32_16x16x32_bf16 v[38:41], v[182:185], v[198:201], v[38:41]
	v_mfma_f32_16x16x32_bf16 v[38:41], v[186:189], v[214:217], v[38:41]
	v_mfma_f32_16x16x32_bf16 v[22:25], v[182:185], v[218:221], v[22:25]
	v_mfma_f32_16x16x32_bf16 v[22:25], v[186:189], v[222:225], v[22:25]
	v_mfma_f32_16x16x32_bf16 v[2:5], v[182:185], v[226:229], v[2:5]
	v_mfma_f32_16x16x32_bf16 v[2:5], v[186:189], v[230:233], v[2:5]
	s_setprio 0
	s_barrier
	s_add_i32 s20, 0, 0x18000
	v_add_u32_e32 v143, s20, v139
	s_add_i32 s21, 0, 0x1c000
	ds_read_b128 v[134:137], v143
	ds_read_b128 v[144:147], v143 offset:1024
	ds_read_b128 v[148:151], v143 offset:2048
	ds_read_b128 v[152:155], v143 offset:3072
	v_add_u32_e32 v143, s21, v139
	ds_read_b128 v[156:159], v143
	ds_read_b128 v[160:163], v143 offset:1024
	ds_read_b128 v[182:185], v143 offset:2048
	ds_read_b128 v[186:189], v143 offset:3072
	ds_read_b128 v[190:193], v142 offset:32768
	ds_read_b128 v[194:197], v142 offset:33792
	ds_read_b128 v[198:201], v142 offset:34816
	ds_read_b128 v[214:217], v142 offset:35840
	ds_read_b128 v[218:221], v142 offset:36864
	ds_read_b128 v[222:225], v142 offset:37888
	ds_read_b128 v[226:229], v142 offset:38912
	ds_read_b128 v[230:233], v142 offset:39936
	s_mov_b32 m0, s47
	v_lshl_add_u64 v[236:237], v[234:235], 0, s[28:29]
	global_load_lds_dwordx4 v[236:237], off
	v_lshl_add_u64 v[236:237], v[234:235], 0, s[82:83]
	s_mov_b32 m0, s78
	s_nop 0
	global_load_lds_dwordx4 v[236:237], off
	s_waitcnt vmcnt(8)
	s_waitcnt lgkmcnt(0)
	s_barrier
	s_setprio 1
	s_waitcnt lgkmcnt(0)
	v_mfma_f32_16x16x32_bf16 v[126:129], v[134:137], v[190:193], v[126:129]
	v_mfma_f32_16x16x32_bf16 v[126:129], v[144:147], v[194:197], v[126:129]
	v_mfma_f32_16x16x32_bf16 v[110:113], v[134:137], v[198:201], v[110:113]
	v_mfma_f32_16x16x32_bf16 v[110:113], v[144:147], v[214:217], v[110:113]
	v_mfma_f32_16x16x32_bf16 v[94:97], v[134:137], v[218:221], v[94:97]
	v_mfma_f32_16x16x32_bf16 v[94:97], v[144:147], v[222:225], v[94:97]
	v_mfma_f32_16x16x32_bf16 v[78:81], v[134:137], v[226:229], v[78:81]
	v_mfma_f32_16x16x32_bf16 v[78:81], v[144:147], v[230:233], v[78:81]
	v_mfma_f32_16x16x32_bf16 v[114:117], v[148:151], v[190:193], v[114:117]
	v_mfma_f32_16x16x32_bf16 v[114:117], v[152:155], v[194:197], v[114:117]
	v_mfma_f32_16x16x32_bf16 v[98:101], v[148:151], v[198:201], v[98:101]
	v_mfma_f32_16x16x32_bf16 v[98:101], v[152:155], v[214:217], v[98:101]
	v_mfma_f32_16x16x32_bf16 v[82:85], v[148:151], v[218:221], v[82:85]
	v_mfma_f32_16x16x32_bf16 v[82:85], v[152:155], v[222:225], v[82:85]
	v_mfma_f32_16x16x32_bf16 v[66:69], v[148:151], v[226:229], v[66:69]
	v_mfma_f32_16x16x32_bf16 v[66:69], v[152:155], v[230:233], v[66:69]
	s_setprio 0
	s_setprio 1
	v_mfma_f32_16x16x32_bf16 v[122:125], v[156:159], v[190:193], v[122:125]
	v_mfma_f32_16x16x32_bf16 v[122:125], v[160:163], v[194:197], v[122:125]
	v_mfma_f32_16x16x32_bf16 v[106:109], v[156:159], v[198:201], v[106:109]
	v_mfma_f32_16x16x32_bf16 v[106:109], v[160:163], v[214:217], v[106:109]
	v_mfma_f32_16x16x32_bf16 v[90:93], v[156:159], v[218:221], v[90:93]
	v_mfma_f32_16x16x32_bf16 v[90:93], v[160:163], v[222:225], v[90:93]
	v_mfma_f32_16x16x32_bf16 v[74:77], v[156:159], v[226:229], v[74:77]
	v_mfma_f32_16x16x32_bf16 v[74:77], v[160:163], v[230:233], v[74:77]
	v_mfma_f32_16x16x32_bf16 v[118:121], v[182:185], v[190:193], v[118:121]
	v_mfma_f32_16x16x32_bf16 v[118:121], v[186:189], v[194:197], v[118:121]
	v_mfma_f32_16x16x32_bf16 v[102:105], v[182:185], v[198:201], v[102:105]
	v_mfma_f32_16x16x32_bf16 v[102:105], v[186:189], v[214:217], v[102:105]
	v_mfma_f32_16x16x32_bf16 v[86:89], v[182:185], v[218:221], v[86:89]
	v_mfma_f32_16x16x32_bf16 v[86:89], v[186:189], v[222:225], v[86:89]
	v_mfma_f32_16x16x32_bf16 v[70:73], v[182:185], v[226:229], v[70:73]
	v_mfma_f32_16x16x32_bf16 v[70:73], v[186:189], v[230:233], v[70:73]
	s_setprio 0
	s_barrier
	ds_read_b128 v[190:193], v142 offset:49152
	ds_read_b128 v[194:197], v142 offset:50176
	ds_read_b128 v[198:201], v142 offset:51200
	ds_read_b128 v[214:217], v142 offset:52224
	ds_read_b128 v[218:221], v142 offset:53248
	ds_read_b128 v[222:225], v142 offset:54272
	ds_read_b128 v[226:229], v142 offset:55296
	ds_read_b128 v[230:233], v142 offset:56320
	s_add_i32 s20, s20, s14
	s_mov_b32 m0, s20
	v_lshl_add_u64 v[236:237], v[202:203], 0, s[34:35]
	global_load_lds_dwordx4 v[236:237], off
	v_lshl_add_u64 v[236:237], v[202:203], 0, s[38:39]
	s_add_i32 m0, s20, 0x2000
	s_add_i32 s20, s21, s14
	global_load_lds_dwordx4 v[236:237], off
	v_lshl_add_u64 v[236:237], v[202:203], 0, s[44:45]
	s_mov_b32 m0, s20
	v_lshl_add_u64 v[202:203], v[202:203], 0, s[10:11]
	global_load_lds_dwordx4 v[236:237], off
	s_add_i32 m0, s20, 0x2000
	s_nop 0
	global_load_lds_dwordx4 v[202:203], off
	v_lshl_add_u64 v[202:203], v[234:235], 0, s[34:35]
	s_mov_b32 m0, s79
	s_nop 0
	global_load_lds_dwordx4 v[202:203], off
	v_lshl_add_u64 v[202:203], v[234:235], 0, s[38:39]
	s_mov_b32 m0, s88
	s_nop 0
	global_load_lds_dwordx4 v[202:203], off
	s_waitcnt vmcnt(8)
	s_waitcnt lgkmcnt(0)
	s_barrier
	s_setprio 1
	s_waitcnt lgkmcnt(0)
	v_mfma_f32_16x16x32_bf16 v[62:65], v[134:137], v[190:193], v[62:65]
	v_mfma_f32_16x16x32_bf16 v[62:65], v[144:147], v[194:197], v[62:65]
	v_mfma_f32_16x16x32_bf16 v[46:49], v[134:137], v[198:201], v[46:49]
	v_mfma_f32_16x16x32_bf16 v[46:49], v[144:147], v[214:217], v[46:49]
	v_mfma_f32_16x16x32_bf16 v[30:33], v[134:137], v[218:221], v[30:33]
	v_mfma_f32_16x16x32_bf16 v[30:33], v[144:147], v[222:225], v[30:33]
	v_mfma_f32_16x16x32_bf16 v[14:17], v[134:137], v[226:229], v[14:17]
	v_mfma_f32_16x16x32_bf16 v[14:17], v[144:147], v[230:233], v[14:17]
	v_mfma_f32_16x16x32_bf16 v[50:53], v[148:151], v[190:193], v[50:53]
	v_mfma_f32_16x16x32_bf16 v[50:53], v[152:155], v[194:197], v[50:53]
	v_mfma_f32_16x16x32_bf16 v[34:37], v[148:151], v[198:201], v[34:37]
	v_mfma_f32_16x16x32_bf16 v[34:37], v[152:155], v[214:217], v[34:37]
	v_mfma_f32_16x16x32_bf16 v[18:21], v[148:151], v[218:221], v[18:21]
	v_mfma_f32_16x16x32_bf16 v[18:21], v[152:155], v[222:225], v[18:21]
	v_mfma_f32_16x16x32_bf16 v[6:9], v[148:151], v[226:229], v[6:9]
	v_mfma_f32_16x16x32_bf16 v[6:9], v[152:155], v[230:233], v[6:9]
	s_add_i32 s97, s97, 2
	s_add_u32 s68, s68, 0x100
	s_addc_u32 s69, s69, 0
	s_add_u32 s91, s91, 0x100
	s_addc_u32 s96, s96, 0
	s_setprio 0
	s_setprio 1
	v_mfma_f32_16x16x32_bf16 v[58:61], v[156:159], v[190:193], v[58:61]
	v_mfma_f32_16x16x32_bf16 v[58:61], v[160:163], v[194:197], v[58:61]
	v_mfma_f32_16x16x32_bf16 v[42:45], v[156:159], v[198:201], v[42:45]
	v_mfma_f32_16x16x32_bf16 v[42:45], v[160:163], v[214:217], v[42:45]
	v_mfma_f32_16x16x32_bf16 v[26:29], v[156:159], v[218:221], v[26:29]
	v_mfma_f32_16x16x32_bf16 v[26:29], v[160:163], v[222:225], v[26:29]
	v_mfma_f32_16x16x32_bf16 v[10:13], v[156:159], v[226:229], v[10:13]
	v_mfma_f32_16x16x32_bf16 v[10:13], v[160:163], v[230:233], v[10:13]
	v_mfma_f32_16x16x32_bf16 v[54:57], v[182:185], v[190:193], v[54:57]
	v_mfma_f32_16x16x32_bf16 v[54:57], v[186:189], v[194:197], v[54:57]
	v_mfma_f32_16x16x32_bf16 v[38:41], v[182:185], v[198:201], v[38:41]
	v_mfma_f32_16x16x32_bf16 v[38:41], v[186:189], v[214:217], v[38:41]
	v_mfma_f32_16x16x32_bf16 v[22:25], v[182:185], v[218:221], v[22:25]
	v_mfma_f32_16x16x32_bf16 v[22:25], v[186:189], v[222:225], v[22:25]
	v_mfma_f32_16x16x32_bf16 v[2:5], v[182:185], v[226:229], v[2:5]
	v_mfma_f32_16x16x32_bf16 v[2:5], v[186:189], v[230:233], v[2:5]
	s_setprio 0
	s_barrier
	s_cmp_gt_u32 s97, 13
	s_cbranch_scc0 .LBB0_488
	s_and_b64 vcc, exec, s[48:49]
	s_cbranch_vccz .LBB0_491
	s_barrier

.LBB0_562:
	s_add_u32 s20, s62, s68
	s_addc_u32 s21, s63, s69
	s_add_u32 s20, s20, 0x100
	s_addc_u32 s21, s21, 0
	s_add_u32 s22, s97, s68
	s_addc_u32 s23, vcc_lo, s69
	s_cmpk_eq_i32 s68, 0x700
	s_cselect_b32 s77, s51, s21
	s_cselect_b32 s76, s86, s20
	s_cselect_b32 s21, s49, s23
	s_cselect_b32 s20, s87, s22
	s_add_i32 s22, 0, 0x10000
	v_add_u32_e32 v0, s22, v215
	s_add_i32 s23, 0, 0x14000
	ds_read_b128 v[118:121], v0
	ds_read_b128 v[122:125], v0 offset:1024
	ds_read_b128 v[132:135], v0 offset:2048
	ds_read_b128 v[148:151], v0 offset:3072
	v_add_u32_e32 v0, s23, v215
	ds_read_b128 v[152:155], v0
	ds_read_b128 v[156:159], v0 offset:1024
	ds_read_b128 v[160:163], v0 offset:2048
	ds_read_b128 v[188:191], v0 offset:3072
	v_lshl_add_u64 v[2:3], v[116:117], 0, s[68:69]
	v_lshl_add_u64 v[126:127], v[2:3], 0, s[44:45]
	s_add_i32 m0, s47, 0xc000
	ds_read_b128 v[192:195], v218
	ds_read_b128 v[196:199], v218 offset:1024
	ds_read_b128 v[200:203], v218 offset:2048
	ds_read_b128 v[220:223], v218 offset:3072
	ds_read_b128 v[224:227], v218 offset:4096
	ds_read_b128 v[228:231], v218 offset:5120
	ds_read_b128 v[232:235], v218 offset:6144
	ds_read_b128 v[236:239], v218 offset:7168
	global_load_lds_dwordx4 v[126:127], off
	v_lshl_add_u64 v[2:3], v[2:3], 0, s[10:11]
	s_add_i32 m0, s47, 0xe000
	s_nop 0
	global_load_lds_dwordx4 v[2:3], off
	s_waitcnt vmcnt(8)
	s_waitcnt lgkmcnt(0)
	s_barrier
	s_setprio 1
	s_waitcnt lgkmcnt(0)
	v_mfma_f32_16x16x32_bf16 v[144:147], v[118:121], v[192:195], v[144:147]
	v_mfma_f32_16x16x32_bf16 v[144:147], v[122:125], v[196:199], v[144:147]
	v_mfma_f32_16x16x32_bf16 v[112:115], v[118:121], v[200:203], v[112:115]
	v_mfma_f32_16x16x32_bf16 v[112:115], v[122:125], v[220:223], v[112:115]
	v_mfma_f32_16x16x32_bf16 v[96:99], v[118:121], v[224:227], v[96:99]
	v_mfma_f32_16x16x32_bf16 v[96:99], v[122:125], v[228:231], v[96:99]
	v_mfma_f32_16x16x32_bf16 v[80:83], v[118:121], v[232:235], v[80:83]
	v_mfma_f32_16x16x32_bf16 v[80:83], v[122:125], v[236:239], v[80:83]
	v_mfma_f32_16x16x32_bf16 v[140:143], v[132:135], v[192:195], v[140:143]
	v_mfma_f32_16x16x32_bf16 v[140:143], v[148:151], v[196:199], v[140:143]
	v_mfma_f32_16x16x32_bf16 v[108:111], v[132:135], v[200:203], v[108:111]
	v_mfma_f32_16x16x32_bf16 v[108:111], v[148:151], v[220:223], v[108:111]
	v_mfma_f32_16x16x32_bf16 v[92:95], v[132:135], v[224:227], v[92:95]
	v_mfma_f32_16x16x32_bf16 v[92:95], v[148:151], v[228:231], v[92:95]
	v_mfma_f32_16x16x32_bf16 v[76:79], v[132:135], v[232:235], v[76:79]
	v_mfma_f32_16x16x32_bf16 v[76:79], v[148:151], v[236:239], v[76:79]
	s_setprio 0
	s_setprio 1
	v_mfma_f32_16x16x32_bf16 v[136:139], v[152:155], v[192:195], v[136:139]
	v_mfma_f32_16x16x32_bf16 v[136:139], v[156:159], v[196:199], v[136:139]
	v_mfma_f32_16x16x32_bf16 v[104:107], v[152:155], v[200:203], v[104:107]
	v_mfma_f32_16x16x32_bf16 v[104:107], v[156:159], v[220:223], v[104:107]
	v_mfma_f32_16x16x32_bf16 v[88:91], v[152:155], v[224:227], v[88:91]
	v_mfma_f32_16x16x32_bf16 v[88:91], v[156:159], v[228:231], v[88:91]
	v_mfma_f32_16x16x32_bf16 v[72:75], v[152:155], v[232:235], v[72:75]
	v_mfma_f32_16x16x32_bf16 v[72:75], v[156:159], v[236:239], v[72:75]
	v_mfma_f32_16x16x32_bf16 v[126:129], v[160:163], v[192:195], v[128:131]
	v_mfma_f32_16x16x32_bf16 v[126:129], v[188:191], v[196:199], v[126:129]
	v_mfma_f32_16x16x32_bf16 v[100:103], v[160:163], v[200:203], v[100:103]
	v_mfma_f32_16x16x32_bf16 v[100:103], v[188:191], v[220:223], v[100:103]
	v_mfma_f32_16x16x32_bf16 v[84:87], v[160:163], v[224:227], v[84:87]
	v_mfma_f32_16x16x32_bf16 v[84:87], v[188:191], v[228:231], v[84:87]
	v_mfma_f32_16x16x32_bf16 v[68:71], v[160:163], v[232:235], v[68:71]
	v_mfma_f32_16x16x32_bf16 v[68:71], v[188:191], v[236:239], v[68:71]
	s_setprio 0
	s_barrier
	v_lshl_add_u64 v[240:241], s[20:21], 0, v[182:183]
	s_add_i32 s20, s22, s14
	s_mov_b32 m0, s20
	ds_read_b128 v[192:195], v218 offset:16384
	ds_read_b128 v[196:199], v218 offset:17408
	ds_read_b128 v[200:203], v218 offset:18432
	ds_read_b128 v[220:223], v218 offset:19456
	ds_read_b128 v[224:227], v218 offset:20480
	ds_read_b128 v[228:231], v218 offset:21504
	ds_read_b128 v[232:235], v218 offset:22528
	ds_read_b128 v[236:239], v218 offset:23552
	global_load_lds_dwordx4 v[240:241], off
	v_lshl_add_u64 v[2:3], v[240:241], 0, s[72:73]
	s_add_i32 m0, s20, 0x2000
	s_add_i32 s20, s23, s14
	global_load_lds_dwordx4 v[2:3], off
	v_lshl_add_u64 v[2:3], v[240:241], 0, s[28:29]
	s_mov_b32 m0, s20
	v_lshl_add_u64 v[242:243], s[76:77], 0, v[184:185]
	global_load_lds_dwordx4 v[2:3], off
	v_lshl_add_u64 v[2:3], v[240:241], 0, s[82:83]
	s_add_i32 m0, s20, 0x2000
	s_nop 0
	global_load_lds_dwordx4 v[2:3], off
	s_mov_b32 m0, s47
	v_lshl_add_u64 v[2:3], v[242:243], 0, s[72:73]
	global_load_lds_dwordx4 v[242:243], off
	s_mov_b32 m0, s79
	s_nop 0
	global_load_lds_dwordx4 v[2:3], off
	s_waitcnt vmcnt(8)
	s_waitcnt lgkmcnt(0)
	s_barrier
	s_setprio 1
	s_waitcnt lgkmcnt(0)
	v_mfma_f32_16x16x32_bf16 v[64:67], v[118:121], v[192:195], v[64:67]
	v_mfma_f32_16x16x32_bf16 v[64:67], v[122:125], v[196:199], v[64:67]
	v_mfma_f32_16x16x32_bf16 v[48:51], v[118:121], v[200:203], v[48:51]
	v_mfma_f32_16x16x32_bf16 v[48:51], v[122:125], v[220:223], v[48:51]
	v_mfma_f32_16x16x32_bf16 v[32:35], v[118:121], v[224:227], v[32:35]
	v_mfma_f32_16x16x32_bf16 v[32:35], v[122:125], v[228:231], v[32:35]
	v_mfma_f32_16x16x32_bf16 v[16:19], v[118:121], v[232:235], v[16:19]
	v_mfma_f32_16x16x32_bf16 v[16:19], v[122:125], v[236:239], v[16:19]
	v_mfma_f32_16x16x32_bf16 v[60:63], v[132:135], v[192:195], v[60:63]
	v_mfma_f32_16x16x32_bf16 v[60:63], v[148:151], v[196:199], v[60:63]
	v_mfma_f32_16x16x32_bf16 v[44:47], v[132:135], v[200:203], v[44:47]
	v_mfma_f32_16x16x32_bf16 v[44:47], v[148:151], v[220:223], v[44:47]
	v_mfma_f32_16x16x32_bf16 v[28:31], v[132:135], v[224:227], v[28:31]
	v_mfma_f32_16x16x32_bf16 v[28:31], v[148:151], v[228:231], v[28:31]
	v_mfma_f32_16x16x32_bf16 v[12:15], v[132:135], v[232:235], v[12:15]
	v_mfma_f32_16x16x32_bf16 v[12:15], v[148:151], v[236:239], v[12:15]
	s_setprio 0
	s_setprio 1
	v_mfma_f32_16x16x32_bf16 v[56:59], v[152:155], v[192:195], v[56:59]
	v_mfma_f32_16x16x32_bf16 v[56:59], v[156:159], v[196:199], v[56:59]
	v_mfma_f32_16x16x32_bf16 v[40:43], v[152:155], v[200:203], v[40:43]
	v_mfma_f32_16x16x32_bf16 v[40:43], v[156:159], v[220:223], v[40:43]
	v_mfma_f32_16x16x32_bf16 v[24:27], v[152:155], v[224:227], v[24:27]
	v_mfma_f32_16x16x32_bf16 v[24:27], v[156:159], v[228:231], v[24:27]
	v_mfma_f32_16x16x32_bf16 v[8:11], v[152:155], v[232:235], v[8:11]
	v_mfma_f32_16x16x32_bf16 v[8:11], v[156:159], v[236:239], v[8:11]
	v_mfma_f32_16x16x32_bf16 v[52:55], v[160:163], v[192:195], v[52:55]
	v_mfma_f32_16x16x32_bf16 v[52:55], v[188:191], v[196:199], v[52:55]
	v_mfma_f32_16x16x32_bf16 v[36:39], v[160:163], v[200:203], v[36:39]
	v_mfma_f32_16x16x32_bf16 v[36:39], v[188:191], v[220:223], v[36:39]
	v_mfma_f32_16x16x32_bf16 v[20:23], v[160:163], v[224:227], v[20:23]
	v_mfma_f32_16x16x32_bf16 v[20:23], v[188:191], v[228:231], v[20:23]
	v_mfma_f32_16x16x32_bf16 v[2:5], v[160:163], v[232:235], v[4:7]
	v_mfma_f32_16x16x32_bf16 v[2:5], v[188:191], v[236:239], v[2:5]
	s_setprio 0
	s_barrier
	s_add_i32 s20, 0, 0x18000
	v_add_u32_e32 v0, s20, v215
	s_add_i32 s21, 0, 0x1c000
	ds_read_b128 v[118:121], v0
	ds_read_b128 v[122:125], v0 offset:1024
	ds_read_b128 v[132:135], v0 offset:2048
	ds_read_b128 v[148:151], v0 offset:3072
	v_add_u32_e32 v0, s21, v215
	ds_read_b128 v[152:155], v0
	ds_read_b128 v[156:159], v0 offset:1024
	ds_read_b128 v[160:163], v0 offset:2048
	ds_read_b128 v[188:191], v0 offset:3072
	s_mov_b32 m0, s88
	v_lshl_add_u64 v[6:7], v[242:243], 0, s[28:29]
	ds_read_b128 v[192:195], v218 offset:32768
	ds_read_b128 v[196:199], v218 offset:33792
	ds_read_b128 v[200:203], v218 offset:34816
	ds_read_b128 v[220:223], v218 offset:35840
	ds_read_b128 v[224:227], v218 offset:36864
	ds_read_b128 v[228:231], v218 offset:37888
	ds_read_b128 v[232:235], v218 offset:38912
	ds_read_b128 v[236:239], v218 offset:39936
	global_load_lds_dwordx4 v[6:7], off
	v_lshl_add_u64 v[6:7], v[242:243], 0, s[82:83]
	s_mov_b32 m0, s89
	s_nop 0
	global_load_lds_dwordx4 v[6:7], off
	s_waitcnt vmcnt(8)
	s_waitcnt lgkmcnt(0)
	s_barrier
	s_setprio 1
	s_waitcnt lgkmcnt(0)
	v_mfma_f32_16x16x32_bf16 v[144:147], v[118:121], v[192:195], v[144:147]
	v_mfma_f32_16x16x32_bf16 v[144:147], v[122:125], v[196:199], v[144:147]
	v_mfma_f32_16x16x32_bf16 v[112:115], v[118:121], v[200:203], v[112:115]
	v_mfma_f32_16x16x32_bf16 v[112:115], v[122:125], v[220:223], v[112:115]
	v_mfma_f32_16x16x32_bf16 v[96:99], v[118:121], v[224:227], v[96:99]
	v_mfma_f32_16x16x32_bf16 v[96:99], v[122:125], v[228:231], v[96:99]
	v_mfma_f32_16x16x32_bf16 v[80:83], v[118:121], v[232:235], v[80:83]
	v_mfma_f32_16x16x32_bf16 v[80:83], v[122:125], v[236:239], v[80:83]
	v_mfma_f32_16x16x32_bf16 v[140:143], v[132:135], v[192:195], v[140:143]
	v_mfma_f32_16x16x32_bf16 v[140:143], v[148:151], v[196:199], v[140:143]
	v_mfma_f32_16x16x32_bf16 v[108:111], v[132:135], v[200:203], v[108:111]
	v_mfma_f32_16x16x32_bf16 v[108:111], v[148:151], v[220:223], v[108:111]
	v_mfma_f32_16x16x32_bf16 v[92:95], v[132:135], v[224:227], v[92:95]
	v_mfma_f32_16x16x32_bf16 v[92:95], v[148:151], v[228:231], v[92:95]
	v_mfma_f32_16x16x32_bf16 v[76:79], v[132:135], v[232:235], v[76:79]
	v_mfma_f32_16x16x32_bf16 v[76:79], v[148:151], v[236:239], v[76:79]
	s_setprio 0
	s_setprio 1
	v_mfma_f32_16x16x32_bf16 v[136:139], v[152:155], v[192:195], v[136:139]
	v_mfma_f32_16x16x32_bf16 v[136:139], v[156:159], v[196:199], v[136:139]
	v_mfma_f32_16x16x32_bf16 v[104:107], v[152:155], v[200:203], v[104:107]
	v_mfma_f32_16x16x32_bf16 v[104:107], v[156:159], v[220:223], v[104:107]
	v_mfma_f32_16x16x32_bf16 v[88:91], v[152:155], v[224:227], v[88:91]
	v_mfma_f32_16x16x32_bf16 v[88:91], v[156:159], v[228:231], v[88:91]
	v_mfma_f32_16x16x32_bf16 v[72:75], v[152:155], v[232:235], v[72:75]
	v_mfma_f32_16x16x32_bf16 v[72:75], v[156:159], v[236:239], v[72:75]
	v_mfma_f32_16x16x32_bf16 v[126:129], v[160:163], v[192:195], v[126:129]
	v_mfma_f32_16x16x32_bf16 v[100:103], v[160:163], v[200:203], v[100:103]
	v_mfma_f32_16x16x32_bf16 v[100:103], v[188:191], v[220:223], v[100:103]
	v_mfma_f32_16x16x32_bf16 v[84:87], v[160:163], v[224:227], v[84:87]
	v_mfma_f32_16x16x32_bf16 v[84:87], v[188:191], v[228:231], v[84:87]
	v_mfma_f32_16x16x32_bf16 v[68:71], v[160:163], v[232:235], v[68:71]
	v_mfma_f32_16x16x32_bf16 v[68:71], v[188:191], v[236:239], v[68:71]
	v_mfma_f32_16x16x32_bf16 v[128:131], v[188:191], v[196:199], v[126:129]
	s_setprio 0
	s_barrier
	s_add_i32 s20, s20, s14
	v_lshl_add_u64 v[6:7], v[240:241], 0, s[34:35]
	s_mov_b32 m0, s20
	ds_read_b128 v[192:195], v218 offset:49152
	ds_read_b128 v[196:199], v218 offset:50176
	ds_read_b128 v[200:203], v218 offset:51200
	ds_read_b128 v[220:223], v218 offset:52224
	ds_read_b128 v[224:227], v218 offset:53248
	ds_read_b128 v[228:231], v218 offset:54272
	ds_read_b128 v[232:235], v218 offset:55296
	ds_read_b128 v[236:239], v218 offset:56320
	global_load_lds_dwordx4 v[6:7], off
	v_lshl_add_u64 v[6:7], v[240:241], 0, s[38:39]
	s_add_i32 m0, s20, 0x2000
	s_add_i32 s20, s21, s14
	global_load_lds_dwordx4 v[6:7], off
	v_lshl_add_u64 v[6:7], v[240:241], 0, s[44:45]
	s_mov_b32 m0, s20
	s_nop 0
	global_load_lds_dwordx4 v[6:7], off
	v_lshl_add_u64 v[6:7], v[240:241], 0, s[10:11]
	s_add_i32 m0, s20, 0x2000
	s_nop 0
	global_load_lds_dwordx4 v[6:7], off
	v_lshl_add_u64 v[6:7], v[242:243], 0, s[34:35]
	s_mov_b32 m0, s90
	s_nop 0
	global_load_lds_dwordx4 v[6:7], off
	v_lshl_add_u64 v[6:7], v[242:243], 0, s[38:39]
	s_mov_b32 m0, s91
	s_nop 0
	global_load_lds_dwordx4 v[6:7], off
	s_waitcnt vmcnt(8)
	s_waitcnt lgkmcnt(0)
	s_barrier
	s_setprio 1
	s_waitcnt lgkmcnt(0)
	v_mfma_f32_16x16x32_bf16 v[64:67], v[118:121], v[192:195], v[64:67]
	v_mfma_f32_16x16x32_bf16 v[64:67], v[122:125], v[196:199], v[64:67]
	v_mfma_f32_16x16x32_bf16 v[48:51], v[118:121], v[200:203], v[48:51]
	v_mfma_f32_16x16x32_bf16 v[48:51], v[122:125], v[220:223], v[48:51]
	v_mfma_f32_16x16x32_bf16 v[32:35], v[118:121], v[224:227], v[32:35]
	v_mfma_f32_16x16x32_bf16 v[32:35], v[122:125], v[228:231], v[32:35]
	v_mfma_f32_16x16x32_bf16 v[16:19], v[118:121], v[232:235], v[16:19]
	v_mfma_f32_16x16x32_bf16 v[16:19], v[122:125], v[236:239], v[16:19]
	v_mfma_f32_16x16x32_bf16 v[60:63], v[132:135], v[192:195], v[60:63]
	v_mfma_f32_16x16x32_bf16 v[60:63], v[148:151], v[196:199], v[60:63]
	v_mfma_f32_16x16x32_bf16 v[44:47], v[132:135], v[200:203], v[44:47]
	v_mfma_f32_16x16x32_bf16 v[44:47], v[148:151], v[220:223], v[44:47]
	v_mfma_f32_16x16x32_bf16 v[28:31], v[132:135], v[224:227], v[28:31]
	v_mfma_f32_16x16x32_bf16 v[28:31], v[148:151], v[228:231], v[28:31]
	v_mfma_f32_16x16x32_bf16 v[12:15], v[132:135], v[232:235], v[12:15]
	v_mfma_f32_16x16x32_bf16 v[12:15], v[148:151], v[236:239], v[12:15]
	s_setprio 0
	s_setprio 1
	v_mfma_f32_16x16x32_bf16 v[56:59], v[152:155], v[192:195], v[56:59]
	v_mfma_f32_16x16x32_bf16 v[56:59], v[156:159], v[196:199], v[56:59]
	v_mfma_f32_16x16x32_bf16 v[40:43], v[152:155], v[200:203], v[40:43]
	v_mfma_f32_16x16x32_bf16 v[40:43], v[156:159], v[220:223], v[40:43]
	v_mfma_f32_16x16x32_bf16 v[24:27], v[152:155], v[224:227], v[24:27]
	v_mfma_f32_16x16x32_bf16 v[24:27], v[156:159], v[228:231], v[24:27]
	v_mfma_f32_16x16x32_bf16 v[6:9], v[152:155], v[232:235], v[8:11]
	v_mfma_f32_16x16x32_bf16 v[8:11], v[156:159], v[236:239], v[6:9]
	v_mfma_f32_16x16x32_bf16 v[52:55], v[160:163], v[192:195], v[52:55]
	v_mfma_f32_16x16x32_bf16 v[52:55], v[188:191], v[196:199], v[52:55]
	v_mfma_f32_16x16x32_bf16 v[36:39], v[160:163], v[200:203], v[36:39]
	v_mfma_f32_16x16x32_bf16 v[36:39], v[188:191], v[220:223], v[36:39]
	v_mfma_f32_16x16x32_bf16 v[20:23], v[160:163], v[224:227], v[20:23]
	v_mfma_f32_16x16x32_bf16 v[20:23], v[188:191], v[228:231], v[20:23]
	v_mfma_f32_16x16x32_bf16 v[2:5], v[160:163], v[232:235], v[2:5]
	v_mfma_f32_16x16x32_bf16 v[4:7], v[188:191], v[236:239], v[2:5]
	s_setprio 0
	s_barrier
	s_add_i32 vcc_hi, vcc_hi, 2
	s_add_u32 s68, s68, 0x100
	s_addc_u32 s69, s69, 0
	s_cmp_gt_u32 vcc_hi, 13
	s_cbranch_scc1 .LBB0_565

.Lmid1_604:
	s_add_i32 s22, 0, 0x10000
	s_add_i32 s23, 0, 0x14000
	s_add_u32 s20, s6, 0xfffe0080
	s_addc_u32 s21, s7, -1
	s_cmp_eq_u32 s84, 4
	s_cselect_b32 s69, s42, s21
	s_cselect_b32 s68, s43, s20
	s_cselect_b32 s21, s46, s51
	s_cselect_b32 s20, s47, s49
	s_add_i32 m0, s89, 0xc000
	v_lshl_add_u64 v[162:163], s[6:7], 0, v[132:133]
	global_load_lds_dwordx4 v[162:163], off
	v_lshl_add_u64 v[162:163], v[162:163], 0, s[64:65]
	s_add_i32 m0, s89, 0xe000
	s_nop 0
	global_load_lds_dwordx4 v[162:163], off
	s_waitcnt vmcnt(8)
	s_waitcnt lgkmcnt(0)
	s_barrier
	s_setprio 1
	s_waitcnt lgkmcnt(0)
	v_mfma_f32_16x16x32_bf16 v[126:129], v[134:137], v[190:193], 0
	v_mfma_f32_16x16x32_bf16 v[126:129], v[142:145], v[194:197], v[126:129]
	v_mfma_f32_16x16x32_bf16 v[110:113], v[134:137], v[198:201], 0
	v_mfma_f32_16x16x32_bf16 v[110:113], v[142:145], v[214:217], v[110:113]
	v_mfma_f32_16x16x32_bf16 v[94:97], v[134:137], v[218:221], 0
	v_mfma_f32_16x16x32_bf16 v[94:97], v[142:145], v[222:225], v[94:97]
	v_mfma_f32_16x16x32_bf16 v[78:81], v[134:137], v[226:229], 0
	v_mfma_f32_16x16x32_bf16 v[78:81], v[142:145], v[230:233], v[78:81]
	v_mfma_f32_16x16x32_bf16 v[122:125], v[146:149], v[190:193], 0
	v_mfma_f32_16x16x32_bf16 v[122:125], v[150:153], v[194:197], v[122:125]
	v_mfma_f32_16x16x32_bf16 v[106:109], v[146:149], v[198:201], 0
	v_mfma_f32_16x16x32_bf16 v[106:109], v[150:153], v[214:217], v[106:109]
	v_mfma_f32_16x16x32_bf16 v[90:93], v[146:149], v[218:221], 0
	v_mfma_f32_16x16x32_bf16 v[90:93], v[150:153], v[222:225], v[90:93]
	v_mfma_f32_16x16x32_bf16 v[74:77], v[146:149], v[226:229], 0
	v_mfma_f32_16x16x32_bf16 v[74:77], v[150:153], v[230:233], v[74:77]
	s_setprio 0
	s_setprio 1
	v_mfma_f32_16x16x32_bf16 v[118:121], v[154:157], v[190:193], 0
	v_mfma_f32_16x16x32_bf16 v[118:121], v[158:161], v[194:197], v[118:121]
	v_mfma_f32_16x16x32_bf16 v[102:105], v[154:157], v[198:201], 0
	v_mfma_f32_16x16x32_bf16 v[102:105], v[158:161], v[214:217], v[102:105]
	v_mfma_f32_16x16x32_bf16 v[86:89], v[154:157], v[218:221], 0
	v_mfma_f32_16x16x32_bf16 v[86:89], v[158:161], v[222:225], v[86:89]
	v_mfma_f32_16x16x32_bf16 v[70:73], v[154:157], v[226:229], 0
	v_mfma_f32_16x16x32_bf16 v[70:73], v[158:161], v[230:233], v[70:73]
	v_mfma_f32_16x16x32_bf16 v[114:117], v[182:185], v[190:193], 0
	v_mfma_f32_16x16x32_bf16 v[114:117], v[186:189], v[194:197], v[114:117]
	v_mfma_f32_16x16x32_bf16 v[98:101], v[182:185], v[198:201], 0
	v_mfma_f32_16x16x32_bf16 v[98:101], v[186:189], v[214:217], v[98:101]
	v_mfma_f32_16x16x32_bf16 v[82:85], v[182:185], v[218:221], 0
	v_mfma_f32_16x16x32_bf16 v[82:85], v[186:189], v[222:225], v[82:85]
	v_mfma_f32_16x16x32_bf16 v[66:69], v[182:185], v[226:229], 0
	v_mfma_f32_16x16x32_bf16 v[66:69], v[186:189], v[230:233], v[66:69]
	s_setprio 0
	s_barrier
	ds_read_b128 v[190:193], v141 offset:16384
	ds_read_b128 v[194:197], v141 offset:17408
	ds_read_b128 v[198:201], v141 offset:18432
	ds_read_b128 v[214:217], v141 offset:19456
	ds_read_b128 v[218:221], v141 offset:20480
	ds_read_b128 v[222:225], v141 offset:21504
	ds_read_b128 v[226:229], v141 offset:22528
	ds_read_b128 v[230:233], v141 offset:23552
	v_lshl_add_u64 v[162:163], s[20:21], 0, v[0:1]
	s_add_i32 s20, s22, s88
	s_mov_b32 m0, s20
	s_nop 0
	s_nop 0
	global_load_lds_dwordx4 v[162:163], off
	v_lshl_add_u64 v[202:203], v[162:163], 0, s[64:65]
	s_add_i32 m0, s20, 0x2000
	s_add_i32 s20, s23, s88
	global_load_lds_dwordx4 v[202:203], off
	v_lshl_add_u64 v[202:203], v[162:163], 0, s[72:73]
	s_mov_b32 m0, s20
	s_nop 0
	global_load_lds_dwordx4 v[202:203], off
	v_lshl_add_u64 v[202:203], v[162:163], 0, s[74:75]
	s_add_i32 m0, s20, 0x2000
	s_nop 0
	global_load_lds_dwordx4 v[202:203], off
	v_lshl_add_u64 v[202:203], s[68:69], 0, v[130:131]
	s_mov_b32 m0, s89
	v_lshl_add_u64 v[234:235], v[202:203], 0, s[64:65]
	global_load_lds_dwordx4 v[202:203], off
	s_mov_b32 m0, s90
	s_nop 0
	global_load_lds_dwordx4 v[234:235], off
	s_waitcnt vmcnt(8)
	s_waitcnt lgkmcnt(0)
	s_barrier
	s_setprio 1
	s_waitcnt lgkmcnt(0)
	v_mfma_f32_16x16x32_bf16 v[62:65], v[134:137], v[190:193], 0
	v_mfma_f32_16x16x32_bf16 v[62:65], v[142:145], v[194:197], v[62:65]
	v_mfma_f32_16x16x32_bf16 v[46:49], v[134:137], v[198:201], 0
	v_mfma_f32_16x16x32_bf16 v[46:49], v[142:145], v[214:217], v[46:49]
	v_mfma_f32_16x16x32_bf16 v[30:33], v[134:137], v[218:221], 0
	v_mfma_f32_16x16x32_bf16 v[30:33], v[142:145], v[222:225], v[30:33]
	v_mfma_f32_16x16x32_bf16 v[14:17], v[134:137], v[226:229], 0
	v_mfma_f32_16x16x32_bf16 v[14:17], v[142:145], v[230:233], v[14:17]
	v_mfma_f32_16x16x32_bf16 v[58:61], v[146:149], v[190:193], 0
	v_mfma_f32_16x16x32_bf16 v[58:61], v[150:153], v[194:197], v[58:61]
	v_mfma_f32_16x16x32_bf16 v[42:45], v[146:149], v[198:201], 0
	v_mfma_f32_16x16x32_bf16 v[42:45], v[150:153], v[214:217], v[42:45]
	v_mfma_f32_16x16x32_bf16 v[26:29], v[146:149], v[218:221], 0
	v_mfma_f32_16x16x32_bf16 v[26:29], v[150:153], v[222:225], v[26:29]
	v_mfma_f32_16x16x32_bf16 v[10:13], v[146:149], v[226:229], 0
	v_mfma_f32_16x16x32_bf16 v[10:13], v[150:153], v[230:233], v[10:13]
	s_setprio 0
	s_setprio 1
	v_mfma_f32_16x16x32_bf16 v[54:57], v[154:157], v[190:193], 0
	v_mfma_f32_16x16x32_bf16 v[54:57], v[158:161], v[194:197], v[54:57]
	v_mfma_f32_16x16x32_bf16 v[38:41], v[154:157], v[198:201], 0
	v_mfma_f32_16x16x32_bf16 v[38:41], v[158:161], v[214:217], v[38:41]
	v_mfma_f32_16x16x32_bf16 v[22:25], v[154:157], v[218:221], 0
	v_mfma_f32_16x16x32_bf16 v[22:25], v[158:161], v[222:225], v[22:25]
	v_mfma_f32_16x16x32_bf16 v[6:9], v[154:157], v[226:229], 0
	v_mfma_f32_16x16x32_bf16 v[6:9], v[158:161], v[230:233], v[6:9]
	v_mfma_f32_16x16x32_bf16 v[50:53], v[182:185], v[190:193], 0
	v_mfma_f32_16x16x32_bf16 v[50:53], v[186:189], v[194:197], v[50:53]
	v_mfma_f32_16x16x32_bf16 v[34:37], v[182:185], v[198:201], 0
	v_mfma_f32_16x16x32_bf16 v[34:37], v[186:189], v[214:217], v[34:37]
	v_mfma_f32_16x16x32_bf16 v[18:21], v[182:185], v[218:221], 0
	v_mfma_f32_16x16x32_bf16 v[18:21], v[186:189], v[222:225], v[18:21]
	v_mfma_f32_16x16x32_bf16 v[2:5], v[182:185], v[226:229], 0
	v_mfma_f32_16x16x32_bf16 v[2:5], v[186:189], v[230:233], v[2:5]
	s_setprio 0
	s_barrier
	s_add_i32 s20, 0, 0x18000
	s_add_i32 s21, 0, 0x1c000
	v_add_u32_e32 v150, s20, v139
	v_add_u32_e32 v186, s21, v139
	ds_read_b128 v[134:137], v150
	ds_read_b128 v[142:145], v150 offset:1024
	ds_read_b128 v[146:149], v150 offset:2048
	ds_read_b128 v[150:153], v150 offset:3072
	ds_read_b128 v[154:157], v186
	ds_read_b128 v[158:161], v186 offset:1024
	ds_read_b128 v[182:185], v186 offset:2048
	ds_read_b128 v[186:189], v186 offset:3072
	ds_read_b128 v[190:193], v141 offset:32768
	ds_read_b128 v[194:197], v141 offset:33792
	ds_read_b128 v[198:201], v141 offset:34816
	ds_read_b128 v[214:217], v141 offset:35840
	ds_read_b128 v[218:221], v141 offset:36864
	ds_read_b128 v[222:225], v141 offset:37888
	ds_read_b128 v[226:229], v141 offset:38912
	ds_read_b128 v[230:233], v141 offset:39936
	s_mov_b32 m0, s91
	v_lshl_add_u64 v[234:235], v[202:203], 0, s[72:73]
	global_load_lds_dwordx4 v[234:235], off
	v_lshl_add_u64 v[234:235], v[202:203], 0, s[74:75]
	s_mov_b32 m0, s96
	s_nop 0
	global_load_lds_dwordx4 v[234:235], off
	s_waitcnt vmcnt(8)
	s_waitcnt lgkmcnt(0)
	s_barrier
	s_setprio 1
	s_waitcnt lgkmcnt(0)
	v_mfma_f32_16x16x32_bf16 v[126:129], v[134:137], v[190:193], v[126:129]
	v_mfma_f32_16x16x32_bf16 v[126:129], v[142:145], v[194:197], v[126:129]
	v_mfma_f32_16x16x32_bf16 v[110:113], v[134:137], v[198:201], v[110:113]
	v_mfma_f32_16x16x32_bf16 v[110:113], v[142:145], v[214:217], v[110:113]
	v_mfma_f32_16x16x32_bf16 v[94:97], v[134:137], v[218:221], v[94:97]
	v_mfma_f32_16x16x32_bf16 v[94:97], v[142:145], v[222:225], v[94:97]
	v_mfma_f32_16x16x32_bf16 v[78:81], v[134:137], v[226:229], v[78:81]
	v_mfma_f32_16x16x32_bf16 v[78:81], v[142:145], v[230:233], v[78:81]
	v_mfma_f32_16x16x32_bf16 v[122:125], v[146:149], v[190:193], v[122:125]
	v_mfma_f32_16x16x32_bf16 v[122:125], v[150:153], v[194:197], v[122:125]
	v_mfma_f32_16x16x32_bf16 v[106:109], v[146:149], v[198:201], v[106:109]
	v_mfma_f32_16x16x32_bf16 v[106:109], v[150:153], v[214:217], v[106:109]
	v_mfma_f32_16x16x32_bf16 v[90:93], v[146:149], v[218:221], v[90:93]
	v_mfma_f32_16x16x32_bf16 v[90:93], v[150:153], v[222:225], v[90:93]
	v_mfma_f32_16x16x32_bf16 v[74:77], v[146:149], v[226:229], v[74:77]
	v_mfma_f32_16x16x32_bf16 v[74:77], v[150:153], v[230:233], v[74:77]
	s_setprio 0
	s_setprio 1
	v_mfma_f32_16x16x32_bf16 v[118:121], v[154:157], v[190:193], v[118:121]
	v_mfma_f32_16x16x32_bf16 v[118:121], v[158:161], v[194:197], v[118:121]
	v_mfma_f32_16x16x32_bf16 v[102:105], v[154:157], v[198:201], v[102:105]
	v_mfma_f32_16x16x32_bf16 v[102:105], v[158:161], v[214:217], v[102:105]
	v_mfma_f32_16x16x32_bf16 v[86:89], v[154:157], v[218:221], v[86:89]
	v_mfma_f32_16x16x32_bf16 v[86:89], v[158:161], v[222:225], v[86:89]
	v_mfma_f32_16x16x32_bf16 v[70:73], v[154:157], v[226:229], v[70:73]
	v_mfma_f32_16x16x32_bf16 v[70:73], v[158:161], v[230:233], v[70:73]
	v_mfma_f32_16x16x32_bf16 v[114:117], v[182:185], v[190:193], v[114:117]
	v_mfma_f32_16x16x32_bf16 v[114:117], v[186:189], v[194:197], v[114:117]
	v_mfma_f32_16x16x32_bf16 v[98:101], v[182:185], v[198:201], v[98:101]
	v_mfma_f32_16x16x32_bf16 v[98:101], v[186:189], v[214:217], v[98:101]
	v_mfma_f32_16x16x32_bf16 v[82:85], v[182:185], v[218:221], v[82:85]
	v_mfma_f32_16x16x32_bf16 v[82:85], v[186:189], v[222:225], v[82:85]
	v_mfma_f32_16x16x32_bf16 v[66:69], v[182:185], v[226:229], v[66:69]
	v_mfma_f32_16x16x32_bf16 v[66:69], v[186:189], v[230:233], v[66:69]
	s_setprio 0
	s_barrier
	ds_read_b128 v[190:193], v141 offset:49152
	ds_read_b128 v[194:197], v141 offset:50176
	ds_read_b128 v[198:201], v141 offset:51200
	ds_read_b128 v[214:217], v141 offset:52224
	ds_read_b128 v[218:221], v141 offset:53248
	ds_read_b128 v[222:225], v141 offset:54272
	ds_read_b128 v[226:229], v141 offset:55296
	ds_read_b128 v[230:233], v141 offset:56320
	s_add_i32 s20, s20, s88
	s_mov_b32 m0, s20
	v_lshl_add_u64 v[234:235], v[162:163], 0, s[34:35]
	global_load_lds_dwordx4 v[234:235], off
	v_lshl_add_u64 v[234:235], v[162:163], 0, s[80:81]
	s_add_i32 m0, s20, 0x2000
	s_add_i32 s20, s21, s88
	global_load_lds_dwordx4 v[234:235], off
	v_lshl_add_u64 v[234:235], v[162:163], 0, s[38:39]
	s_mov_b32 m0, s20
	v_lshl_add_u64 v[162:163], v[162:163], 0, s[86:87]
	global_load_lds_dwordx4 v[234:235], off
	s_add_i32 m0, s20, 0x2000
	s_nop 0
	global_load_lds_dwordx4 v[162:163], off
	v_lshl_add_u64 v[162:163], v[202:203], 0, s[34:35]
	s_mov_b32 m0, s97
	s_nop 0
	global_load_lds_dwordx4 v[162:163], off
	v_lshl_add_u64 v[162:163], v[202:203], 0, s[80:81]
	s_mov_b32 m0, s58
	s_nop 0
	global_load_lds_dwordx4 v[162:163], off
	s_waitcnt vmcnt(8)
	s_waitcnt lgkmcnt(0)
	s_barrier
	s_setprio 1
	s_waitcnt lgkmcnt(0)
	v_mfma_f32_16x16x32_bf16 v[62:65], v[134:137], v[190:193], v[62:65]
	v_mfma_f32_16x16x32_bf16 v[62:65], v[142:145], v[194:197], v[62:65]
	v_mfma_f32_16x16x32_bf16 v[46:49], v[134:137], v[198:201], v[46:49]
	v_mfma_f32_16x16x32_bf16 v[46:49], v[142:145], v[214:217], v[46:49]
	v_mfma_f32_16x16x32_bf16 v[30:33], v[134:137], v[218:221], v[30:33]
	v_mfma_f32_16x16x32_bf16 v[30:33], v[142:145], v[222:225], v[30:33]
	v_mfma_f32_16x16x32_bf16 v[14:17], v[134:137], v[226:229], v[14:17]
	v_mfma_f32_16x16x32_bf16 v[14:17], v[142:145], v[230:233], v[14:17]
	v_mfma_f32_16x16x32_bf16 v[58:61], v[146:149], v[190:193], v[58:61]
	v_mfma_f32_16x16x32_bf16 v[58:61], v[150:153], v[194:197], v[58:61]
	v_mfma_f32_16x16x32_bf16 v[42:45], v[146:149], v[198:201], v[42:45]
	v_mfma_f32_16x16x32_bf16 v[42:45], v[150:153], v[214:217], v[42:45]
	v_mfma_f32_16x16x32_bf16 v[26:29], v[146:149], v[218:221], v[26:29]
	v_mfma_f32_16x16x32_bf16 v[26:29], v[150:153], v[222:225], v[26:29]
	v_mfma_f32_16x16x32_bf16 v[10:13], v[146:149], v[226:229], v[10:13]
	v_mfma_f32_16x16x32_bf16 v[10:13], v[150:153], v[230:233], v[10:13]
	s_add_i32 s84, s84, 2
	s_add_u32 s6, s6, 0x100
	s_addc_u32 s7, s7, 0
	s_add_u32 s49, s49, 0x100
	s_addc_u32 s51, s51, 0
	s_setprio 0
	s_setprio 1
	v_mfma_f32_16x16x32_bf16 v[54:57], v[154:157], v[190:193], v[54:57]
	v_mfma_f32_16x16x32_bf16 v[54:57], v[158:161], v[194:197], v[54:57]
	v_mfma_f32_16x16x32_bf16 v[38:41], v[154:157], v[198:201], v[38:41]
	v_mfma_f32_16x16x32_bf16 v[38:41], v[158:161], v[214:217], v[38:41]
	v_mfma_f32_16x16x32_bf16 v[22:25], v[154:157], v[218:221], v[22:25]
	v_mfma_f32_16x16x32_bf16 v[22:25], v[158:161], v[222:225], v[22:25]
	v_mfma_f32_16x16x32_bf16 v[6:9], v[154:157], v[226:229], v[6:9]
	v_mfma_f32_16x16x32_bf16 v[6:9], v[158:161], v[230:233], v[6:9]
	v_mfma_f32_16x16x32_bf16 v[50:53], v[182:185], v[190:193], v[50:53]
	v_mfma_f32_16x16x32_bf16 v[50:53], v[186:189], v[194:197], v[50:53]
	v_mfma_f32_16x16x32_bf16 v[34:37], v[182:185], v[198:201], v[34:37]
	v_mfma_f32_16x16x32_bf16 v[34:37], v[186:189], v[214:217], v[34:37]
	v_mfma_f32_16x16x32_bf16 v[18:21], v[182:185], v[218:221], v[18:21]
	v_mfma_f32_16x16x32_bf16 v[18:21], v[186:189], v[222:225], v[18:21]
	v_mfma_f32_16x16x32_bf16 v[2:5], v[182:185], v[226:229], v[2:5]
	v_mfma_f32_16x16x32_bf16 v[2:5], v[186:189], v[230:233], v[2:5]
	s_setprio 0
	s_barrier
	s_branch .LBB0_604
	.p2alignl 6, 3212836864
.LBB0_604:
	s_add_i32 s22, 0, 0x10000
	s_add_i32 s23, 0, 0x14000
	v_add_u32_e32 v150, s22, v139
	v_add_u32_e32 v162, s23, v139
	ds_read_b128 v[134:137], v150
	ds_read_b128 v[142:145], v150 offset:1024
	ds_read_b128 v[146:149], v150 offset:2048
	ds_read_b128 v[150:153], v150 offset:3072
	ds_read_b128 v[154:157], v162
	ds_read_b128 v[158:161], v162 offset:1024
	ds_read_b128 v[182:185], v162 offset:2048
	ds_read_b128 v[186:189], v162 offset:3072
	ds_read_b128 v[190:193], v141
	ds_read_b128 v[194:197], v141 offset:1024
	ds_read_b128 v[198:201], v141 offset:2048
	ds_read_b128 v[214:217], v141 offset:3072
	ds_read_b128 v[218:221], v141 offset:4096
	ds_read_b128 v[222:225], v141 offset:5120
	ds_read_b128 v[226:229], v141 offset:6144
	ds_read_b128 v[230:233], v141 offset:7168
	s_add_u32 s20, s6, 0xfffe0080
	s_addc_u32 s21, s7, -1
	s_cmp_eq_u32 s84, 4
	s_cselect_b32 s69, s42, s21
	s_cselect_b32 s68, s43, s20
	s_cselect_b32 s21, s46, s51
	s_cselect_b32 s20, s47, s49
	s_add_i32 m0, s89, 0xc000
	v_lshl_add_u64 v[162:163], s[6:7], 0, v[132:133]
	global_load_lds_dwordx4 v[162:163], off
	v_lshl_add_u64 v[162:163], v[162:163], 0, s[64:65]
	s_add_i32 m0, s89, 0xe000
	s_nop 0
	global_load_lds_dwordx4 v[162:163], off
	s_waitcnt vmcnt(8)
	s_waitcnt lgkmcnt(0)
	s_barrier
	s_setprio 1
	s_waitcnt lgkmcnt(0)
	v_mfma_f32_16x16x32_bf16 v[126:129], v[134:137], v[190:193], v[126:129]
	v_mfma_f32_16x16x32_bf16 v[126:129], v[142:145], v[194:197], v[126:129]
	v_mfma_f32_16x16x32_bf16 v[110:113], v[134:137], v[198:201], v[110:113]
	v_mfma_f32_16x16x32_bf16 v[110:113], v[142:145], v[214:217], v[110:113]
	v_mfma_f32_16x16x32_bf16 v[94:97], v[134:137], v[218:221], v[94:97]
	v_mfma_f32_16x16x32_bf16 v[94:97], v[142:145], v[222:225], v[94:97]
	v_mfma_f32_16x16x32_bf16 v[78:81], v[134:137], v[226:229], v[78:81]
	v_mfma_f32_16x16x32_bf16 v[78:81], v[142:145], v[230:233], v[78:81]
	v_mfma_f32_16x16x32_bf16 v[122:125], v[146:149], v[190:193], v[122:125]
	v_mfma_f32_16x16x32_bf16 v[122:125], v[150:153], v[194:197], v[122:125]
	v_mfma_f32_16x16x32_bf16 v[106:109], v[146:149], v[198:201], v[106:109]
	v_mfma_f32_16x16x32_bf16 v[106:109], v[150:153], v[214:217], v[106:109]
	v_mfma_f32_16x16x32_bf16 v[90:93], v[146:149], v[218:221], v[90:93]
	v_mfma_f32_16x16x32_bf16 v[90:93], v[150:153], v[222:225], v[90:93]
	v_mfma_f32_16x16x32_bf16 v[74:77], v[146:149], v[226:229], v[74:77]
	v_mfma_f32_16x16x32_bf16 v[74:77], v[150:153], v[230:233], v[74:77]
	s_setprio 0
	s_setprio 1
	v_mfma_f32_16x16x32_bf16 v[118:121], v[154:157], v[190:193], v[118:121]
	v_mfma_f32_16x16x32_bf16 v[118:121], v[158:161], v[194:197], v[118:121]
	v_mfma_f32_16x16x32_bf16 v[102:105], v[154:157], v[198:201], v[102:105]
	v_mfma_f32_16x16x32_bf16 v[102:105], v[158:161], v[214:217], v[102:105]
	v_mfma_f32_16x16x32_bf16 v[86:89], v[154:157], v[218:221], v[86:89]
	v_mfma_f32_16x16x32_bf16 v[86:89], v[158:161], v[222:225], v[86:89]
	v_mfma_f32_16x16x32_bf16 v[70:73], v[154:157], v[226:229], v[70:73]
	v_mfma_f32_16x16x32_bf16 v[70:73], v[158:161], v[230:233], v[70:73]
	v_mfma_f32_16x16x32_bf16 v[114:117], v[182:185], v[190:193], v[114:117]
	v_mfma_f32_16x16x32_bf16 v[114:117], v[186:189], v[194:197], v[114:117]
	v_mfma_f32_16x16x32_bf16 v[98:101], v[182:185], v[198:201], v[98:101]
	v_mfma_f32_16x16x32_bf16 v[98:101], v[186:189], v[214:217], v[98:101]
	v_mfma_f32_16x16x32_bf16 v[82:85], v[182:185], v[218:221], v[82:85]
	v_mfma_f32_16x16x32_bf16 v[82:85], v[186:189], v[222:225], v[82:85]
	v_mfma_f32_16x16x32_bf16 v[66:69], v[182:185], v[226:229], v[66:69]
	v_mfma_f32_16x16x32_bf16 v[66:69], v[186:189], v[230:233], v[66:69]
	s_setprio 0
	s_barrier
	ds_read_b128 v[190:193], v141 offset:16384
	ds_read_b128 v[194:197], v141 offset:17408
	ds_read_b128 v[198:201], v141 offset:18432
	ds_read_b128 v[214:217], v141 offset:19456
	ds_read_b128 v[218:221], v141 offset:20480
	ds_read_b128 v[222:225], v141 offset:21504
	ds_read_b128 v[226:229], v141 offset:22528
	ds_read_b128 v[230:233], v141 offset:23552
	v_lshl_add_u64 v[162:163], s[20:21], 0, v[0:1]
	s_add_i32 s20, s22, s88
	s_mov_b32 m0, s20
	s_nop 0
	s_nop 0
	global_load_lds_dwordx4 v[162:163], off
	v_lshl_add_u64 v[202:203], v[162:163], 0, s[64:65]
	s_add_i32 m0, s20, 0x2000
	s_add_i32 s20, s23, s88
	global_load_lds_dwordx4 v[202:203], off
	v_lshl_add_u64 v[202:203], v[162:163], 0, s[72:73]
	s_mov_b32 m0, s20
	s_nop 0
	global_load_lds_dwordx4 v[202:203], off
	v_lshl_add_u64 v[202:203], v[162:163], 0, s[74:75]
	s_add_i32 m0, s20, 0x2000
	s_nop 0
	global_load_lds_dwordx4 v[202:203], off
	v_lshl_add_u64 v[202:203], s[68:69], 0, v[130:131]
	s_mov_b32 m0, s89
	v_lshl_add_u64 v[234:235], v[202:203], 0, s[64:65]
	global_load_lds_dwordx4 v[202:203], off
	s_mov_b32 m0, s90
	s_nop 0
	global_load_lds_dwordx4 v[234:235], off
	s_waitcnt vmcnt(8)
	s_waitcnt lgkmcnt(0)
	s_barrier
	s_setprio 1
	s_waitcnt lgkmcnt(0)
	v_mfma_f32_16x16x32_bf16 v[62:65], v[134:137], v[190:193], v[62:65]
	v_mfma_f32_16x16x32_bf16 v[62:65], v[142:145], v[194:197], v[62:65]
	v_mfma_f32_16x16x32_bf16 v[46:49], v[134:137], v[198:201], v[46:49]
	v_mfma_f32_16x16x32_bf16 v[46:49], v[142:145], v[214:217], v[46:49]
	v_mfma_f32_16x16x32_bf16 v[30:33], v[134:137], v[218:221], v[30:33]
	v_mfma_f32_16x16x32_bf16 v[30:33], v[142:145], v[222:225], v[30:33]
	v_mfma_f32_16x16x32_bf16 v[14:17], v[134:137], v[226:229], v[14:17]
	v_mfma_f32_16x16x32_bf16 v[14:17], v[142:145], v[230:233], v[14:17]
	v_mfma_f32_16x16x32_bf16 v[58:61], v[146:149], v[190:193], v[58:61]
	v_mfma_f32_16x16x32_bf16 v[58:61], v[150:153], v[194:197], v[58:61]
	v_mfma_f32_16x16x32_bf16 v[42:45], v[146:149], v[198:201], v[42:45]
	v_mfma_f32_16x16x32_bf16 v[42:45], v[150:153], v[214:217], v[42:45]
	v_mfma_f32_16x16x32_bf16 v[26:29], v[146:149], v[218:221], v[26:29]
	v_mfma_f32_16x16x32_bf16 v[26:29], v[150:153], v[222:225], v[26:29]
	v_mfma_f32_16x16x32_bf16 v[10:13], v[146:149], v[226:229], v[10:13]
	v_mfma_f32_16x16x32_bf16 v[10:13], v[150:153], v[230:233], v[10:13]
	s_setprio 0
	s_setprio 1
	v_mfma_f32_16x16x32_bf16 v[54:57], v[154:157], v[190:193], v[54:57]
	v_mfma_f32_16x16x32_bf16 v[54:57], v[158:161], v[194:197], v[54:57]
	v_mfma_f32_16x16x32_bf16 v[38:41], v[154:157], v[198:201], v[38:41]
	v_mfma_f32_16x16x32_bf16 v[38:41], v[158:161], v[214:217], v[38:41]
	v_mfma_f32_16x16x32_bf16 v[22:25], v[154:157], v[218:221], v[22:25]
	v_mfma_f32_16x16x32_bf16 v[22:25], v[158:161], v[222:225], v[22:25]
	v_mfma_f32_16x16x32_bf16 v[6:9], v[154:157], v[226:229], v[6:9]
	v_mfma_f32_16x16x32_bf16 v[6:9], v[158:161], v[230:233], v[6:9]
	v_mfma_f32_16x16x32_bf16 v[50:53], v[182:185], v[190:193], v[50:53]
	v_mfma_f32_16x16x32_bf16 v[50:53], v[186:189], v[194:197], v[50:53]
	v_mfma_f32_16x16x32_bf16 v[34:37], v[182:185], v[198:201], v[34:37]
	v_mfma_f32_16x16x32_bf16 v[34:37], v[186:189], v[214:217], v[34:37]
	v_mfma_f32_16x16x32_bf16 v[18:21], v[182:185], v[218:221], v[18:21]
	v_mfma_f32_16x16x32_bf16 v[18:21], v[186:189], v[222:225], v[18:21]
	v_mfma_f32_16x16x32_bf16 v[2:5], v[182:185], v[226:229], v[2:5]
	v_mfma_f32_16x16x32_bf16 v[2:5], v[186:189], v[230:233], v[2:5]
	s_setprio 0
	s_barrier
	s_add_i32 s20, 0, 0x18000
	s_add_i32 s21, 0, 0x1c000
	v_add_u32_e32 v150, s20, v139
	v_add_u32_e32 v186, s21, v139
	ds_read_b128 v[134:137], v150
	ds_read_b128 v[142:145], v150 offset:1024
	ds_read_b128 v[146:149], v150 offset:2048
	ds_read_b128 v[150:153], v150 offset:3072
	ds_read_b128 v[154:157], v186
	ds_read_b128 v[158:161], v186 offset:1024
	ds_read_b128 v[182:185], v186 offset:2048
	ds_read_b128 v[186:189], v186 offset:3072
	ds_read_b128 v[190:193], v141 offset:32768
	ds_read_b128 v[194:197], v141 offset:33792
	ds_read_b128 v[198:201], v141 offset:34816
	ds_read_b128 v[214:217], v141 offset:35840
	ds_read_b128 v[218:221], v141 offset:36864
	ds_read_b128 v[222:225], v141 offset:37888
	ds_read_b128 v[226:229], v141 offset:38912
	ds_read_b128 v[230:233], v141 offset:39936
	s_mov_b32 m0, s91
	v_lshl_add_u64 v[234:235], v[202:203], 0, s[72:73]
	global_load_lds_dwordx4 v[234:235], off
	v_lshl_add_u64 v[234:235], v[202:203], 0, s[74:75]
	s_mov_b32 m0, s96
	s_nop 0
	global_load_lds_dwordx4 v[234:235], off
	s_waitcnt vmcnt(8)
	s_waitcnt lgkmcnt(0)
	s_barrier
	s_setprio 1
	s_waitcnt lgkmcnt(0)
	v_mfma_f32_16x16x32_bf16 v[126:129], v[134:137], v[190:193], v[126:129]
	v_mfma_f32_16x16x32_bf16 v[126:129], v[142:145], v[194:197], v[126:129]
	v_mfma_f32_16x16x32_bf16 v[110:113], v[134:137], v[198:201], v[110:113]
	v_mfma_f32_16x16x32_bf16 v[110:113], v[142:145], v[214:217], v[110:113]
	v_mfma_f32_16x16x32_bf16 v[94:97], v[134:137], v[218:221], v[94:97]
	v_mfma_f32_16x16x32_bf16 v[94:97], v[142:145], v[222:225], v[94:97]
	v_mfma_f32_16x16x32_bf16 v[78:81], v[134:137], v[226:229], v[78:81]
	v_mfma_f32_16x16x32_bf16 v[78:81], v[142:145], v[230:233], v[78:81]
	v_mfma_f32_16x16x32_bf16 v[122:125], v[146:149], v[190:193], v[122:125]
	v_mfma_f32_16x16x32_bf16 v[122:125], v[150:153], v[194:197], v[122:125]
	v_mfma_f32_16x16x32_bf16 v[106:109], v[146:149], v[198:201], v[106:109]
	v_mfma_f32_16x16x32_bf16 v[106:109], v[150:153], v[214:217], v[106:109]
	v_mfma_f32_16x16x32_bf16 v[90:93], v[146:149], v[218:221], v[90:93]
	v_mfma_f32_16x16x32_bf16 v[90:93], v[150:153], v[222:225], v[90:93]
	v_mfma_f32_16x16x32_bf16 v[74:77], v[146:149], v[226:229], v[74:77]
	v_mfma_f32_16x16x32_bf16 v[74:77], v[150:153], v[230:233], v[74:77]
	s_setprio 0
	s_setprio 1
	v_mfma_f32_16x16x32_bf16 v[118:121], v[154:157], v[190:193], v[118:121]
	v_mfma_f32_16x16x32_bf16 v[118:121], v[158:161], v[194:197], v[118:121]
	v_mfma_f32_16x16x32_bf16 v[102:105], v[154:157], v[198:201], v[102:105]
	v_mfma_f32_16x16x32_bf16 v[102:105], v[158:161], v[214:217], v[102:105]
	v_mfma_f32_16x16x32_bf16 v[86:89], v[154:157], v[218:221], v[86:89]
	v_mfma_f32_16x16x32_bf16 v[86:89], v[158:161], v[222:225], v[86:89]
	v_mfma_f32_16x16x32_bf16 v[70:73], v[154:157], v[226:229], v[70:73]
	v_mfma_f32_16x16x32_bf16 v[70:73], v[158:161], v[230:233], v[70:73]
	v_mfma_f32_16x16x32_bf16 v[114:117], v[182:185], v[190:193], v[114:117]
	v_mfma_f32_16x16x32_bf16 v[114:117], v[186:189], v[194:197], v[114:117]
	v_mfma_f32_16x16x32_bf16 v[98:101], v[182:185], v[198:201], v[98:101]
	v_mfma_f32_16x16x32_bf16 v[98:101], v[186:189], v[214:217], v[98:101]
	v_mfma_f32_16x16x32_bf16 v[82:85], v[182:185], v[218:221], v[82:85]
	v_mfma_f32_16x16x32_bf16 v[82:85], v[186:189], v[222:225], v[82:85]
	v_mfma_f32_16x16x32_bf16 v[66:69], v[182:185], v[226:229], v[66:69]
	v_mfma_f32_16x16x32_bf16 v[66:69], v[186:189], v[230:233], v[66:69]
	s_setprio 0
	s_barrier
	ds_read_b128 v[190:193], v141 offset:49152
	ds_read_b128 v[194:197], v141 offset:50176
	ds_read_b128 v[198:201], v141 offset:51200
	ds_read_b128 v[214:217], v141 offset:52224
	ds_read_b128 v[218:221], v141 offset:53248
	ds_read_b128 v[222:225], v141 offset:54272
	ds_read_b128 v[226:229], v141 offset:55296
	ds_read_b128 v[230:233], v141 offset:56320
	s_add_i32 s20, s20, s88
	s_mov_b32 m0, s20
	v_lshl_add_u64 v[234:235], v[162:163], 0, s[34:35]
	global_load_lds_dwordx4 v[234:235], off
	v_lshl_add_u64 v[234:235], v[162:163], 0, s[80:81]
	s_add_i32 m0, s20, 0x2000
	s_add_i32 s20, s21, s88
	global_load_lds_dwordx4 v[234:235], off
	v_lshl_add_u64 v[234:235], v[162:163], 0, s[38:39]
	s_mov_b32 m0, s20
	v_lshl_add_u64 v[162:163], v[162:163], 0, s[86:87]
	global_load_lds_dwordx4 v[234:235], off
	s_add_i32 m0, s20, 0x2000
	s_nop 0
	global_load_lds_dwordx4 v[162:163], off
	v_lshl_add_u64 v[162:163], v[202:203], 0, s[34:35]
	s_mov_b32 m0, s97
	s_nop 0
	global_load_lds_dwordx4 v[162:163], off
	v_lshl_add_u64 v[162:163], v[202:203], 0, s[80:81]
	s_mov_b32 m0, s58
	s_nop 0
	global_load_lds_dwordx4 v[162:163], off
	s_waitcnt vmcnt(8)
	s_waitcnt lgkmcnt(0)
	s_barrier
	s_setprio 1
	s_waitcnt lgkmcnt(0)
	v_mfma_f32_16x16x32_bf16 v[62:65], v[134:137], v[190:193], v[62:65]
	v_mfma_f32_16x16x32_bf16 v[62:65], v[142:145], v[194:197], v[62:65]
	v_mfma_f32_16x16x32_bf16 v[46:49], v[134:137], v[198:201], v[46:49]
	v_mfma_f32_16x16x32_bf16 v[46:49], v[142:145], v[214:217], v[46:49]
	v_mfma_f32_16x16x32_bf16 v[30:33], v[134:137], v[218:221], v[30:33]
	v_mfma_f32_16x16x32_bf16 v[30:33], v[142:145], v[222:225], v[30:33]
	v_mfma_f32_16x16x32_bf16 v[14:17], v[134:137], v[226:229], v[14:17]
	v_mfma_f32_16x16x32_bf16 v[14:17], v[142:145], v[230:233], v[14:17]
	v_mfma_f32_16x16x32_bf16 v[58:61], v[146:149], v[190:193], v[58:61]
	v_mfma_f32_16x16x32_bf16 v[58:61], v[150:153], v[194:197], v[58:61]
	v_mfma_f32_16x16x32_bf16 v[42:45], v[146:149], v[198:201], v[42:45]
	v_mfma_f32_16x16x32_bf16 v[42:45], v[150:153], v[214:217], v[42:45]
	v_mfma_f32_16x16x32_bf16 v[26:29], v[146:149], v[218:221], v[26:29]
	v_mfma_f32_16x16x32_bf16 v[26:29], v[150:153], v[222:225], v[26:29]
	v_mfma_f32_16x16x32_bf16 v[10:13], v[146:149], v[226:229], v[10:13]
	v_mfma_f32_16x16x32_bf16 v[10:13], v[150:153], v[230:233], v[10:13]
	s_add_i32 s84, s84, 2
	s_add_u32 s6, s6, 0x100
	s_addc_u32 s7, s7, 0
	s_add_u32 s49, s49, 0x100
	s_addc_u32 s51, s51, 0
	s_setprio 0
	s_setprio 1
	v_mfma_f32_16x16x32_bf16 v[54:57], v[154:157], v[190:193], v[54:57]
	v_mfma_f32_16x16x32_bf16 v[54:57], v[158:161], v[194:197], v[54:57]
	v_mfma_f32_16x16x32_bf16 v[38:41], v[154:157], v[198:201], v[38:41]
	v_mfma_f32_16x16x32_bf16 v[38:41], v[158:161], v[214:217], v[38:41]
	v_mfma_f32_16x16x32_bf16 v[22:25], v[154:157], v[218:221], v[22:25]
	v_mfma_f32_16x16x32_bf16 v[22:25], v[158:161], v[222:225], v[22:25]
	v_mfma_f32_16x16x32_bf16 v[6:9], v[154:157], v[226:229], v[6:9]
	v_mfma_f32_16x16x32_bf16 v[6:9], v[158:161], v[230:233], v[6:9]
	v_mfma_f32_16x16x32_bf16 v[50:53], v[182:185], v[190:193], v[50:53]
	v_mfma_f32_16x16x32_bf16 v[50:53], v[186:189], v[194:197], v[50:53]
	v_mfma_f32_16x16x32_bf16 v[34:37], v[182:185], v[198:201], v[34:37]
	v_mfma_f32_16x16x32_bf16 v[34:37], v[186:189], v[214:217], v[34:37]
	v_mfma_f32_16x16x32_bf16 v[18:21], v[182:185], v[218:221], v[18:21]
	v_mfma_f32_16x16x32_bf16 v[18:21], v[186:189], v[222:225], v[18:21]
	v_mfma_f32_16x16x32_bf16 v[2:5], v[182:185], v[226:229], v[2:5]
	v_mfma_f32_16x16x32_bf16 v[2:5], v[186:189], v[230:233], v[2:5]
	s_setprio 0
	s_barrier
	s_cmp_gt_u32 s84, 5
	s_cbranch_scc0 .LBB0_604
	s_and_b64 vcc, exec, s[52:53]
	s_cbranch_vccz .LBB0_607
	s_barrier

.LBB0_642:
	s_add_u32 s88, s60, s76
	s_addc_u32 s89, s61, s77
	s_add_u32 s22, s88, 0x100
	s_addc_u32 s23, s89, 0
	s_and_b64 s[20:21], s[68:69], exec
	s_cselect_b32 s78, s84, s22
	s_cselect_b32 s79, s51, s23
	s_add_u32 s20, s58, s76
	s_addc_u32 s21, s59, s77
	s_add_u32 s22, s20, 0x100
	s_addc_u32 s23, s21, 0
	s_add_i32 s40, 0, 0x10000
	s_and_b64 s[20:21], s[68:69], exec
	s_cselect_b32 s68, s85, s22
	s_cselect_b32 s69, s49, s23
	s_add_i32 s20, 0, 0x14000
	v_add_u32_e32 v148, s40, v133
	v_add_u32_e32 v182, s20, v133
	ds_read_b128 v[136:139], v148
	ds_read_b128 v[140:143], v148 offset:1024
	ds_read_b128 v[144:147], v148 offset:2048
	ds_read_b128 v[148:151], v148 offset:3072
	ds_read_b128 v[152:155], v182
	ds_read_b128 v[156:159], v182 offset:1024
	ds_read_b128 v[160:163], v182 offset:2048
	ds_read_b128 v[182:185], v182 offset:3072
	s_add_i32 s86, 0, 0x18000
	s_add_i32 s77, 0, 0x1c000
	s_add_i32 vcc_hi, s40, s46
	s_add_i32 vcc_lo, s20, s46
	s_add_i32 s76, s86, s46
	s_add_i32 s43, s77, s46
	s_add_i32 m0, s47, 0xc000
	s_add_i32 s21, s47, 0xe000
	s_add_i32 s42, vcc_hi, 0x2000
	s_add_i32 s87, vcc_lo, 0x2000
	s_add_i32 s41, s76, 0x2000
	s_add_i32 s40, s43, 0x2000
	v_lshl_add_u64 v[202:203], s[88:89], 0, v[130:131]
	v_lshl_add_u64 v[230:231], v[202:203], 0, s[80:81]
	ds_read_b128 v[186:189], v135
	ds_read_b128 v[190:193], v135 offset:1024
	ds_read_b128 v[194:197], v135 offset:2048
	ds_read_b128 v[198:201], v135 offset:3072
	ds_read_b128 v[214:217], v135 offset:4096
	ds_read_b128 v[218:221], v135 offset:5120
	ds_read_b128 v[222:225], v135 offset:6144
	ds_read_b128 v[226:229], v135 offset:7168
	global_load_lds_dwordx4 v[230:231], off
	v_lshl_add_u64 v[202:203], v[202:203], 0, s[30:31]
	s_mov_b32 m0, s21
	s_nop 0
	global_load_lds_dwordx4 v[202:203], off
	s_waitcnt vmcnt(8)
	s_waitcnt lgkmcnt(0)
	s_barrier
	s_setprio 1
	s_waitcnt lgkmcnt(0)
	v_mfma_f32_16x16x32_bf16 v[126:129], v[136:139], v[186:189], v[126:129]
	v_mfma_f32_16x16x32_bf16 v[126:129], v[140:143], v[190:193], v[126:129]
	v_mfma_f32_16x16x32_bf16 v[118:121], v[136:139], v[194:197], v[118:121]
	v_mfma_f32_16x16x32_bf16 v[118:121], v[140:143], v[198:201], v[118:121]
	v_mfma_f32_16x16x32_bf16 v[102:105], v[136:139], v[214:217], v[102:105]
	v_mfma_f32_16x16x32_bf16 v[102:105], v[140:143], v[218:221], v[102:105]
	v_mfma_f32_16x16x32_bf16 v[86:89], v[136:139], v[222:225], v[86:89]
	v_mfma_f32_16x16x32_bf16 v[86:89], v[140:143], v[226:229], v[86:89]
	v_mfma_f32_16x16x32_bf16 v[122:125], v[144:147], v[186:189], v[122:125]
	v_mfma_f32_16x16x32_bf16 v[122:125], v[148:151], v[190:193], v[122:125]
	v_mfma_f32_16x16x32_bf16 v[110:113], v[144:147], v[194:197], v[110:113]
	v_mfma_f32_16x16x32_bf16 v[110:113], v[148:151], v[198:201], v[110:113]
	v_mfma_f32_16x16x32_bf16 v[94:97], v[144:147], v[214:217], v[94:97]
	v_mfma_f32_16x16x32_bf16 v[94:97], v[148:151], v[218:221], v[94:97]
	v_mfma_f32_16x16x32_bf16 v[78:81], v[144:147], v[222:225], v[78:81]
	v_mfma_f32_16x16x32_bf16 v[78:81], v[148:151], v[226:229], v[78:81]
	s_setprio 0
	s_setprio 1
	v_mfma_f32_16x16x32_bf16 v[114:117], v[152:155], v[186:189], v[114:117]
	v_mfma_f32_16x16x32_bf16 v[114:117], v[156:159], v[190:193], v[114:117]
	v_mfma_f32_16x16x32_bf16 v[98:101], v[152:155], v[194:197], v[98:101]
	v_mfma_f32_16x16x32_bf16 v[98:101], v[156:159], v[198:201], v[98:101]
	v_mfma_f32_16x16x32_bf16 v[82:85], v[152:155], v[214:217], v[82:85]
	v_mfma_f32_16x16x32_bf16 v[82:85], v[156:159], v[218:221], v[82:85]
	v_mfma_f32_16x16x32_bf16 v[70:73], v[152:155], v[222:225], v[70:73]
	v_mfma_f32_16x16x32_bf16 v[70:73], v[156:159], v[226:229], v[70:73]
	v_mfma_f32_16x16x32_bf16 v[106:109], v[160:163], v[186:189], v[106:109]
	v_mfma_f32_16x16x32_bf16 v[106:109], v[182:185], v[190:193], v[106:109]
	v_mfma_f32_16x16x32_bf16 v[90:93], v[160:163], v[194:197], v[90:93]
	v_mfma_f32_16x16x32_bf16 v[90:93], v[182:185], v[198:201], v[90:93]
	v_mfma_f32_16x16x32_bf16 v[74:77], v[160:163], v[214:217], v[74:77]
	v_mfma_f32_16x16x32_bf16 v[74:77], v[182:185], v[218:221], v[74:77]
	v_mfma_f32_16x16x32_bf16 v[66:69], v[160:163], v[222:225], v[66:69]
	v_mfma_f32_16x16x32_bf16 v[66:69], v[182:185], v[226:229], v[66:69]
	s_setprio 0
	s_barrier
	s_mov_b32 m0, vcc_hi
	v_lshl_add_u64 v[202:203], s[68:69], 0, v[0:1]
	ds_read_b128 v[186:189], v135 offset:16384
	ds_read_b128 v[190:193], v135 offset:17408
	ds_read_b128 v[194:197], v135 offset:18432
	ds_read_b128 v[198:201], v135 offset:19456
	ds_read_b128 v[214:217], v135 offset:20480
	ds_read_b128 v[218:221], v135 offset:21504
	ds_read_b128 v[222:225], v135 offset:22528
	ds_read_b128 v[226:229], v135 offset:23552
	global_load_lds_dwordx4 v[202:203], off
	v_lshl_add_u64 v[230:231], v[202:203], 0, s[36:37]
	s_mov_b32 m0, s42
	s_nop 0
	global_load_lds_dwordx4 v[230:231], off
	v_lshl_add_u64 v[230:231], v[202:203], 0, s[64:65]
	s_mov_b32 m0, vcc_lo
	s_nop 0
	global_load_lds_dwordx4 v[230:231], off
	v_lshl_add_u64 v[230:231], v[202:203], 0, s[8:9]
	s_mov_b32 m0, s87
	s_nop 0
	global_load_lds_dwordx4 v[230:231], off
	v_lshl_add_u64 v[230:231], s[78:79], 0, v[130:131]
	s_mov_b32 m0, s47
	v_lshl_add_u64 v[232:233], v[230:231], 0, s[36:37]
	global_load_lds_dwordx4 v[230:231], off
	s_mov_b32 m0, s90
	s_nop 0
	global_load_lds_dwordx4 v[232:233], off
	s_waitcnt vmcnt(8)
	s_waitcnt lgkmcnt(0)
	s_barrier
	s_setprio 1
	s_waitcnt lgkmcnt(0)
	v_mfma_f32_16x16x32_bf16 v[62:65], v[136:139], v[186:189], v[62:65]
	v_mfma_f32_16x16x32_bf16 v[62:65], v[140:143], v[190:193], v[62:65]
	v_mfma_f32_16x16x32_bf16 v[54:57], v[136:139], v[194:197], v[54:57]
	v_mfma_f32_16x16x32_bf16 v[54:57], v[140:143], v[198:201], v[54:57]
	v_mfma_f32_16x16x32_bf16 v[38:41], v[136:139], v[214:217], v[38:41]
	v_mfma_f32_16x16x32_bf16 v[38:41], v[140:143], v[218:221], v[38:41]
	v_mfma_f32_16x16x32_bf16 v[22:25], v[136:139], v[222:225], v[22:25]
	v_mfma_f32_16x16x32_bf16 v[22:25], v[140:143], v[226:229], v[22:25]
	v_mfma_f32_16x16x32_bf16 v[58:61], v[144:147], v[186:189], v[58:61]
	v_mfma_f32_16x16x32_bf16 v[58:61], v[148:151], v[190:193], v[58:61]
	v_mfma_f32_16x16x32_bf16 v[46:49], v[144:147], v[194:197], v[46:49]
	v_mfma_f32_16x16x32_bf16 v[46:49], v[148:151], v[198:201], v[46:49]
	v_mfma_f32_16x16x32_bf16 v[30:33], v[144:147], v[214:217], v[30:33]
	v_mfma_f32_16x16x32_bf16 v[30:33], v[148:151], v[218:221], v[30:33]
	v_mfma_f32_16x16x32_bf16 v[14:17], v[144:147], v[222:225], v[14:17]
	v_mfma_f32_16x16x32_bf16 v[14:17], v[148:151], v[226:229], v[14:17]
	s_setprio 0
	s_setprio 1
	v_mfma_f32_16x16x32_bf16 v[50:53], v[152:155], v[186:189], v[50:53]
	v_mfma_f32_16x16x32_bf16 v[50:53], v[156:159], v[190:193], v[50:53]
	v_mfma_f32_16x16x32_bf16 v[34:37], v[152:155], v[194:197], v[34:37]
	v_mfma_f32_16x16x32_bf16 v[34:37], v[156:159], v[198:201], v[34:37]
	v_mfma_f32_16x16x32_bf16 v[18:21], v[152:155], v[214:217], v[18:21]
	v_mfma_f32_16x16x32_bf16 v[18:21], v[156:159], v[218:221], v[18:21]
	v_mfma_f32_16x16x32_bf16 v[6:9], v[152:155], v[222:225], v[6:9]
	v_mfma_f32_16x16x32_bf16 v[6:9], v[156:159], v[226:229], v[6:9]
	v_mfma_f32_16x16x32_bf16 v[42:45], v[160:163], v[186:189], v[42:45]
	v_mfma_f32_16x16x32_bf16 v[42:45], v[182:185], v[190:193], v[42:45]
	v_mfma_f32_16x16x32_bf16 v[26:29], v[160:163], v[194:197], v[26:29]
	v_mfma_f32_16x16x32_bf16 v[26:29], v[182:185], v[198:201], v[26:29]
	v_mfma_f32_16x16x32_bf16 v[10:13], v[160:163], v[214:217], v[10:13]
	v_mfma_f32_16x16x32_bf16 v[10:13], v[182:185], v[218:221], v[10:13]
	v_mfma_f32_16x16x32_bf16 v[2:5], v[160:163], v[222:225], v[2:5]
	v_mfma_f32_16x16x32_bf16 v[2:5], v[182:185], v[226:229], v[2:5]
	s_setprio 0
	s_barrier
	v_add_u32_e32 v148, s86, v133
	v_add_u32_e32 v182, s77, v133
	ds_read_b128 v[136:139], v148
	ds_read_b128 v[140:143], v148 offset:1024
	ds_read_b128 v[144:147], v148 offset:2048
	ds_read_b128 v[148:151], v148 offset:3072
	ds_read_b128 v[152:155], v182
	ds_read_b128 v[156:159], v182 offset:1024
	ds_read_b128 v[160:163], v182 offset:2048
	ds_read_b128 v[182:185], v182 offset:3072
	s_mov_b32 m0, s91
	v_lshl_add_u64 v[232:233], v[230:231], 0, s[64:65]
	ds_read_b128 v[186:189], v135 offset:32768
	ds_read_b128 v[190:193], v135 offset:33792
	ds_read_b128 v[194:197], v135 offset:34816
	ds_read_b128 v[198:201], v135 offset:35840
	ds_read_b128 v[214:217], v135 offset:36864
	ds_read_b128 v[218:221], v135 offset:37888
	ds_read_b128 v[222:225], v135 offset:38912
	ds_read_b128 v[226:229], v135 offset:39936
	global_load_lds_dwordx4 v[232:233], off
	v_lshl_add_u64 v[232:233], v[230:231], 0, s[8:9]
	s_mov_b32 m0, s96
	s_nop 0
	global_load_lds_dwordx4 v[232:233], off
	s_waitcnt vmcnt(8)
	s_waitcnt lgkmcnt(0)
	s_barrier
	s_setprio 1
	s_waitcnt lgkmcnt(0)
	v_mfma_f32_16x16x32_bf16 v[126:129], v[136:139], v[186:189], v[126:129]
	v_mfma_f32_16x16x32_bf16 v[126:129], v[140:143], v[190:193], v[126:129]
	v_mfma_f32_16x16x32_bf16 v[118:121], v[136:139], v[194:197], v[118:121]
	v_mfma_f32_16x16x32_bf16 v[118:121], v[140:143], v[198:201], v[118:121]
	v_mfma_f32_16x16x32_bf16 v[102:105], v[136:139], v[214:217], v[102:105]
	v_mfma_f32_16x16x32_bf16 v[102:105], v[140:143], v[218:221], v[102:105]
	v_mfma_f32_16x16x32_bf16 v[86:89], v[136:139], v[222:225], v[86:89]
	v_mfma_f32_16x16x32_bf16 v[86:89], v[140:143], v[226:229], v[86:89]
	v_mfma_f32_16x16x32_bf16 v[122:125], v[144:147], v[186:189], v[122:125]
	v_mfma_f32_16x16x32_bf16 v[122:125], v[148:151], v[190:193], v[122:125]
	v_mfma_f32_16x16x32_bf16 v[110:113], v[144:147], v[194:197], v[110:113]
	v_mfma_f32_16x16x32_bf16 v[110:113], v[148:151], v[198:201], v[110:113]
	v_mfma_f32_16x16x32_bf16 v[94:97], v[144:147], v[214:217], v[94:97]
	v_mfma_f32_16x16x32_bf16 v[94:97], v[148:151], v[218:221], v[94:97]
	v_mfma_f32_16x16x32_bf16 v[78:81], v[144:147], v[222:225], v[78:81]
	v_mfma_f32_16x16x32_bf16 v[78:81], v[148:151], v[226:229], v[78:81]
	s_setprio 0
	s_setprio 1
	v_mfma_f32_16x16x32_bf16 v[114:117], v[152:155], v[186:189], v[114:117]
	v_mfma_f32_16x16x32_bf16 v[114:117], v[156:159], v[190:193], v[114:117]
	v_mfma_f32_16x16x32_bf16 v[98:101], v[152:155], v[194:197], v[98:101]
	v_mfma_f32_16x16x32_bf16 v[98:101], v[156:159], v[198:201], v[98:101]
	v_mfma_f32_16x16x32_bf16 v[82:85], v[152:155], v[214:217], v[82:85]
	v_mfma_f32_16x16x32_bf16 v[82:85], v[156:159], v[218:221], v[82:85]
	v_mfma_f32_16x16x32_bf16 v[70:73], v[152:155], v[222:225], v[70:73]
	v_mfma_f32_16x16x32_bf16 v[70:73], v[156:159], v[226:229], v[70:73]
	v_mfma_f32_16x16x32_bf16 v[106:109], v[160:163], v[186:189], v[106:109]
	v_mfma_f32_16x16x32_bf16 v[106:109], v[182:185], v[190:193], v[106:109]
	v_mfma_f32_16x16x32_bf16 v[90:93], v[160:163], v[194:197], v[90:93]
	v_mfma_f32_16x16x32_bf16 v[90:93], v[182:185], v[198:201], v[90:93]
	v_mfma_f32_16x16x32_bf16 v[74:77], v[160:163], v[214:217], v[74:77]
	v_mfma_f32_16x16x32_bf16 v[74:77], v[182:185], v[218:221], v[74:77]
	v_mfma_f32_16x16x32_bf16 v[66:69], v[160:163], v[222:225], v[66:69]
	v_mfma_f32_16x16x32_bf16 v[66:69], v[182:185], v[226:229], v[66:69]
	s_setprio 0
	s_barrier
	s_mov_b32 m0, s76
	v_lshl_add_u64 v[232:233], v[202:203], 0, s[34:35]
	ds_read_b128 v[186:189], v135 offset:49152
	ds_read_b128 v[190:193], v135 offset:50176
	ds_read_b128 v[194:197], v135 offset:51200
	ds_read_b128 v[198:201], v135 offset:52224
	ds_read_b128 v[214:217], v135 offset:53248
	ds_read_b128 v[218:221], v135 offset:54272
	ds_read_b128 v[222:225], v135 offset:55296
	ds_read_b128 v[226:229], v135 offset:56320
	global_load_lds_dwordx4 v[232:233], off
	v_lshl_add_u64 v[232:233], v[202:203], 0, s[70:71]
	s_mov_b32 m0, s41
	s_nop 0
	global_load_lds_dwordx4 v[232:233], off
	v_lshl_add_u64 v[232:233], v[202:203], 0, s[80:81]
	s_mov_b32 m0, s43
	v_lshl_add_u64 v[202:203], v[202:203], 0, s[30:31]
	global_load_lds_dwordx4 v[232:233], off
	s_mov_b32 m0, s40
	s_nop 0
	global_load_lds_dwordx4 v[202:203], off
	v_lshl_add_u64 v[202:203], v[230:231], 0, s[34:35]
	s_mov_b32 m0, s97
	s_nop 0
	global_load_lds_dwordx4 v[202:203], off
	v_lshl_add_u64 v[202:203], v[230:231], 0, s[70:71]
	s_mov_b32 m0, s0
	s_nop 0
	global_load_lds_dwordx4 v[202:203], off
	s_waitcnt vmcnt(8)
	s_waitcnt lgkmcnt(0)
	s_barrier
	s_setprio 1
	s_waitcnt lgkmcnt(0)
	v_mfma_f32_16x16x32_bf16 v[62:65], v[136:139], v[186:189], v[62:65]
	v_mfma_f32_16x16x32_bf16 v[62:65], v[140:143], v[190:193], v[62:65]
	v_mfma_f32_16x16x32_bf16 v[54:57], v[136:139], v[194:197], v[54:57]
	v_mfma_f32_16x16x32_bf16 v[54:57], v[140:143], v[198:201], v[54:57]
	v_mfma_f32_16x16x32_bf16 v[38:41], v[136:139], v[214:217], v[38:41]
	v_mfma_f32_16x16x32_bf16 v[38:41], v[140:143], v[218:221], v[38:41]
	v_mfma_f32_16x16x32_bf16 v[22:25], v[136:139], v[222:225], v[22:25]
	v_mfma_f32_16x16x32_bf16 v[22:25], v[140:143], v[226:229], v[22:25]
	v_mfma_f32_16x16x32_bf16 v[58:61], v[144:147], v[186:189], v[58:61]
	v_mfma_f32_16x16x32_bf16 v[58:61], v[148:151], v[190:193], v[58:61]
	v_mfma_f32_16x16x32_bf16 v[46:49], v[144:147], v[194:197], v[46:49]
	v_mfma_f32_16x16x32_bf16 v[46:49], v[148:151], v[198:201], v[46:49]
	v_mfma_f32_16x16x32_bf16 v[30:33], v[144:147], v[214:217], v[30:33]
	v_mfma_f32_16x16x32_bf16 v[30:33], v[148:151], v[218:221], v[30:33]
	v_mfma_f32_16x16x32_bf16 v[14:17], v[144:147], v[222:225], v[14:17]
	v_mfma_f32_16x16x32_bf16 v[14:17], v[148:151], v[226:229], v[14:17]
	s_setprio 0
	s_setprio 1
	v_mfma_f32_16x16x32_bf16 v[50:53], v[152:155], v[186:189], v[50:53]
	v_mfma_f32_16x16x32_bf16 v[50:53], v[156:159], v[190:193], v[50:53]
	v_mfma_f32_16x16x32_bf16 v[34:37], v[152:155], v[194:197], v[34:37]
	v_mfma_f32_16x16x32_bf16 v[34:37], v[156:159], v[198:201], v[34:37]
	v_mfma_f32_16x16x32_bf16 v[18:21], v[152:155], v[214:217], v[18:21]
	v_mfma_f32_16x16x32_bf16 v[18:21], v[156:159], v[218:221], v[18:21]
	v_mfma_f32_16x16x32_bf16 v[6:9], v[152:155], v[222:225], v[6:9]
	v_mfma_f32_16x16x32_bf16 v[6:9], v[156:159], v[226:229], v[6:9]
	v_mfma_f32_16x16x32_bf16 v[42:45], v[160:163], v[186:189], v[42:45]
	v_mfma_f32_16x16x32_bf16 v[42:45], v[182:185], v[190:193], v[42:45]
	v_mfma_f32_16x16x32_bf16 v[26:29], v[160:163], v[194:197], v[26:29]
	v_mfma_f32_16x16x32_bf16 v[26:29], v[182:185], v[198:201], v[26:29]
	v_mfma_f32_16x16x32_bf16 v[10:13], v[160:163], v[214:217], v[10:13]
	v_mfma_f32_16x16x32_bf16 v[10:13], v[182:185], v[218:221], v[10:13]
	v_mfma_f32_16x16x32_bf16 v[2:5], v[160:163], v[222:225], v[2:5]
	v_mfma_f32_16x16x32_bf16 v[2:5], v[182:185], v[226:229], v[2:5]
	s_setprio 0
	s_barrier
	s_andn2_b64 vcc, exec, s[62:63]
	s_mov_b64 s[68:69], -1
	s_mov_b64 s[62:63], 0
	s_mov_b64 s[76:77], 0x100
	s_cbranch_vccz .LBB0_642
	v_readlane_b32 s12, v244, 8
	v_readlane_b32 s13, v244, 9
	s_and_b64 vcc, exec, s[12:13]
	v_readlane_b32 s85, v244, 4
	s_cbranch_vccz .LBB0_645
	s_barrier

.Lmid1_778:
	s_add_i32 s22, 0, 0x10000
	s_add_i32 s23, 0, 0x14000
	s_add_u32 s20, s76, 0xfffc0080
	s_addc_u32 s21, s77, -1
	s_cmp_eq_u32 vcc_hi, 12
	s_cselect_b32 s79, s61, s21
	s_cselect_b32 s78, s85, s20
	s_cselect_b32 s21, s59, vcc_lo
	s_cselect_b32 s20, s86, s87
	s_add_i32 m0, s43, 0xc000
	v_lshl_add_u64 v[202:203], s[76:77], 0, v[182:183]
	global_load_lds_dwordx4 v[202:203], off
	v_lshl_add_u64 v[202:203], v[202:203], 0, s[72:73]
	s_add_i32 m0, s43, 0xe000
	s_nop 0
	global_load_lds_dwordx4 v[202:203], off
	s_waitcnt vmcnt(8)
	s_waitcnt lgkmcnt(0)
	s_barrier
	s_setprio 1
	s_waitcnt lgkmcnt(0)
	v_mfma_f32_16x16x32_bf16 v[126:129], v[130:133], v[184:187], 0
	v_mfma_f32_16x16x32_bf16 v[126:129], v[134:137], v[188:191], v[126:129]
	v_mfma_f32_16x16x32_bf16 v[110:113], v[130:133], v[198:201], 0
	v_mfma_f32_16x16x32_bf16 v[110:113], v[134:137], v[214:217], v[110:113]
	v_mfma_f32_16x16x32_bf16 v[94:97], v[130:133], v[218:221], 0
	v_mfma_f32_16x16x32_bf16 v[94:97], v[134:137], v[222:225], v[94:97]
	v_mfma_f32_16x16x32_bf16 v[78:81], v[130:133], v[226:229], 0
	v_mfma_f32_16x16x32_bf16 v[78:81], v[134:137], v[230:233], v[78:81]
	v_mfma_f32_16x16x32_bf16 v[122:125], v[138:141], v[184:187], 0
	v_mfma_f32_16x16x32_bf16 v[122:125], v[142:145], v[188:191], v[122:125]
	v_mfma_f32_16x16x32_bf16 v[106:109], v[138:141], v[198:201], 0
	v_mfma_f32_16x16x32_bf16 v[106:109], v[142:145], v[214:217], v[106:109]
	v_mfma_f32_16x16x32_bf16 v[90:93], v[138:141], v[218:221], 0
	v_mfma_f32_16x16x32_bf16 v[90:93], v[142:145], v[222:225], v[90:93]
	v_mfma_f32_16x16x32_bf16 v[74:77], v[138:141], v[226:229], 0
	v_mfma_f32_16x16x32_bf16 v[74:77], v[142:145], v[230:233], v[74:77]
	s_setprio 0
	s_setprio 1
	v_mfma_f32_16x16x32_bf16 v[118:121], v[146:149], v[184:187], 0
	v_mfma_f32_16x16x32_bf16 v[118:121], v[150:153], v[188:191], v[118:121]
	v_mfma_f32_16x16x32_bf16 v[102:105], v[146:149], v[198:201], 0
	v_mfma_f32_16x16x32_bf16 v[102:105], v[150:153], v[214:217], v[102:105]
	v_mfma_f32_16x16x32_bf16 v[86:89], v[146:149], v[218:221], 0
	v_mfma_f32_16x16x32_bf16 v[86:89], v[150:153], v[222:225], v[86:89]
	v_mfma_f32_16x16x32_bf16 v[70:73], v[146:149], v[226:229], 0
	v_mfma_f32_16x16x32_bf16 v[70:73], v[150:153], v[230:233], v[70:73]
	v_mfma_f32_16x16x32_bf16 v[114:117], v[154:157], v[184:187], 0
	v_mfma_f32_16x16x32_bf16 v[114:117], v[158:161], v[188:191], v[114:117]
	v_mfma_f32_16x16x32_bf16 v[98:101], v[154:157], v[198:201], 0
	v_mfma_f32_16x16x32_bf16 v[98:101], v[158:161], v[214:217], v[98:101]
	v_mfma_f32_16x16x32_bf16 v[82:85], v[154:157], v[218:221], 0
	v_mfma_f32_16x16x32_bf16 v[82:85], v[158:161], v[222:225], v[82:85]
	v_mfma_f32_16x16x32_bf16 v[66:69], v[154:157], v[226:229], 0
	v_mfma_f32_16x16x32_bf16 v[66:69], v[158:161], v[230:233], v[66:69]
	s_setprio 0
	s_barrier
	ds_read_b128 v[184:187], v196 offset:16384
	ds_read_b128 v[188:191], v196 offset:17408
	ds_read_b128 v[198:201], v196 offset:18432
	ds_read_b128 v[214:217], v196 offset:19456
	ds_read_b128 v[218:221], v196 offset:20480
	ds_read_b128 v[222:225], v196 offset:21504
	ds_read_b128 v[226:229], v196 offset:22528
	ds_read_b128 v[230:233], v196 offset:23552
	v_lshl_add_u64 v[202:203], s[20:21], 0, v[0:1]
	s_add_i32 s20, s22, s14
	s_mov_b32 m0, s20
	s_nop 0
	s_nop 0
	global_load_lds_dwordx4 v[202:203], off
	v_lshl_add_u64 v[234:235], v[202:203], 0, s[72:73]
	s_add_i32 m0, s20, 0x2000
	s_add_i32 s20, s23, s14
	global_load_lds_dwordx4 v[234:235], off
	v_lshl_add_u64 v[234:235], v[202:203], 0, s[28:29]
	s_mov_b32 m0, s20
	s_nop 0
	global_load_lds_dwordx4 v[234:235], off
	v_lshl_add_u64 v[234:235], v[202:203], 0, s[82:83]
	s_add_i32 m0, s20, 0x2000
	s_nop 0
	global_load_lds_dwordx4 v[234:235], off
	v_lshl_add_u64 v[234:235], s[78:79], 0, v[162:163]
	s_mov_b32 m0, s43
	v_lshl_add_u64 v[236:237], v[234:235], 0, s[72:73]
	global_load_lds_dwordx4 v[234:235], off
	s_mov_b32 m0, s46
	s_nop 0
	global_load_lds_dwordx4 v[236:237], off
	s_waitcnt vmcnt(8)
	s_waitcnt lgkmcnt(0)
	s_barrier
	s_setprio 1
	s_waitcnt lgkmcnt(0)
	v_mfma_f32_16x16x32_bf16 v[62:65], v[130:133], v[184:187], 0
	v_mfma_f32_16x16x32_bf16 v[62:65], v[134:137], v[188:191], v[62:65]
	v_mfma_f32_16x16x32_bf16 v[46:49], v[130:133], v[198:201], 0
	v_mfma_f32_16x16x32_bf16 v[46:49], v[134:137], v[214:217], v[46:49]
	v_mfma_f32_16x16x32_bf16 v[30:33], v[130:133], v[218:221], 0
	v_mfma_f32_16x16x32_bf16 v[30:33], v[134:137], v[222:225], v[30:33]
	v_mfma_f32_16x16x32_bf16 v[14:17], v[130:133], v[226:229], 0
	v_mfma_f32_16x16x32_bf16 v[14:17], v[134:137], v[230:233], v[14:17]
	v_mfma_f32_16x16x32_bf16 v[58:61], v[138:141], v[184:187], 0
	v_mfma_f32_16x16x32_bf16 v[58:61], v[142:145], v[188:191], v[58:61]
	v_mfma_f32_16x16x32_bf16 v[42:45], v[138:141], v[198:201], 0
	v_mfma_f32_16x16x32_bf16 v[42:45], v[142:145], v[214:217], v[42:45]
	v_mfma_f32_16x16x32_bf16 v[26:29], v[138:141], v[218:221], 0
	v_mfma_f32_16x16x32_bf16 v[26:29], v[142:145], v[222:225], v[26:29]
	v_mfma_f32_16x16x32_bf16 v[10:13], v[138:141], v[226:229], 0
	v_mfma_f32_16x16x32_bf16 v[10:13], v[142:145], v[230:233], v[10:13]
	s_setprio 0
	s_setprio 1
	v_mfma_f32_16x16x32_bf16 v[54:57], v[146:149], v[184:187], 0
	v_mfma_f32_16x16x32_bf16 v[54:57], v[150:153], v[188:191], v[54:57]
	v_mfma_f32_16x16x32_bf16 v[38:41], v[146:149], v[198:201], 0
	v_mfma_f32_16x16x32_bf16 v[38:41], v[150:153], v[214:217], v[38:41]
	v_mfma_f32_16x16x32_bf16 v[22:25], v[146:149], v[218:221], 0
	v_mfma_f32_16x16x32_bf16 v[22:25], v[150:153], v[222:225], v[22:25]
	v_mfma_f32_16x16x32_bf16 v[6:9], v[146:149], v[226:229], 0
	v_mfma_f32_16x16x32_bf16 v[6:9], v[150:153], v[230:233], v[6:9]
	v_mfma_f32_16x16x32_bf16 v[50:53], v[154:157], v[184:187], 0
	v_mfma_f32_16x16x32_bf16 v[50:53], v[158:161], v[188:191], v[50:53]
	v_mfma_f32_16x16x32_bf16 v[34:37], v[154:157], v[198:201], 0
	v_mfma_f32_16x16x32_bf16 v[34:37], v[158:161], v[214:217], v[34:37]
	v_mfma_f32_16x16x32_bf16 v[18:21], v[154:157], v[218:221], 0
	v_mfma_f32_16x16x32_bf16 v[18:21], v[158:161], v[222:225], v[18:21]
	v_mfma_f32_16x16x32_bf16 v[2:5], v[154:157], v[226:229], 0
	v_mfma_f32_16x16x32_bf16 v[2:5], v[158:161], v[230:233], v[2:5]
	s_setprio 0
	s_barrier
	s_add_i32 s20, 0, 0x18000
	s_add_i32 s21, 0, 0x1c000
	v_add_u32_e32 v142, s20, v193
	v_add_u32_e32 v158, s21, v193
	ds_read_b128 v[130:133], v142
	ds_read_b128 v[134:137], v142 offset:1024
	ds_read_b128 v[138:141], v142 offset:2048
	ds_read_b128 v[142:145], v142 offset:3072
	ds_read_b128 v[146:149], v158
	ds_read_b128 v[150:153], v158 offset:1024
	ds_read_b128 v[154:157], v158 offset:2048
	ds_read_b128 v[158:161], v158 offset:3072
	ds_read_b128 v[184:187], v196 offset:32768
	ds_read_b128 v[188:191], v196 offset:33792
	ds_read_b128 v[198:201], v196 offset:34816
	ds_read_b128 v[214:217], v196 offset:35840
	ds_read_b128 v[218:221], v196 offset:36864
	ds_read_b128 v[222:225], v196 offset:37888
	ds_read_b128 v[226:229], v196 offset:38912
	ds_read_b128 v[230:233], v196 offset:39936
	s_mov_b32 m0, s47
	v_lshl_add_u64 v[236:237], v[234:235], 0, s[28:29]
	global_load_lds_dwordx4 v[236:237], off
	v_lshl_add_u64 v[236:237], v[234:235], 0, s[82:83]
	s_mov_b32 m0, s88
	s_nop 0
	global_load_lds_dwordx4 v[236:237], off
	s_waitcnt vmcnt(8)
	s_waitcnt lgkmcnt(0)
	s_barrier
	s_setprio 1
	s_waitcnt lgkmcnt(0)
	v_mfma_f32_16x16x32_bf16 v[126:129], v[130:133], v[184:187], v[126:129]
	v_mfma_f32_16x16x32_bf16 v[126:129], v[134:137], v[188:191], v[126:129]
	v_mfma_f32_16x16x32_bf16 v[110:113], v[130:133], v[198:201], v[110:113]
	v_mfma_f32_16x16x32_bf16 v[110:113], v[134:137], v[214:217], v[110:113]
	v_mfma_f32_16x16x32_bf16 v[94:97], v[130:133], v[218:221], v[94:97]
	v_mfma_f32_16x16x32_bf16 v[94:97], v[134:137], v[222:225], v[94:97]
	v_mfma_f32_16x16x32_bf16 v[78:81], v[130:133], v[226:229], v[78:81]
	v_mfma_f32_16x16x32_bf16 v[78:81], v[134:137], v[230:233], v[78:81]
	v_mfma_f32_16x16x32_bf16 v[122:125], v[138:141], v[184:187], v[122:125]
	v_mfma_f32_16x16x32_bf16 v[122:125], v[142:145], v[188:191], v[122:125]
	v_mfma_f32_16x16x32_bf16 v[106:109], v[138:141], v[198:201], v[106:109]
	v_mfma_f32_16x16x32_bf16 v[106:109], v[142:145], v[214:217], v[106:109]
	v_mfma_f32_16x16x32_bf16 v[90:93], v[138:141], v[218:221], v[90:93]
	v_mfma_f32_16x16x32_bf16 v[90:93], v[142:145], v[222:225], v[90:93]
	v_mfma_f32_16x16x32_bf16 v[74:77], v[138:141], v[226:229], v[74:77]
	v_mfma_f32_16x16x32_bf16 v[74:77], v[142:145], v[230:233], v[74:77]
	s_setprio 0
	s_setprio 1
	v_mfma_f32_16x16x32_bf16 v[118:121], v[146:149], v[184:187], v[118:121]
	v_mfma_f32_16x16x32_bf16 v[118:121], v[150:153], v[188:191], v[118:121]
	v_mfma_f32_16x16x32_bf16 v[102:105], v[146:149], v[198:201], v[102:105]
	v_mfma_f32_16x16x32_bf16 v[102:105], v[150:153], v[214:217], v[102:105]
	v_mfma_f32_16x16x32_bf16 v[86:89], v[146:149], v[218:221], v[86:89]
	v_mfma_f32_16x16x32_bf16 v[86:89], v[150:153], v[222:225], v[86:89]
	v_mfma_f32_16x16x32_bf16 v[70:73], v[146:149], v[226:229], v[70:73]
	v_mfma_f32_16x16x32_bf16 v[70:73], v[150:153], v[230:233], v[70:73]
	v_mfma_f32_16x16x32_bf16 v[114:117], v[154:157], v[184:187], v[114:117]
	v_mfma_f32_16x16x32_bf16 v[114:117], v[158:161], v[188:191], v[114:117]
	v_mfma_f32_16x16x32_bf16 v[98:101], v[154:157], v[198:201], v[98:101]
	v_mfma_f32_16x16x32_bf16 v[98:101], v[158:161], v[214:217], v[98:101]
	v_mfma_f32_16x16x32_bf16 v[82:85], v[154:157], v[218:221], v[82:85]
	v_mfma_f32_16x16x32_bf16 v[82:85], v[158:161], v[222:225], v[82:85]
	v_mfma_f32_16x16x32_bf16 v[66:69], v[154:157], v[226:229], v[66:69]
	v_mfma_f32_16x16x32_bf16 v[66:69], v[158:161], v[230:233], v[66:69]
	s_setprio 0
	s_barrier
	ds_read_b128 v[184:187], v196 offset:49152
	ds_read_b128 v[188:191], v196 offset:50176
	ds_read_b128 v[198:201], v196 offset:51200
	ds_read_b128 v[214:217], v196 offset:52224
	ds_read_b128 v[218:221], v196 offset:53248
	ds_read_b128 v[222:225], v196 offset:54272
	ds_read_b128 v[226:229], v196 offset:55296
	ds_read_b128 v[230:233], v196 offset:56320
	s_add_i32 s20, s20, s14
	s_mov_b32 m0, s20
	v_lshl_add_u64 v[236:237], v[202:203], 0, s[34:35]
	global_load_lds_dwordx4 v[236:237], off
	v_lshl_add_u64 v[236:237], v[202:203], 0, s[38:39]
	s_add_i32 m0, s20, 0x2000
	s_add_i32 s20, s21, s14
	global_load_lds_dwordx4 v[236:237], off
	v_lshl_add_u64 v[236:237], v[202:203], 0, s[44:45]
	s_mov_b32 m0, s20
	v_lshl_add_u64 v[202:203], v[202:203], 0, s[10:11]
	global_load_lds_dwordx4 v[236:237], off
	s_add_i32 m0, s20, 0x2000
	s_nop 0
	global_load_lds_dwordx4 v[202:203], off
	v_lshl_add_u64 v[202:203], v[234:235], 0, s[34:35]
	s_mov_b32 m0, s89
	s_nop 0
	global_load_lds_dwordx4 v[202:203], off
	v_lshl_add_u64 v[202:203], v[234:235], 0, s[38:39]
	s_mov_b32 m0, s90
	s_nop 0
	global_load_lds_dwordx4 v[202:203], off
	s_waitcnt vmcnt(8)
	s_waitcnt lgkmcnt(0)
	s_barrier
	s_setprio 1
	s_waitcnt lgkmcnt(0)
	v_mfma_f32_16x16x32_bf16 v[62:65], v[130:133], v[184:187], v[62:65]
	v_mfma_f32_16x16x32_bf16 v[62:65], v[134:137], v[188:191], v[62:65]
	v_mfma_f32_16x16x32_bf16 v[46:49], v[130:133], v[198:201], v[46:49]
	v_mfma_f32_16x16x32_bf16 v[46:49], v[134:137], v[214:217], v[46:49]
	v_mfma_f32_16x16x32_bf16 v[30:33], v[130:133], v[218:221], v[30:33]
	v_mfma_f32_16x16x32_bf16 v[30:33], v[134:137], v[222:225], v[30:33]
	v_mfma_f32_16x16x32_bf16 v[14:17], v[130:133], v[226:229], v[14:17]
	v_mfma_f32_16x16x32_bf16 v[14:17], v[134:137], v[230:233], v[14:17]
	v_mfma_f32_16x16x32_bf16 v[58:61], v[138:141], v[184:187], v[58:61]
	v_mfma_f32_16x16x32_bf16 v[58:61], v[142:145], v[188:191], v[58:61]
	v_mfma_f32_16x16x32_bf16 v[42:45], v[138:141], v[198:201], v[42:45]
	v_mfma_f32_16x16x32_bf16 v[42:45], v[142:145], v[214:217], v[42:45]
	v_mfma_f32_16x16x32_bf16 v[26:29], v[138:141], v[218:221], v[26:29]
	v_mfma_f32_16x16x32_bf16 v[26:29], v[142:145], v[222:225], v[26:29]
	v_mfma_f32_16x16x32_bf16 v[10:13], v[138:141], v[226:229], v[10:13]
	v_mfma_f32_16x16x32_bf16 v[10:13], v[142:145], v[230:233], v[10:13]
	s_add_i32 vcc_hi, vcc_hi, 2
	s_add_u32 s76, s76, 0x100
	s_addc_u32 s77, s77, 0
	s_add_u32 s87, s87, 0x100
	s_addc_u32 vcc_lo, vcc_lo, 0
	s_setprio 0
	s_setprio 1
	v_mfma_f32_16x16x32_bf16 v[54:57], v[146:149], v[184:187], v[54:57]
	v_mfma_f32_16x16x32_bf16 v[54:57], v[150:153], v[188:191], v[54:57]
	v_mfma_f32_16x16x32_bf16 v[38:41], v[146:149], v[198:201], v[38:41]
	v_mfma_f32_16x16x32_bf16 v[38:41], v[150:153], v[214:217], v[38:41]
	v_mfma_f32_16x16x32_bf16 v[22:25], v[146:149], v[218:221], v[22:25]
	v_mfma_f32_16x16x32_bf16 v[22:25], v[150:153], v[222:225], v[22:25]
	v_mfma_f32_16x16x32_bf16 v[6:9], v[146:149], v[226:229], v[6:9]
	v_mfma_f32_16x16x32_bf16 v[6:9], v[150:153], v[230:233], v[6:9]
	v_mfma_f32_16x16x32_bf16 v[50:53], v[154:157], v[184:187], v[50:53]
	v_mfma_f32_16x16x32_bf16 v[50:53], v[158:161], v[188:191], v[50:53]
	v_mfma_f32_16x16x32_bf16 v[34:37], v[154:157], v[198:201], v[34:37]
	v_mfma_f32_16x16x32_bf16 v[34:37], v[158:161], v[214:217], v[34:37]
	v_mfma_f32_16x16x32_bf16 v[18:21], v[154:157], v[218:221], v[18:21]
	v_mfma_f32_16x16x32_bf16 v[18:21], v[158:161], v[222:225], v[18:21]
	v_mfma_f32_16x16x32_bf16 v[2:5], v[154:157], v[226:229], v[2:5]
	v_mfma_f32_16x16x32_bf16 v[2:5], v[158:161], v[230:233], v[2:5]
	s_setprio 0
	s_barrier
	s_branch .LBB0_778
	.p2alignl 6, 3212836864
.LBB0_778:
	s_add_i32 s22, 0, 0x10000
	s_add_i32 s23, 0, 0x14000
	v_add_u32_e32 v142, s22, v193
	v_add_u32_e32 v158, s23, v193
	ds_read_b128 v[130:133], v142
	ds_read_b128 v[134:137], v142 offset:1024
	ds_read_b128 v[138:141], v142 offset:2048
	ds_read_b128 v[142:145], v142 offset:3072
	ds_read_b128 v[146:149], v158
	ds_read_b128 v[150:153], v158 offset:1024
	ds_read_b128 v[154:157], v158 offset:2048
	ds_read_b128 v[158:161], v158 offset:3072
	ds_read_b128 v[184:187], v196
	ds_read_b128 v[188:191], v196 offset:1024
	ds_read_b128 v[198:201], v196 offset:2048
	ds_read_b128 v[214:217], v196 offset:3072
	ds_read_b128 v[218:221], v196 offset:4096
	ds_read_b128 v[222:225], v196 offset:5120
	ds_read_b128 v[226:229], v196 offset:6144
	ds_read_b128 v[230:233], v196 offset:7168
	s_add_u32 s20, s76, 0xfffc0080
	s_addc_u32 s21, s77, -1
	s_cmp_eq_u32 vcc_hi, 12
	s_cselect_b32 s79, s61, s21
	s_cselect_b32 s78, s85, s20
	s_cselect_b32 s21, s59, vcc_lo
	s_cselect_b32 s20, s86, s87
	s_add_i32 m0, s43, 0xc000
	v_lshl_add_u64 v[202:203], s[76:77], 0, v[182:183]
	global_load_lds_dwordx4 v[202:203], off
	v_lshl_add_u64 v[202:203], v[202:203], 0, s[72:73]
	s_add_i32 m0, s43, 0xe000
	s_nop 0
	global_load_lds_dwordx4 v[202:203], off
	s_waitcnt vmcnt(8)
	s_waitcnt lgkmcnt(0)
	s_barrier
	s_setprio 1
	s_waitcnt lgkmcnt(0)
	v_mfma_f32_16x16x32_bf16 v[126:129], v[130:133], v[184:187], v[126:129]
	v_mfma_f32_16x16x32_bf16 v[126:129], v[134:137], v[188:191], v[126:129]
	v_mfma_f32_16x16x32_bf16 v[110:113], v[130:133], v[198:201], v[110:113]
	v_mfma_f32_16x16x32_bf16 v[110:113], v[134:137], v[214:217], v[110:113]
	v_mfma_f32_16x16x32_bf16 v[94:97], v[130:133], v[218:221], v[94:97]
	v_mfma_f32_16x16x32_bf16 v[94:97], v[134:137], v[222:225], v[94:97]
	v_mfma_f32_16x16x32_bf16 v[78:81], v[130:133], v[226:229], v[78:81]
	v_mfma_f32_16x16x32_bf16 v[78:81], v[134:137], v[230:233], v[78:81]
	v_mfma_f32_16x16x32_bf16 v[122:125], v[138:141], v[184:187], v[122:125]
	v_mfma_f32_16x16x32_bf16 v[122:125], v[142:145], v[188:191], v[122:125]
	v_mfma_f32_16x16x32_bf16 v[106:109], v[138:141], v[198:201], v[106:109]
	v_mfma_f32_16x16x32_bf16 v[106:109], v[142:145], v[214:217], v[106:109]
	v_mfma_f32_16x16x32_bf16 v[90:93], v[138:141], v[218:221], v[90:93]
	v_mfma_f32_16x16x32_bf16 v[90:93], v[142:145], v[222:225], v[90:93]
	v_mfma_f32_16x16x32_bf16 v[74:77], v[138:141], v[226:229], v[74:77]
	v_mfma_f32_16x16x32_bf16 v[74:77], v[142:145], v[230:233], v[74:77]
	s_setprio 0
	s_setprio 1
	v_mfma_f32_16x16x32_bf16 v[118:121], v[146:149], v[184:187], v[118:121]
	v_mfma_f32_16x16x32_bf16 v[118:121], v[150:153], v[188:191], v[118:121]
	v_mfma_f32_16x16x32_bf16 v[102:105], v[146:149], v[198:201], v[102:105]
	v_mfma_f32_16x16x32_bf16 v[102:105], v[150:153], v[214:217], v[102:105]
	v_mfma_f32_16x16x32_bf16 v[86:89], v[146:149], v[218:221], v[86:89]
	v_mfma_f32_16x16x32_bf16 v[86:89], v[150:153], v[222:225], v[86:89]
	v_mfma_f32_16x16x32_bf16 v[70:73], v[146:149], v[226:229], v[70:73]
	v_mfma_f32_16x16x32_bf16 v[70:73], v[150:153], v[230:233], v[70:73]
	v_mfma_f32_16x16x32_bf16 v[114:117], v[154:157], v[184:187], v[114:117]
	v_mfma_f32_16x16x32_bf16 v[114:117], v[158:161], v[188:191], v[114:117]
	v_mfma_f32_16x16x32_bf16 v[98:101], v[154:157], v[198:201], v[98:101]
	v_mfma_f32_16x16x32_bf16 v[98:101], v[158:161], v[214:217], v[98:101]
	v_mfma_f32_16x16x32_bf16 v[82:85], v[154:157], v[218:221], v[82:85]
	v_mfma_f32_16x16x32_bf16 v[82:85], v[158:161], v[222:225], v[82:85]
	v_mfma_f32_16x16x32_bf16 v[66:69], v[154:157], v[226:229], v[66:69]
	v_mfma_f32_16x16x32_bf16 v[66:69], v[158:161], v[230:233], v[66:69]
	s_setprio 0
	s_barrier
	ds_read_b128 v[184:187], v196 offset:16384
	ds_read_b128 v[188:191], v196 offset:17408
	ds_read_b128 v[198:201], v196 offset:18432
	ds_read_b128 v[214:217], v196 offset:19456
	ds_read_b128 v[218:221], v196 offset:20480
	ds_read_b128 v[222:225], v196 offset:21504
	ds_read_b128 v[226:229], v196 offset:22528
	ds_read_b128 v[230:233], v196 offset:23552
	v_lshl_add_u64 v[202:203], s[20:21], 0, v[0:1]
	s_add_i32 s20, s22, s14
	s_mov_b32 m0, s20
	s_nop 0
	s_nop 0
	global_load_lds_dwordx4 v[202:203], off
	v_lshl_add_u64 v[234:235], v[202:203], 0, s[72:73]
	s_add_i32 m0, s20, 0x2000
	s_add_i32 s20, s23, s14
	global_load_lds_dwordx4 v[234:235], off
	v_lshl_add_u64 v[234:235], v[202:203], 0, s[28:29]
	s_mov_b32 m0, s20
	s_nop 0
	global_load_lds_dwordx4 v[234:235], off
	v_lshl_add_u64 v[234:235], v[202:203], 0, s[82:83]
	s_add_i32 m0, s20, 0x2000
	s_nop 0
	global_load_lds_dwordx4 v[234:235], off
	v_lshl_add_u64 v[234:235], s[78:79], 0, v[162:163]
	s_mov_b32 m0, s43
	v_lshl_add_u64 v[236:237], v[234:235], 0, s[72:73]
	global_load_lds_dwordx4 v[234:235], off
	s_mov_b32 m0, s46
	s_nop 0
	global_load_lds_dwordx4 v[236:237], off
	s_waitcnt vmcnt(8)
	s_waitcnt lgkmcnt(0)
	s_barrier
	s_setprio 1
	s_waitcnt lgkmcnt(0)
	v_mfma_f32_16x16x32_bf16 v[62:65], v[130:133], v[184:187], v[62:65]
	v_mfma_f32_16x16x32_bf16 v[62:65], v[134:137], v[188:191], v[62:65]
	v_mfma_f32_16x16x32_bf16 v[46:49], v[130:133], v[198:201], v[46:49]
	v_mfma_f32_16x16x32_bf16 v[46:49], v[134:137], v[214:217], v[46:49]
	v_mfma_f32_16x16x32_bf16 v[30:33], v[130:133], v[218:221], v[30:33]
	v_mfma_f32_16x16x32_bf16 v[30:33], v[134:137], v[222:225], v[30:33]
	v_mfma_f32_16x16x32_bf16 v[14:17], v[130:133], v[226:229], v[14:17]
	v_mfma_f32_16x16x32_bf16 v[14:17], v[134:137], v[230:233], v[14:17]
	v_mfma_f32_16x16x32_bf16 v[58:61], v[138:141], v[184:187], v[58:61]
	v_mfma_f32_16x16x32_bf16 v[58:61], v[142:145], v[188:191], v[58:61]
	v_mfma_f32_16x16x32_bf16 v[42:45], v[138:141], v[198:201], v[42:45]
	v_mfma_f32_16x16x32_bf16 v[42:45], v[142:145], v[214:217], v[42:45]
	v_mfma_f32_16x16x32_bf16 v[26:29], v[138:141], v[218:221], v[26:29]
	v_mfma_f32_16x16x32_bf16 v[26:29], v[142:145], v[222:225], v[26:29]
	v_mfma_f32_16x16x32_bf16 v[10:13], v[138:141], v[226:229], v[10:13]
	v_mfma_f32_16x16x32_bf16 v[10:13], v[142:145], v[230:233], v[10:13]
	s_setprio 0
	s_setprio 1
	v_mfma_f32_16x16x32_bf16 v[54:57], v[146:149], v[184:187], v[54:57]
	v_mfma_f32_16x16x32_bf16 v[54:57], v[150:153], v[188:191], v[54:57]
	v_mfma_f32_16x16x32_bf16 v[38:41], v[146:149], v[198:201], v[38:41]
	v_mfma_f32_16x16x32_bf16 v[38:41], v[150:153], v[214:217], v[38:41]
	v_mfma_f32_16x16x32_bf16 v[22:25], v[146:149], v[218:221], v[22:25]
	v_mfma_f32_16x16x32_bf16 v[22:25], v[150:153], v[222:225], v[22:25]
	v_mfma_f32_16x16x32_bf16 v[6:9], v[146:149], v[226:229], v[6:9]
	v_mfma_f32_16x16x32_bf16 v[6:9], v[150:153], v[230:233], v[6:9]
	v_mfma_f32_16x16x32_bf16 v[50:53], v[154:157], v[184:187], v[50:53]
	v_mfma_f32_16x16x32_bf16 v[50:53], v[158:161], v[188:191], v[50:53]
	v_mfma_f32_16x16x32_bf16 v[34:37], v[154:157], v[198:201], v[34:37]
	v_mfma_f32_16x16x32_bf16 v[34:37], v[158:161], v[214:217], v[34:37]
	v_mfma_f32_16x16x32_bf16 v[18:21], v[154:157], v[218:221], v[18:21]
	v_mfma_f32_16x16x32_bf16 v[18:21], v[158:161], v[222:225], v[18:21]
	v_mfma_f32_16x16x32_bf16 v[2:5], v[154:157], v[226:229], v[2:5]
	v_mfma_f32_16x16x32_bf16 v[2:5], v[158:161], v[230:233], v[2:5]
	s_setprio 0
	s_barrier
	s_add_i32 s20, 0, 0x18000
	s_add_i32 s21, 0, 0x1c000
	v_add_u32_e32 v142, s20, v193
	v_add_u32_e32 v158, s21, v193
	ds_read_b128 v[130:133], v142
	ds_read_b128 v[134:137], v142 offset:1024
	ds_read_b128 v[138:141], v142 offset:2048
	ds_read_b128 v[142:145], v142 offset:3072
	ds_read_b128 v[146:149], v158
	ds_read_b128 v[150:153], v158 offset:1024
	ds_read_b128 v[154:157], v158 offset:2048
	ds_read_b128 v[158:161], v158 offset:3072
	ds_read_b128 v[184:187], v196 offset:32768
	ds_read_b128 v[188:191], v196 offset:33792
	ds_read_b128 v[198:201], v196 offset:34816
	ds_read_b128 v[214:217], v196 offset:35840
	ds_read_b128 v[218:221], v196 offset:36864
	ds_read_b128 v[222:225], v196 offset:37888
	ds_read_b128 v[226:229], v196 offset:38912
	ds_read_b128 v[230:233], v196 offset:39936
	s_mov_b32 m0, s47
	v_lshl_add_u64 v[236:237], v[234:235], 0, s[28:29]
	global_load_lds_dwordx4 v[236:237], off
	v_lshl_add_u64 v[236:237], v[234:235], 0, s[82:83]
	s_mov_b32 m0, s88
	s_nop 0
	global_load_lds_dwordx4 v[236:237], off
	s_waitcnt vmcnt(8)
	s_waitcnt lgkmcnt(0)
	s_barrier
	s_setprio 1
	s_waitcnt lgkmcnt(0)
	v_mfma_f32_16x16x32_bf16 v[126:129], v[130:133], v[184:187], v[126:129]
	v_mfma_f32_16x16x32_bf16 v[126:129], v[134:137], v[188:191], v[126:129]
	v_mfma_f32_16x16x32_bf16 v[110:113], v[130:133], v[198:201], v[110:113]
	v_mfma_f32_16x16x32_bf16 v[110:113], v[134:137], v[214:217], v[110:113]
	v_mfma_f32_16x16x32_bf16 v[94:97], v[130:133], v[218:221], v[94:97]
	v_mfma_f32_16x16x32_bf16 v[94:97], v[134:137], v[222:225], v[94:97]
	v_mfma_f32_16x16x32_bf16 v[78:81], v[130:133], v[226:229], v[78:81]
	v_mfma_f32_16x16x32_bf16 v[78:81], v[134:137], v[230:233], v[78:81]
	v_mfma_f32_16x16x32_bf16 v[122:125], v[138:141], v[184:187], v[122:125]
	v_mfma_f32_16x16x32_bf16 v[122:125], v[142:145], v[188:191], v[122:125]
	v_mfma_f32_16x16x32_bf16 v[106:109], v[138:141], v[198:201], v[106:109]
	v_mfma_f32_16x16x32_bf16 v[106:109], v[142:145], v[214:217], v[106:109]
	v_mfma_f32_16x16x32_bf16 v[90:93], v[138:141], v[218:221], v[90:93]
	v_mfma_f32_16x16x32_bf16 v[90:93], v[142:145], v[222:225], v[90:93]
	v_mfma_f32_16x16x32_bf16 v[74:77], v[138:141], v[226:229], v[74:77]
	v_mfma_f32_16x16x32_bf16 v[74:77], v[142:145], v[230:233], v[74:77]
	s_setprio 0
	s_setprio 1
	v_mfma_f32_16x16x32_bf16 v[118:121], v[146:149], v[184:187], v[118:121]
	v_mfma_f32_16x16x32_bf16 v[118:121], v[150:153], v[188:191], v[118:121]
	v_mfma_f32_16x16x32_bf16 v[102:105], v[146:149], v[198:201], v[102:105]
	v_mfma_f32_16x16x32_bf16 v[102:105], v[150:153], v[214:217], v[102:105]
	v_mfma_f32_16x16x32_bf16 v[86:89], v[146:149], v[218:221], v[86:89]
	v_mfma_f32_16x16x32_bf16 v[86:89], v[150:153], v[222:225], v[86:89]
	v_mfma_f32_16x16x32_bf16 v[70:73], v[146:149], v[226:229], v[70:73]
	v_mfma_f32_16x16x32_bf16 v[70:73], v[150:153], v[230:233], v[70:73]
	v_mfma_f32_16x16x32_bf16 v[114:117], v[154:157], v[184:187], v[114:117]
	v_mfma_f32_16x16x32_bf16 v[114:117], v[158:161], v[188:191], v[114:117]
	v_mfma_f32_16x16x32_bf16 v[98:101], v[154:157], v[198:201], v[98:101]
	v_mfma_f32_16x16x32_bf16 v[98:101], v[158:161], v[214:217], v[98:101]
	v_mfma_f32_16x16x32_bf16 v[82:85], v[154:157], v[218:221], v[82:85]
	v_mfma_f32_16x16x32_bf16 v[82:85], v[158:161], v[222:225], v[82:85]
	v_mfma_f32_16x16x32_bf16 v[66:69], v[154:157], v[226:229], v[66:69]
	v_mfma_f32_16x16x32_bf16 v[66:69], v[158:161], v[230:233], v[66:69]
	s_setprio 0
	s_barrier
	ds_read_b128 v[184:187], v196 offset:49152
	ds_read_b128 v[188:191], v196 offset:50176
	ds_read_b128 v[198:201], v196 offset:51200
	ds_read_b128 v[214:217], v196 offset:52224
	ds_read_b128 v[218:221], v196 offset:53248
	ds_read_b128 v[222:225], v196 offset:54272
	ds_read_b128 v[226:229], v196 offset:55296
	ds_read_b128 v[230:233], v196 offset:56320
	s_add_i32 s20, s20, s14
	s_mov_b32 m0, s20
	v_lshl_add_u64 v[236:237], v[202:203], 0, s[34:35]
	global_load_lds_dwordx4 v[236:237], off
	v_lshl_add_u64 v[236:237], v[202:203], 0, s[38:39]
	s_add_i32 m0, s20, 0x2000
	s_add_i32 s20, s21, s14
	global_load_lds_dwordx4 v[236:237], off
	v_lshl_add_u64 v[236:237], v[202:203], 0, s[44:45]
	s_mov_b32 m0, s20
	v_lshl_add_u64 v[202:203], v[202:203], 0, s[10:11]
	global_load_lds_dwordx4 v[236:237], off
	s_add_i32 m0, s20, 0x2000
	s_nop 0
	global_load_lds_dwordx4 v[202:203], off
	v_lshl_add_u64 v[202:203], v[234:235], 0, s[34:35]
	s_mov_b32 m0, s89
	s_nop 0
	global_load_lds_dwordx4 v[202:203], off
	v_lshl_add_u64 v[202:203], v[234:235], 0, s[38:39]
	s_mov_b32 m0, s90
	s_nop 0
	global_load_lds_dwordx4 v[202:203], off
	s_waitcnt vmcnt(8)
	s_waitcnt lgkmcnt(0)
	s_barrier
	s_setprio 1
	s_waitcnt lgkmcnt(0)
	v_mfma_f32_16x16x32_bf16 v[62:65], v[130:133], v[184:187], v[62:65]
	v_mfma_f32_16x16x32_bf16 v[62:65], v[134:137], v[188:191], v[62:65]
	v_mfma_f32_16x16x32_bf16 v[46:49], v[130:133], v[198:201], v[46:49]
	v_mfma_f32_16x16x32_bf16 v[46:49], v[134:137], v[214:217], v[46:49]
	v_mfma_f32_16x16x32_bf16 v[30:33], v[130:133], v[218:221], v[30:33]
	v_mfma_f32_16x16x32_bf16 v[30:33], v[134:137], v[222:225], v[30:33]
	v_mfma_f32_16x16x32_bf16 v[14:17], v[130:133], v[226:229], v[14:17]
	v_mfma_f32_16x16x32_bf16 v[14:17], v[134:137], v[230:233], v[14:17]
	v_mfma_f32_16x16x32_bf16 v[58:61], v[138:141], v[184:187], v[58:61]
	v_mfma_f32_16x16x32_bf16 v[58:61], v[142:145], v[188:191], v[58:61]
	v_mfma_f32_16x16x32_bf16 v[42:45], v[138:141], v[198:201], v[42:45]
	v_mfma_f32_16x16x32_bf16 v[42:45], v[142:145], v[214:217], v[42:45]
	v_mfma_f32_16x16x32_bf16 v[26:29], v[138:141], v[218:221], v[26:29]
	v_mfma_f32_16x16x32_bf16 v[26:29], v[142:145], v[222:225], v[26:29]
	v_mfma_f32_16x16x32_bf16 v[10:13], v[138:141], v[226:229], v[10:13]
	v_mfma_f32_16x16x32_bf16 v[10:13], v[142:145], v[230:233], v[10:13]
	s_add_i32 vcc_hi, vcc_hi, 2
	s_add_u32 s76, s76, 0x100
	s_addc_u32 s77, s77, 0
	s_add_u32 s87, s87, 0x100
	s_addc_u32 vcc_lo, vcc_lo, 0
	s_setprio 0
	s_setprio 1
	v_mfma_f32_16x16x32_bf16 v[54:57], v[146:149], v[184:187], v[54:57]
	v_mfma_f32_16x16x32_bf16 v[54:57], v[150:153], v[188:191], v[54:57]
	v_mfma_f32_16x16x32_bf16 v[38:41], v[146:149], v[198:201], v[38:41]
	v_mfma_f32_16x16x32_bf16 v[38:41], v[150:153], v[214:217], v[38:41]
	v_mfma_f32_16x16x32_bf16 v[22:25], v[146:149], v[218:221], v[22:25]
	v_mfma_f32_16x16x32_bf16 v[22:25], v[150:153], v[222:225], v[22:25]
	v_mfma_f32_16x16x32_bf16 v[6:9], v[146:149], v[226:229], v[6:9]
	v_mfma_f32_16x16x32_bf16 v[6:9], v[150:153], v[230:233], v[6:9]
	v_mfma_f32_16x16x32_bf16 v[50:53], v[154:157], v[184:187], v[50:53]
	v_mfma_f32_16x16x32_bf16 v[50:53], v[158:161], v[188:191], v[50:53]
	v_mfma_f32_16x16x32_bf16 v[34:37], v[154:157], v[198:201], v[34:37]
	v_mfma_f32_16x16x32_bf16 v[34:37], v[158:161], v[214:217], v[34:37]
	v_mfma_f32_16x16x32_bf16 v[18:21], v[154:157], v[218:221], v[18:21]
	v_mfma_f32_16x16x32_bf16 v[18:21], v[158:161], v[222:225], v[18:21]
	v_mfma_f32_16x16x32_bf16 v[2:5], v[154:157], v[226:229], v[2:5]
	v_mfma_f32_16x16x32_bf16 v[2:5], v[158:161], v[230:233], v[2:5]
	s_setprio 0
	s_barrier
	s_cmp_gt_u32 vcc_hi, 13
	s_cbranch_scc0 .LBB0_778
	s_and_b64 vcc, exec, s[50:51]
	s_cbranch_vccz .LBB0_781
	s_barrier

.Lmid1_850:
	s_add_i32 vcc_lo, 0, 0x10000
	s_add_i32 vcc_hi, 0, 0x14000
	s_add_u32 s20, s56, 0xfffc0080
	s_addc_u32 s21, s57, -1
	s_cmp_eq_u32 s91, 12
	s_cselect_b32 s59, s76, s21
	s_cselect_b32 s58, s77, s20
	s_cselect_b32 s21, s69, s87
	s_cselect_b32 s20, s79, s86
	s_add_i32 m0, s15, 0xc000
	v_lshl_add_u64 v[142:143], s[56:57], 0, v[136:137]
	global_load_lds_dwordx4 v[142:143], off
	v_lshl_add_u64 v[142:143], v[142:143], 0, s[72:73]
	s_add_i32 m0, s15, 0xe000
	s_nop 0
	global_load_lds_dwordx4 v[142:143], off
	s_waitcnt vmcnt(8)
	s_waitcnt lgkmcnt(0)
	s_barrier
	s_setprio 1
	s_waitcnt lgkmcnt(0)
	v_mfma_f32_16x16x32_bf16 v[126:129], v[138:141], v[198:201], 0
	v_mfma_f32_16x16x32_bf16 v[126:129], v[146:149], v[214:217], v[126:129]
	v_mfma_f32_16x16x32_bf16 v[110:113], v[138:141], v[218:221], 0
	v_mfma_f32_16x16x32_bf16 v[110:113], v[146:149], v[222:225], v[110:113]
	v_mfma_f32_16x16x32_bf16 v[94:97], v[138:141], v[226:229], 0
	v_mfma_f32_16x16x32_bf16 v[94:97], v[146:149], v[230:233], v[94:97]
	v_mfma_f32_16x16x32_bf16 v[78:81], v[138:141], v[234:237], 0
	v_mfma_f32_16x16x32_bf16 v[78:81], v[146:149], v[238:241], v[78:81]
	v_mfma_f32_16x16x32_bf16 v[122:125], v[150:153], v[198:201], 0
	v_mfma_f32_16x16x32_bf16 v[122:125], v[158:161], v[214:217], v[122:125]
	v_mfma_f32_16x16x32_bf16 v[106:109], v[150:153], v[218:221], 0
	v_mfma_f32_16x16x32_bf16 v[106:109], v[158:161], v[222:225], v[106:109]
	v_mfma_f32_16x16x32_bf16 v[90:93], v[150:153], v[226:229], 0
	v_mfma_f32_16x16x32_bf16 v[90:93], v[158:161], v[230:233], v[90:93]
	v_mfma_f32_16x16x32_bf16 v[74:77], v[150:153], v[234:237], 0
	v_mfma_f32_16x16x32_bf16 v[74:77], v[158:161], v[238:241], v[74:77]
	s_setprio 0
	s_setprio 1
	v_mfma_f32_16x16x32_bf16 v[118:121], v[182:185], v[198:201], 0
	v_mfma_f32_16x16x32_bf16 v[118:121], v[186:189], v[214:217], v[118:121]
	v_mfma_f32_16x16x32_bf16 v[102:105], v[182:185], v[218:221], 0
	v_mfma_f32_16x16x32_bf16 v[102:105], v[186:189], v[222:225], v[102:105]
	v_mfma_f32_16x16x32_bf16 v[86:89], v[182:185], v[226:229], 0
	v_mfma_f32_16x16x32_bf16 v[86:89], v[186:189], v[230:233], v[86:89]
	v_mfma_f32_16x16x32_bf16 v[70:73], v[182:185], v[234:237], 0
	v_mfma_f32_16x16x32_bf16 v[70:73], v[186:189], v[238:241], v[70:73]
	v_mfma_f32_16x16x32_bf16 v[114:117], v[190:193], v[198:201], 0
	v_mfma_f32_16x16x32_bf16 v[114:117], v[194:197], v[214:217], v[114:117]
	v_mfma_f32_16x16x32_bf16 v[98:101], v[190:193], v[218:221], 0
	v_mfma_f32_16x16x32_bf16 v[98:101], v[194:197], v[222:225], v[98:101]
	v_mfma_f32_16x16x32_bf16 v[82:85], v[190:193], v[226:229], 0
	v_mfma_f32_16x16x32_bf16 v[82:85], v[194:197], v[230:233], v[82:85]
	v_mfma_f32_16x16x32_bf16 v[66:69], v[190:193], v[234:237], 0
	v_mfma_f32_16x16x32_bf16 v[66:69], v[194:197], v[238:241], v[66:69]
	s_setprio 0
	s_barrier
	ds_read_b128 v[198:201], v157 offset:16384
	ds_read_b128 v[214:217], v157 offset:17408
	ds_read_b128 v[218:221], v157 offset:18432
	ds_read_b128 v[222:225], v157 offset:19456
	ds_read_b128 v[226:229], v157 offset:20480
	ds_read_b128 v[230:233], v157 offset:21504
	ds_read_b128 v[234:237], v157 offset:22528
	ds_read_b128 v[238:241], v157 offset:23552
	v_lshl_add_u64 v[142:143], s[20:21], 0, v[130:131]
	s_add_i32 s20, vcc_lo, s14
	s_mov_b32 m0, s20
	s_nop 0
	s_nop 0
	global_load_lds_dwordx4 v[142:143], off
	v_lshl_add_u64 v[162:163], v[142:143], 0, s[72:73]
	s_add_i32 m0, s20, 0x2000
	s_add_i32 s20, vcc_hi, s14
	global_load_lds_dwordx4 v[162:163], off
	v_lshl_add_u64 v[162:163], v[142:143], 0, s[28:29]
	s_mov_b32 m0, s20
	s_nop 0
	global_load_lds_dwordx4 v[162:163], off
	v_lshl_add_u64 v[162:163], v[142:143], 0, s[82:83]
	s_add_i32 m0, s20, 0x2000
	s_nop 0
	global_load_lds_dwordx4 v[162:163], off
	v_lshl_add_u64 v[162:163], s[58:59], 0, v[132:133]
	s_mov_b32 m0, s15
	v_lshl_add_u64 v[202:203], v[162:163], 0, s[72:73]
	global_load_lds_dwordx4 v[162:163], off
	s_mov_b32 m0, s42
	s_nop 0
	global_load_lds_dwordx4 v[202:203], off
	s_waitcnt vmcnt(8)
	s_waitcnt lgkmcnt(0)
	s_barrier
	s_setprio 1
	s_waitcnt lgkmcnt(0)
	v_mfma_f32_16x16x32_bf16 v[62:65], v[138:141], v[198:201], 0
	v_mfma_f32_16x16x32_bf16 v[62:65], v[146:149], v[214:217], v[62:65]
	v_mfma_f32_16x16x32_bf16 v[46:49], v[138:141], v[218:221], 0
	v_mfma_f32_16x16x32_bf16 v[46:49], v[146:149], v[222:225], v[46:49]
	v_mfma_f32_16x16x32_bf16 v[30:33], v[138:141], v[226:229], 0
	v_mfma_f32_16x16x32_bf16 v[30:33], v[146:149], v[230:233], v[30:33]
	v_mfma_f32_16x16x32_bf16 v[14:17], v[138:141], v[234:237], 0
	v_mfma_f32_16x16x32_bf16 v[14:17], v[146:149], v[238:241], v[14:17]
	v_mfma_f32_16x16x32_bf16 v[58:61], v[150:153], v[198:201], 0
	v_mfma_f32_16x16x32_bf16 v[58:61], v[158:161], v[214:217], v[58:61]
	v_mfma_f32_16x16x32_bf16 v[42:45], v[150:153], v[218:221], 0
	v_mfma_f32_16x16x32_bf16 v[42:45], v[158:161], v[222:225], v[42:45]
	v_mfma_f32_16x16x32_bf16 v[26:29], v[150:153], v[226:229], 0
	v_mfma_f32_16x16x32_bf16 v[26:29], v[158:161], v[230:233], v[26:29]
	v_mfma_f32_16x16x32_bf16 v[10:13], v[150:153], v[234:237], 0
	v_mfma_f32_16x16x32_bf16 v[10:13], v[158:161], v[238:241], v[10:13]
	s_setprio 0
	s_setprio 1
	v_mfma_f32_16x16x32_bf16 v[54:57], v[182:185], v[198:201], 0
	v_mfma_f32_16x16x32_bf16 v[54:57], v[186:189], v[214:217], v[54:57]
	v_mfma_f32_16x16x32_bf16 v[38:41], v[182:185], v[218:221], 0
	v_mfma_f32_16x16x32_bf16 v[38:41], v[186:189], v[222:225], v[38:41]
	v_mfma_f32_16x16x32_bf16 v[22:25], v[182:185], v[226:229], 0
	v_mfma_f32_16x16x32_bf16 v[22:25], v[186:189], v[230:233], v[22:25]
	v_mfma_f32_16x16x32_bf16 v[6:9], v[182:185], v[234:237], 0
	v_mfma_f32_16x16x32_bf16 v[6:9], v[186:189], v[238:241], v[6:9]
	v_mfma_f32_16x16x32_bf16 v[50:53], v[190:193], v[198:201], 0
	v_mfma_f32_16x16x32_bf16 v[50:53], v[194:197], v[214:217], v[50:53]
	v_mfma_f32_16x16x32_bf16 v[34:37], v[190:193], v[218:221], 0
	v_mfma_f32_16x16x32_bf16 v[34:37], v[194:197], v[222:225], v[34:37]
	v_mfma_f32_16x16x32_bf16 v[18:21], v[190:193], v[226:229], 0
	v_mfma_f32_16x16x32_bf16 v[18:21], v[194:197], v[230:233], v[18:21]
	v_mfma_f32_16x16x32_bf16 v[2:5], v[190:193], v[234:237], 0
	v_mfma_f32_16x16x32_bf16 v[2:5], v[194:197], v[238:241], v[2:5]
	s_setprio 0
	s_barrier
	s_add_i32 s20, 0, 0x18000
	v_add_u32_e32 v0, s20, v145
	s_add_i32 s21, 0, 0x1c000
	ds_read_b128 v[138:141], v0
	ds_read_b128 v[146:149], v0 offset:1024
	ds_read_b128 v[150:153], v0 offset:2048
	ds_read_b128 v[158:161], v0 offset:3072
	v_add_u32_e32 v0, s21, v145
	ds_read_b128 v[182:185], v0
	ds_read_b128 v[186:189], v0 offset:1024
	ds_read_b128 v[190:193], v0 offset:2048
	ds_read_b128 v[194:197], v0 offset:3072
	ds_read_b128 v[198:201], v157 offset:32768
	ds_read_b128 v[214:217], v157 offset:33792
	ds_read_b128 v[218:221], v157 offset:34816
	ds_read_b128 v[222:225], v157 offset:35840
	ds_read_b128 v[226:229], v157 offset:36864
	ds_read_b128 v[230:233], v157 offset:37888
	ds_read_b128 v[234:237], v157 offset:38912
	ds_read_b128 v[238:241], v157 offset:39936
	s_mov_b32 m0, s43
	v_lshl_add_u64 v[202:203], v[162:163], 0, s[28:29]
	global_load_lds_dwordx4 v[202:203], off
	v_lshl_add_u64 v[202:203], v[162:163], 0, s[82:83]
	s_mov_b32 m0, s46
	s_nop 0
	global_load_lds_dwordx4 v[202:203], off
	s_waitcnt vmcnt(8)
	s_waitcnt lgkmcnt(0)
	s_barrier
	s_setprio 1
	s_waitcnt lgkmcnt(0)
	v_mfma_f32_16x16x32_bf16 v[126:129], v[138:141], v[198:201], v[126:129]
	v_mfma_f32_16x16x32_bf16 v[126:129], v[146:149], v[214:217], v[126:129]
	v_mfma_f32_16x16x32_bf16 v[110:113], v[138:141], v[218:221], v[110:113]
	v_mfma_f32_16x16x32_bf16 v[110:113], v[146:149], v[222:225], v[110:113]
	v_mfma_f32_16x16x32_bf16 v[94:97], v[138:141], v[226:229], v[94:97]
	v_mfma_f32_16x16x32_bf16 v[94:97], v[146:149], v[230:233], v[94:97]
	v_mfma_f32_16x16x32_bf16 v[78:81], v[138:141], v[234:237], v[78:81]
	v_mfma_f32_16x16x32_bf16 v[78:81], v[146:149], v[238:241], v[78:81]
	v_mfma_f32_16x16x32_bf16 v[122:125], v[150:153], v[198:201], v[122:125]
	v_mfma_f32_16x16x32_bf16 v[122:125], v[158:161], v[214:217], v[122:125]
	v_mfma_f32_16x16x32_bf16 v[106:109], v[150:153], v[218:221], v[106:109]
	v_mfma_f32_16x16x32_bf16 v[106:109], v[158:161], v[222:225], v[106:109]
	v_mfma_f32_16x16x32_bf16 v[90:93], v[150:153], v[226:229], v[90:93]
	v_mfma_f32_16x16x32_bf16 v[90:93], v[158:161], v[230:233], v[90:93]
	v_mfma_f32_16x16x32_bf16 v[74:77], v[150:153], v[234:237], v[74:77]
	v_mfma_f32_16x16x32_bf16 v[74:77], v[158:161], v[238:241], v[74:77]
	s_setprio 0
	s_setprio 1
	v_mfma_f32_16x16x32_bf16 v[118:121], v[182:185], v[198:201], v[118:121]
	v_mfma_f32_16x16x32_bf16 v[118:121], v[186:189], v[214:217], v[118:121]
	v_mfma_f32_16x16x32_bf16 v[102:105], v[182:185], v[218:221], v[102:105]
	v_mfma_f32_16x16x32_bf16 v[102:105], v[186:189], v[222:225], v[102:105]
	v_mfma_f32_16x16x32_bf16 v[86:89], v[182:185], v[226:229], v[86:89]
	v_mfma_f32_16x16x32_bf16 v[86:89], v[186:189], v[230:233], v[86:89]
	v_mfma_f32_16x16x32_bf16 v[70:73], v[182:185], v[234:237], v[70:73]
	v_mfma_f32_16x16x32_bf16 v[70:73], v[186:189], v[238:241], v[70:73]
	v_mfma_f32_16x16x32_bf16 v[114:117], v[190:193], v[198:201], v[114:117]
	v_mfma_f32_16x16x32_bf16 v[114:117], v[194:197], v[214:217], v[114:117]
	v_mfma_f32_16x16x32_bf16 v[98:101], v[190:193], v[218:221], v[98:101]
	v_mfma_f32_16x16x32_bf16 v[98:101], v[194:197], v[222:225], v[98:101]
	v_mfma_f32_16x16x32_bf16 v[82:85], v[190:193], v[226:229], v[82:85]
	v_mfma_f32_16x16x32_bf16 v[82:85], v[194:197], v[230:233], v[82:85]
	v_mfma_f32_16x16x32_bf16 v[66:69], v[190:193], v[234:237], v[66:69]
	v_mfma_f32_16x16x32_bf16 v[66:69], v[194:197], v[238:241], v[66:69]
	s_setprio 0
	s_barrier
	ds_read_b128 v[198:201], v157 offset:49152
	ds_read_b128 v[214:217], v157 offset:50176
	ds_read_b128 v[218:221], v157 offset:51200
	ds_read_b128 v[222:225], v157 offset:52224
	ds_read_b128 v[226:229], v157 offset:53248
	ds_read_b128 v[230:233], v157 offset:54272
	ds_read_b128 v[234:237], v157 offset:55296
	ds_read_b128 v[238:241], v157 offset:56320
	s_add_i32 s20, s20, s14
	s_mov_b32 m0, s20
	v_lshl_add_u64 v[202:203], v[142:143], 0, s[34:35]
	global_load_lds_dwordx4 v[202:203], off
	v_lshl_add_u64 v[202:203], v[142:143], 0, s[38:39]
	s_add_i32 m0, s20, 0x2000
	s_add_i32 s20, s21, s14
	global_load_lds_dwordx4 v[202:203], off
	v_lshl_add_u64 v[202:203], v[142:143], 0, s[44:45]
	s_mov_b32 m0, s20
	v_lshl_add_u64 v[142:143], v[142:143], 0, s[10:11]
	global_load_lds_dwordx4 v[202:203], off
	s_add_i32 m0, s20, 0x2000
	s_nop 0
	global_load_lds_dwordx4 v[142:143], off
	v_lshl_add_u64 v[142:143], v[162:163], 0, s[34:35]
	s_mov_b32 m0, s47
	s_nop 0
	global_load_lds_dwordx4 v[142:143], off
	v_lshl_add_u64 v[142:143], v[162:163], 0, s[38:39]
	s_mov_b32 m0, s96
	s_nop 0
	global_load_lds_dwordx4 v[142:143], off
	s_waitcnt vmcnt(8)
	s_waitcnt lgkmcnt(0)
	s_barrier
	s_setprio 1
	s_waitcnt lgkmcnt(0)
	v_mfma_f32_16x16x32_bf16 v[62:65], v[138:141], v[198:201], v[62:65]
	v_mfma_f32_16x16x32_bf16 v[62:65], v[146:149], v[214:217], v[62:65]
	v_mfma_f32_16x16x32_bf16 v[46:49], v[138:141], v[218:221], v[46:49]
	v_mfma_f32_16x16x32_bf16 v[46:49], v[146:149], v[222:225], v[46:49]
	v_mfma_f32_16x16x32_bf16 v[30:33], v[138:141], v[226:229], v[30:33]
	v_mfma_f32_16x16x32_bf16 v[30:33], v[146:149], v[230:233], v[30:33]
	v_mfma_f32_16x16x32_bf16 v[14:17], v[138:141], v[234:237], v[14:17]
	v_mfma_f32_16x16x32_bf16 v[14:17], v[146:149], v[238:241], v[14:17]
	v_mfma_f32_16x16x32_bf16 v[58:61], v[150:153], v[198:201], v[58:61]
	v_mfma_f32_16x16x32_bf16 v[58:61], v[158:161], v[214:217], v[58:61]
	v_mfma_f32_16x16x32_bf16 v[42:45], v[150:153], v[218:221], v[42:45]
	v_mfma_f32_16x16x32_bf16 v[42:45], v[158:161], v[222:225], v[42:45]
	v_mfma_f32_16x16x32_bf16 v[26:29], v[150:153], v[226:229], v[26:29]
	v_mfma_f32_16x16x32_bf16 v[26:29], v[158:161], v[230:233], v[26:29]
	v_mfma_f32_16x16x32_bf16 v[10:13], v[150:153], v[234:237], v[10:13]
	v_mfma_f32_16x16x32_bf16 v[10:13], v[158:161], v[238:241], v[10:13]
	s_add_i32 s91, s91, 2
	s_add_u32 s56, s56, 0x100
	s_addc_u32 s57, s57, 0
	s_add_u32 s86, s86, 0x100
	s_addc_u32 s87, s87, 0
	s_setprio 0
	s_setprio 1
	v_mfma_f32_16x16x32_bf16 v[54:57], v[182:185], v[198:201], v[54:57]
	v_mfma_f32_16x16x32_bf16 v[54:57], v[186:189], v[214:217], v[54:57]
	v_mfma_f32_16x16x32_bf16 v[38:41], v[182:185], v[218:221], v[38:41]
	v_mfma_f32_16x16x32_bf16 v[38:41], v[186:189], v[222:225], v[38:41]
	v_mfma_f32_16x16x32_bf16 v[22:25], v[182:185], v[226:229], v[22:25]
	v_mfma_f32_16x16x32_bf16 v[22:25], v[186:189], v[230:233], v[22:25]
	v_mfma_f32_16x16x32_bf16 v[6:9], v[182:185], v[234:237], v[6:9]
	v_mfma_f32_16x16x32_bf16 v[6:9], v[186:189], v[238:241], v[6:9]
	v_mfma_f32_16x16x32_bf16 v[50:53], v[190:193], v[198:201], v[50:53]
	v_mfma_f32_16x16x32_bf16 v[50:53], v[194:197], v[214:217], v[50:53]
	v_mfma_f32_16x16x32_bf16 v[34:37], v[190:193], v[218:221], v[34:37]
	v_mfma_f32_16x16x32_bf16 v[34:37], v[194:197], v[222:225], v[34:37]
	v_mfma_f32_16x16x32_bf16 v[18:21], v[190:193], v[226:229], v[18:21]
	v_mfma_f32_16x16x32_bf16 v[18:21], v[194:197], v[230:233], v[18:21]
	v_mfma_f32_16x16x32_bf16 v[2:5], v[190:193], v[234:237], v[2:5]
	v_mfma_f32_16x16x32_bf16 v[2:5], v[194:197], v[238:241], v[2:5]
	s_setprio 0
	s_barrier
	s_branch .LBB0_850
	.p2alignl 6, 3212836864
.LBB0_850:
	s_add_i32 vcc_lo, 0, 0x10000
	v_add_u32_e32 v0, vcc_lo, v145
	s_add_i32 vcc_hi, 0, 0x14000
	ds_read_b128 v[138:141], v0
	ds_read_b128 v[146:149], v0 offset:1024
	ds_read_b128 v[150:153], v0 offset:2048
	ds_read_b128 v[158:161], v0 offset:3072
	v_add_u32_e32 v0, vcc_hi, v145
	ds_read_b128 v[182:185], v0
	ds_read_b128 v[186:189], v0 offset:1024
	ds_read_b128 v[190:193], v0 offset:2048
	ds_read_b128 v[194:197], v0 offset:3072
	ds_read_b128 v[198:201], v157
	ds_read_b128 v[214:217], v157 offset:1024
	ds_read_b128 v[218:221], v157 offset:2048
	ds_read_b128 v[222:225], v157 offset:3072
	ds_read_b128 v[226:229], v157 offset:4096
	ds_read_b128 v[230:233], v157 offset:5120
	ds_read_b128 v[234:237], v157 offset:6144
	ds_read_b128 v[238:241], v157 offset:7168
	s_add_u32 s20, s56, 0xfffc0080
	s_addc_u32 s21, s57, -1
	s_cmp_eq_u32 s91, 12
	s_cselect_b32 s59, s76, s21
	s_cselect_b32 s58, s77, s20
	s_cselect_b32 s21, s69, s87
	s_cselect_b32 s20, s79, s86
	s_add_i32 m0, s15, 0xc000
	v_lshl_add_u64 v[142:143], s[56:57], 0, v[136:137]
	global_load_lds_dwordx4 v[142:143], off
	v_lshl_add_u64 v[142:143], v[142:143], 0, s[72:73]
	s_add_i32 m0, s15, 0xe000
	s_nop 0
	global_load_lds_dwordx4 v[142:143], off
	s_waitcnt vmcnt(8)
	s_waitcnt lgkmcnt(0)
	s_barrier
	s_setprio 1
	s_waitcnt lgkmcnt(0)
	v_mfma_f32_16x16x32_bf16 v[126:129], v[138:141], v[198:201], v[126:129]
	v_mfma_f32_16x16x32_bf16 v[126:129], v[146:149], v[214:217], v[126:129]
	v_mfma_f32_16x16x32_bf16 v[110:113], v[138:141], v[218:221], v[110:113]
	v_mfma_f32_16x16x32_bf16 v[110:113], v[146:149], v[222:225], v[110:113]
	v_mfma_f32_16x16x32_bf16 v[94:97], v[138:141], v[226:229], v[94:97]
	v_mfma_f32_16x16x32_bf16 v[94:97], v[146:149], v[230:233], v[94:97]
	v_mfma_f32_16x16x32_bf16 v[78:81], v[138:141], v[234:237], v[78:81]
	v_mfma_f32_16x16x32_bf16 v[78:81], v[146:149], v[238:241], v[78:81]
	v_mfma_f32_16x16x32_bf16 v[122:125], v[150:153], v[198:201], v[122:125]
	v_mfma_f32_16x16x32_bf16 v[122:125], v[158:161], v[214:217], v[122:125]
	v_mfma_f32_16x16x32_bf16 v[106:109], v[150:153], v[218:221], v[106:109]
	v_mfma_f32_16x16x32_bf16 v[106:109], v[158:161], v[222:225], v[106:109]
	v_mfma_f32_16x16x32_bf16 v[90:93], v[150:153], v[226:229], v[90:93]
	v_mfma_f32_16x16x32_bf16 v[90:93], v[158:161], v[230:233], v[90:93]
	v_mfma_f32_16x16x32_bf16 v[74:77], v[150:153], v[234:237], v[74:77]
	v_mfma_f32_16x16x32_bf16 v[74:77], v[158:161], v[238:241], v[74:77]
	s_setprio 0
	s_setprio 1
	v_mfma_f32_16x16x32_bf16 v[118:121], v[182:185], v[198:201], v[118:121]
	v_mfma_f32_16x16x32_bf16 v[118:121], v[186:189], v[214:217], v[118:121]
	v_mfma_f32_16x16x32_bf16 v[102:105], v[182:185], v[218:221], v[102:105]
	v_mfma_f32_16x16x32_bf16 v[102:105], v[186:189], v[222:225], v[102:105]
	v_mfma_f32_16x16x32_bf16 v[86:89], v[182:185], v[226:229], v[86:89]
	v_mfma_f32_16x16x32_bf16 v[86:89], v[186:189], v[230:233], v[86:89]
	v_mfma_f32_16x16x32_bf16 v[70:73], v[182:185], v[234:237], v[70:73]
	v_mfma_f32_16x16x32_bf16 v[70:73], v[186:189], v[238:241], v[70:73]
	v_mfma_f32_16x16x32_bf16 v[114:117], v[190:193], v[198:201], v[114:117]
	v_mfma_f32_16x16x32_bf16 v[114:117], v[194:197], v[214:217], v[114:117]
	v_mfma_f32_16x16x32_bf16 v[98:101], v[190:193], v[218:221], v[98:101]
	v_mfma_f32_16x16x32_bf16 v[98:101], v[194:197], v[222:225], v[98:101]
	v_mfma_f32_16x16x32_bf16 v[82:85], v[190:193], v[226:229], v[82:85]
	v_mfma_f32_16x16x32_bf16 v[82:85], v[194:197], v[230:233], v[82:85]
	v_mfma_f32_16x16x32_bf16 v[66:69], v[190:193], v[234:237], v[66:69]
	v_mfma_f32_16x16x32_bf16 v[66:69], v[194:197], v[238:241], v[66:69]
	s_setprio 0
	s_barrier
	ds_read_b128 v[198:201], v157 offset:16384
	ds_read_b128 v[214:217], v157 offset:17408
	ds_read_b128 v[218:221], v157 offset:18432
	ds_read_b128 v[222:225], v157 offset:19456
	ds_read_b128 v[226:229], v157 offset:20480
	ds_read_b128 v[230:233], v157 offset:21504
	ds_read_b128 v[234:237], v157 offset:22528
	ds_read_b128 v[238:241], v157 offset:23552
	v_lshl_add_u64 v[142:143], s[20:21], 0, v[130:131]
	s_add_i32 s20, vcc_lo, s14
	s_mov_b32 m0, s20
	s_nop 0
	s_nop 0
	global_load_lds_dwordx4 v[142:143], off
	v_lshl_add_u64 v[162:163], v[142:143], 0, s[72:73]
	s_add_i32 m0, s20, 0x2000
	s_add_i32 s20, vcc_hi, s14
	global_load_lds_dwordx4 v[162:163], off
	v_lshl_add_u64 v[162:163], v[142:143], 0, s[28:29]
	s_mov_b32 m0, s20
	s_nop 0
	global_load_lds_dwordx4 v[162:163], off
	v_lshl_add_u64 v[162:163], v[142:143], 0, s[82:83]
	s_add_i32 m0, s20, 0x2000
	s_nop 0
	global_load_lds_dwordx4 v[162:163], off
	v_lshl_add_u64 v[162:163], s[58:59], 0, v[132:133]
	s_mov_b32 m0, s15
	v_lshl_add_u64 v[202:203], v[162:163], 0, s[72:73]
	global_load_lds_dwordx4 v[162:163], off
	s_mov_b32 m0, s42
	s_nop 0
	global_load_lds_dwordx4 v[202:203], off
	s_waitcnt vmcnt(8)
	s_waitcnt lgkmcnt(0)
	s_barrier
	s_setprio 1
	s_waitcnt lgkmcnt(0)
	v_mfma_f32_16x16x32_bf16 v[62:65], v[138:141], v[198:201], v[62:65]
	v_mfma_f32_16x16x32_bf16 v[62:65], v[146:149], v[214:217], v[62:65]
	v_mfma_f32_16x16x32_bf16 v[46:49], v[138:141], v[218:221], v[46:49]
	v_mfma_f32_16x16x32_bf16 v[46:49], v[146:149], v[222:225], v[46:49]
	v_mfma_f32_16x16x32_bf16 v[30:33], v[138:141], v[226:229], v[30:33]
	v_mfma_f32_16x16x32_bf16 v[30:33], v[146:149], v[230:233], v[30:33]
	v_mfma_f32_16x16x32_bf16 v[14:17], v[138:141], v[234:237], v[14:17]
	v_mfma_f32_16x16x32_bf16 v[14:17], v[146:149], v[238:241], v[14:17]
	v_mfma_f32_16x16x32_bf16 v[58:61], v[150:153], v[198:201], v[58:61]
	v_mfma_f32_16x16x32_bf16 v[58:61], v[158:161], v[214:217], v[58:61]
	v_mfma_f32_16x16x32_bf16 v[42:45], v[150:153], v[218:221], v[42:45]
	v_mfma_f32_16x16x32_bf16 v[42:45], v[158:161], v[222:225], v[42:45]
	v_mfma_f32_16x16x32_bf16 v[26:29], v[150:153], v[226:229], v[26:29]
	v_mfma_f32_16x16x32_bf16 v[26:29], v[158:161], v[230:233], v[26:29]
	v_mfma_f32_16x16x32_bf16 v[10:13], v[150:153], v[234:237], v[10:13]
	v_mfma_f32_16x16x32_bf16 v[10:13], v[158:161], v[238:241], v[10:13]
	s_setprio 0
	s_setprio 1
	v_mfma_f32_16x16x32_bf16 v[54:57], v[182:185], v[198:201], v[54:57]
	v_mfma_f32_16x16x32_bf16 v[54:57], v[186:189], v[214:217], v[54:57]
	v_mfma_f32_16x16x32_bf16 v[38:41], v[182:185], v[218:221], v[38:41]
	v_mfma_f32_16x16x32_bf16 v[38:41], v[186:189], v[222:225], v[38:41]
	v_mfma_f32_16x16x32_bf16 v[22:25], v[182:185], v[226:229], v[22:25]
	v_mfma_f32_16x16x32_bf16 v[22:25], v[186:189], v[230:233], v[22:25]
	v_mfma_f32_16x16x32_bf16 v[6:9], v[182:185], v[234:237], v[6:9]
	v_mfma_f32_16x16x32_bf16 v[6:9], v[186:189], v[238:241], v[6:9]
	v_mfma_f32_16x16x32_bf16 v[50:53], v[190:193], v[198:201], v[50:53]
	v_mfma_f32_16x16x32_bf16 v[50:53], v[194:197], v[214:217], v[50:53]
	v_mfma_f32_16x16x32_bf16 v[34:37], v[190:193], v[218:221], v[34:37]
	v_mfma_f32_16x16x32_bf16 v[34:37], v[194:197], v[222:225], v[34:37]
	v_mfma_f32_16x16x32_bf16 v[18:21], v[190:193], v[226:229], v[18:21]
	v_mfma_f32_16x16x32_bf16 v[18:21], v[194:197], v[230:233], v[18:21]
	v_mfma_f32_16x16x32_bf16 v[2:5], v[190:193], v[234:237], v[2:5]
	v_mfma_f32_16x16x32_bf16 v[2:5], v[194:197], v[238:241], v[2:5]
	s_setprio 0
	s_barrier
	s_add_i32 s20, 0, 0x18000
	v_add_u32_e32 v0, s20, v145
	s_add_i32 s21, 0, 0x1c000
	ds_read_b128 v[138:141], v0
	ds_read_b128 v[146:149], v0 offset:1024
	ds_read_b128 v[150:153], v0 offset:2048
	ds_read_b128 v[158:161], v0 offset:3072
	v_add_u32_e32 v0, s21, v145
	ds_read_b128 v[182:185], v0
	ds_read_b128 v[186:189], v0 offset:1024
	ds_read_b128 v[190:193], v0 offset:2048
	ds_read_b128 v[194:197], v0 offset:3072
	ds_read_b128 v[198:201], v157 offset:32768
	ds_read_b128 v[214:217], v157 offset:33792
	ds_read_b128 v[218:221], v157 offset:34816
	ds_read_b128 v[222:225], v157 offset:35840
	ds_read_b128 v[226:229], v157 offset:36864
	ds_read_b128 v[230:233], v157 offset:37888
	ds_read_b128 v[234:237], v157 offset:38912
	ds_read_b128 v[238:241], v157 offset:39936
	s_mov_b32 m0, s43
	v_lshl_add_u64 v[202:203], v[162:163], 0, s[28:29]
	global_load_lds_dwordx4 v[202:203], off
	v_lshl_add_u64 v[202:203], v[162:163], 0, s[82:83]
	s_mov_b32 m0, s46
	s_nop 0
	global_load_lds_dwordx4 v[202:203], off
	s_waitcnt vmcnt(8)
	s_waitcnt lgkmcnt(0)
	s_barrier
	s_setprio 1
	s_waitcnt lgkmcnt(0)
	v_mfma_f32_16x16x32_bf16 v[126:129], v[138:141], v[198:201], v[126:129]
	v_mfma_f32_16x16x32_bf16 v[126:129], v[146:149], v[214:217], v[126:129]
	v_mfma_f32_16x16x32_bf16 v[110:113], v[138:141], v[218:221], v[110:113]
	v_mfma_f32_16x16x32_bf16 v[110:113], v[146:149], v[222:225], v[110:113]
	v_mfma_f32_16x16x32_bf16 v[94:97], v[138:141], v[226:229], v[94:97]
	v_mfma_f32_16x16x32_bf16 v[94:97], v[146:149], v[230:233], v[94:97]
	v_mfma_f32_16x16x32_bf16 v[78:81], v[138:141], v[234:237], v[78:81]
	v_mfma_f32_16x16x32_bf16 v[78:81], v[146:149], v[238:241], v[78:81]
	v_mfma_f32_16x16x32_bf16 v[122:125], v[150:153], v[198:201], v[122:125]
	v_mfma_f32_16x16x32_bf16 v[122:125], v[158:161], v[214:217], v[122:125]
	v_mfma_f32_16x16x32_bf16 v[106:109], v[150:153], v[218:221], v[106:109]
	v_mfma_f32_16x16x32_bf16 v[106:109], v[158:161], v[222:225], v[106:109]
	v_mfma_f32_16x16x32_bf16 v[90:93], v[150:153], v[226:229], v[90:93]
	v_mfma_f32_16x16x32_bf16 v[90:93], v[158:161], v[230:233], v[90:93]
	v_mfma_f32_16x16x32_bf16 v[74:77], v[150:153], v[234:237], v[74:77]
	v_mfma_f32_16x16x32_bf16 v[74:77], v[158:161], v[238:241], v[74:77]
	s_setprio 0
	s_setprio 1
	v_mfma_f32_16x16x32_bf16 v[118:121], v[182:185], v[198:201], v[118:121]
	v_mfma_f32_16x16x32_bf16 v[118:121], v[186:189], v[214:217], v[118:121]
	v_mfma_f32_16x16x32_bf16 v[102:105], v[182:185], v[218:221], v[102:105]
	v_mfma_f32_16x16x32_bf16 v[102:105], v[186:189], v[222:225], v[102:105]
	v_mfma_f32_16x16x32_bf16 v[86:89], v[182:185], v[226:229], v[86:89]
	v_mfma_f32_16x16x32_bf16 v[86:89], v[186:189], v[230:233], v[86:89]
	v_mfma_f32_16x16x32_bf16 v[70:73], v[182:185], v[234:237], v[70:73]
	v_mfma_f32_16x16x32_bf16 v[70:73], v[186:189], v[238:241], v[70:73]
	v_mfma_f32_16x16x32_bf16 v[114:117], v[190:193], v[198:201], v[114:117]
	v_mfma_f32_16x16x32_bf16 v[114:117], v[194:197], v[214:217], v[114:117]
	v_mfma_f32_16x16x32_bf16 v[98:101], v[190:193], v[218:221], v[98:101]
	v_mfma_f32_16x16x32_bf16 v[98:101], v[194:197], v[222:225], v[98:101]
	v_mfma_f32_16x16x32_bf16 v[82:85], v[190:193], v[226:229], v[82:85]
	v_mfma_f32_16x16x32_bf16 v[82:85], v[194:197], v[230:233], v[82:85]
	v_mfma_f32_16x16x32_bf16 v[66:69], v[190:193], v[234:237], v[66:69]
	v_mfma_f32_16x16x32_bf16 v[66:69], v[194:197], v[238:241], v[66:69]
	s_setprio 0
	s_barrier
	ds_read_b128 v[198:201], v157 offset:49152
	ds_read_b128 v[214:217], v157 offset:50176
	ds_read_b128 v[218:221], v157 offset:51200
	ds_read_b128 v[222:225], v157 offset:52224
	ds_read_b128 v[226:229], v157 offset:53248
	ds_read_b128 v[230:233], v157 offset:54272
	ds_read_b128 v[234:237], v157 offset:55296
	ds_read_b128 v[238:241], v157 offset:56320
	s_add_i32 s20, s20, s14
	s_mov_b32 m0, s20
	v_lshl_add_u64 v[202:203], v[142:143], 0, s[34:35]
	global_load_lds_dwordx4 v[202:203], off
	v_lshl_add_u64 v[202:203], v[142:143], 0, s[38:39]
	s_add_i32 m0, s20, 0x2000
	s_add_i32 s20, s21, s14
	global_load_lds_dwordx4 v[202:203], off
	v_lshl_add_u64 v[202:203], v[142:143], 0, s[44:45]
	s_mov_b32 m0, s20
	v_lshl_add_u64 v[142:143], v[142:143], 0, s[10:11]
	global_load_lds_dwordx4 v[202:203], off
	s_add_i32 m0, s20, 0x2000
	s_nop 0
	global_load_lds_dwordx4 v[142:143], off
	v_lshl_add_u64 v[142:143], v[162:163], 0, s[34:35]
	s_mov_b32 m0, s47
	s_nop 0
	global_load_lds_dwordx4 v[142:143], off
	v_lshl_add_u64 v[142:143], v[162:163], 0, s[38:39]
	s_mov_b32 m0, s96
	s_nop 0
	global_load_lds_dwordx4 v[142:143], off
	s_waitcnt vmcnt(8)
	s_waitcnt lgkmcnt(0)
	s_barrier
	s_setprio 1
	s_waitcnt lgkmcnt(0)
	v_mfma_f32_16x16x32_bf16 v[62:65], v[138:141], v[198:201], v[62:65]
	v_mfma_f32_16x16x32_bf16 v[62:65], v[146:149], v[214:217], v[62:65]
	v_mfma_f32_16x16x32_bf16 v[46:49], v[138:141], v[218:221], v[46:49]
	v_mfma_f32_16x16x32_bf16 v[46:49], v[146:149], v[222:225], v[46:49]
	v_mfma_f32_16x16x32_bf16 v[30:33], v[138:141], v[226:229], v[30:33]
	v_mfma_f32_16x16x32_bf16 v[30:33], v[146:149], v[230:233], v[30:33]
	v_mfma_f32_16x16x32_bf16 v[14:17], v[138:141], v[234:237], v[14:17]
	v_mfma_f32_16x16x32_bf16 v[14:17], v[146:149], v[238:241], v[14:17]
	v_mfma_f32_16x16x32_bf16 v[58:61], v[150:153], v[198:201], v[58:61]
	v_mfma_f32_16x16x32_bf16 v[58:61], v[158:161], v[214:217], v[58:61]
	v_mfma_f32_16x16x32_bf16 v[42:45], v[150:153], v[218:221], v[42:45]
	v_mfma_f32_16x16x32_bf16 v[42:45], v[158:161], v[222:225], v[42:45]
	v_mfma_f32_16x16x32_bf16 v[26:29], v[150:153], v[226:229], v[26:29]
	v_mfma_f32_16x16x32_bf16 v[26:29], v[158:161], v[230:233], v[26:29]
	v_mfma_f32_16x16x32_bf16 v[10:13], v[150:153], v[234:237], v[10:13]
	v_mfma_f32_16x16x32_bf16 v[10:13], v[158:161], v[238:241], v[10:13]
	s_add_i32 s91, s91, 2
	s_add_u32 s56, s56, 0x100
	s_addc_u32 s57, s57, 0
	s_add_u32 s86, s86, 0x100
	s_addc_u32 s87, s87, 0
	s_setprio 0
	s_setprio 1
	v_mfma_f32_16x16x32_bf16 v[54:57], v[182:185], v[198:201], v[54:57]
	v_mfma_f32_16x16x32_bf16 v[54:57], v[186:189], v[214:217], v[54:57]
	v_mfma_f32_16x16x32_bf16 v[38:41], v[182:185], v[218:221], v[38:41]
	v_mfma_f32_16x16x32_bf16 v[38:41], v[186:189], v[222:225], v[38:41]
	v_mfma_f32_16x16x32_bf16 v[22:25], v[182:185], v[226:229], v[22:25]
	v_mfma_f32_16x16x32_bf16 v[22:25], v[186:189], v[230:233], v[22:25]
	v_mfma_f32_16x16x32_bf16 v[6:9], v[182:185], v[234:237], v[6:9]
	v_mfma_f32_16x16x32_bf16 v[6:9], v[186:189], v[238:241], v[6:9]
	v_mfma_f32_16x16x32_bf16 v[50:53], v[190:193], v[198:201], v[50:53]
	v_mfma_f32_16x16x32_bf16 v[50:53], v[194:197], v[214:217], v[50:53]
	v_mfma_f32_16x16x32_bf16 v[34:37], v[190:193], v[218:221], v[34:37]
	v_mfma_f32_16x16x32_bf16 v[34:37], v[194:197], v[222:225], v[34:37]
	v_mfma_f32_16x16x32_bf16 v[18:21], v[190:193], v[226:229], v[18:21]
	v_mfma_f32_16x16x32_bf16 v[18:21], v[194:197], v[230:233], v[18:21]
	v_mfma_f32_16x16x32_bf16 v[2:5], v[190:193], v[234:237], v[2:5]
	v_mfma_f32_16x16x32_bf16 v[2:5], v[194:197], v[238:241], v[2:5]
	s_setprio 0
	s_barrier
	s_cmp_gt_u32 s91, 13
	s_cbranch_scc0 .LBB0_850
	s_and_b64 vcc, exec, s[62:63]
	s_cbranch_vccz .LBB0_853
	s_barrier

.LBB0_1052:
	s_add_u32 s78, s58, s68
	s_addc_u32 s79, s59, s69
	s_add_u32 s76, s78, 0x100
	s_addc_u32 s77, s79, 0
	s_and_b64 s[20:21], s[62:63], exec
	s_cselect_b32 s76, s86, s76
	s_cselect_b32 s77, s41, s77
	s_add_u32 s20, s56, s68
	s_addc_u32 s21, s57, s69
	s_add_u32 s68, s20, 0x100
	s_addc_u32 s69, s21, 0
	s_add_i32 vcc_lo, 0, 0x10000
	s_and_b64 s[20:21], s[62:63], exec
	s_cselect_b32 s62, s87, s68
	s_cselect_b32 s63, s49, s69
	s_add_i32 s21, 0, 0x14000
	v_add_u32_e32 v148, vcc_lo, v133
	v_add_u32_e32 v182, s21, v133
	ds_read_b128 v[136:139], v148
	ds_read_b128 v[140:143], v148 offset:1024
	ds_read_b128 v[144:147], v148 offset:2048
	ds_read_b128 v[148:151], v148 offset:3072
	ds_read_b128 v[152:155], v182
	ds_read_b128 v[156:159], v182 offset:1024
	ds_read_b128 v[160:163], v182 offset:2048
	ds_read_b128 v[182:185], v182 offset:3072
	s_add_i32 s93, 0, 0x18000
	s_add_i32 s69, 0, 0x1c000
	s_add_i32 s20, s93, s46
	s_add_i32 s97, vcc_lo, s46
	s_add_i32 s95, s21, s46
	s_add_i32 s68, s20, 0x2000
	s_add_i32 vcc_hi, s69, s46
	s_add_i32 m0, s22, 0xc000
	s_add_i32 s47, s22, 0xe000
	s_add_i32 s96, s97, 0x2000
	s_add_i32 s94, s95, 0x2000
	s_add_i32 vcc_lo, vcc_hi, 0x2000
	v_lshl_add_u64 v[202:203], s[78:79], 0, v[130:131]
	v_lshl_add_u64 v[230:231], v[202:203], 0, s[80:81]
	ds_read_b128 v[186:189], v135
	ds_read_b128 v[190:193], v135 offset:1024
	ds_read_b128 v[194:197], v135 offset:2048
	ds_read_b128 v[198:201], v135 offset:3072
	ds_read_b128 v[214:217], v135 offset:4096
	ds_read_b128 v[218:221], v135 offset:5120
	ds_read_b128 v[222:225], v135 offset:6144
	ds_read_b128 v[226:229], v135 offset:7168
	global_load_lds_dwordx4 v[230:231], off
	v_lshl_add_u64 v[202:203], v[202:203], 0, s[30:31]
	s_mov_b32 m0, s47
	s_nop 0
	global_load_lds_dwordx4 v[202:203], off
	s_waitcnt vmcnt(8)
	s_waitcnt lgkmcnt(0)
	s_barrier
	s_setprio 1
	s_waitcnt lgkmcnt(0)
	v_mfma_f32_16x16x32_bf16 v[126:129], v[136:139], v[186:189], v[126:129]
	v_mfma_f32_16x16x32_bf16 v[126:129], v[140:143], v[190:193], v[126:129]
	v_mfma_f32_16x16x32_bf16 v[118:121], v[136:139], v[194:197], v[118:121]
	v_mfma_f32_16x16x32_bf16 v[118:121], v[140:143], v[198:201], v[118:121]
	v_mfma_f32_16x16x32_bf16 v[102:105], v[136:139], v[214:217], v[102:105]
	v_mfma_f32_16x16x32_bf16 v[102:105], v[140:143], v[218:221], v[102:105]
	v_mfma_f32_16x16x32_bf16 v[86:89], v[136:139], v[222:225], v[86:89]
	v_mfma_f32_16x16x32_bf16 v[86:89], v[140:143], v[226:229], v[86:89]
	v_mfma_f32_16x16x32_bf16 v[122:125], v[144:147], v[186:189], v[122:125]
	v_mfma_f32_16x16x32_bf16 v[122:125], v[148:151], v[190:193], v[122:125]
	v_mfma_f32_16x16x32_bf16 v[110:113], v[144:147], v[194:197], v[110:113]
	v_mfma_f32_16x16x32_bf16 v[110:113], v[148:151], v[198:201], v[110:113]
	v_mfma_f32_16x16x32_bf16 v[94:97], v[144:147], v[214:217], v[94:97]
	v_mfma_f32_16x16x32_bf16 v[94:97], v[148:151], v[218:221], v[94:97]
	v_mfma_f32_16x16x32_bf16 v[78:81], v[144:147], v[222:225], v[78:81]
	v_mfma_f32_16x16x32_bf16 v[78:81], v[148:151], v[226:229], v[78:81]
	s_setprio 0
	s_setprio 1
	v_mfma_f32_16x16x32_bf16 v[114:117], v[152:155], v[186:189], v[114:117]
	v_mfma_f32_16x16x32_bf16 v[114:117], v[156:159], v[190:193], v[114:117]
	v_mfma_f32_16x16x32_bf16 v[98:101], v[152:155], v[194:197], v[98:101]
	v_mfma_f32_16x16x32_bf16 v[98:101], v[156:159], v[198:201], v[98:101]
	v_mfma_f32_16x16x32_bf16 v[82:85], v[152:155], v[214:217], v[82:85]
	v_mfma_f32_16x16x32_bf16 v[82:85], v[156:159], v[218:221], v[82:85]
	v_mfma_f32_16x16x32_bf16 v[70:73], v[152:155], v[222:225], v[70:73]
	v_mfma_f32_16x16x32_bf16 v[70:73], v[156:159], v[226:229], v[70:73]
	v_mfma_f32_16x16x32_bf16 v[106:109], v[160:163], v[186:189], v[106:109]
	v_mfma_f32_16x16x32_bf16 v[106:109], v[182:185], v[190:193], v[106:109]
	v_mfma_f32_16x16x32_bf16 v[90:93], v[160:163], v[194:197], v[90:93]
	v_mfma_f32_16x16x32_bf16 v[90:93], v[182:185], v[198:201], v[90:93]
	v_mfma_f32_16x16x32_bf16 v[74:77], v[160:163], v[214:217], v[74:77]
	v_mfma_f32_16x16x32_bf16 v[74:77], v[182:185], v[218:221], v[74:77]
	v_mfma_f32_16x16x32_bf16 v[66:69], v[160:163], v[222:225], v[66:69]
	v_mfma_f32_16x16x32_bf16 v[66:69], v[182:185], v[226:229], v[66:69]
	s_setprio 0
	s_barrier
	s_mov_b32 m0, s97
	v_lshl_add_u64 v[202:203], s[62:63], 0, v[0:1]
	ds_read_b128 v[186:189], v135 offset:16384
	ds_read_b128 v[190:193], v135 offset:17408
	ds_read_b128 v[194:197], v135 offset:18432
	ds_read_b128 v[198:201], v135 offset:19456
	ds_read_b128 v[214:217], v135 offset:20480
	ds_read_b128 v[218:221], v135 offset:21504
	ds_read_b128 v[222:225], v135 offset:22528
	ds_read_b128 v[226:229], v135 offset:23552
	global_load_lds_dwordx4 v[202:203], off
	v_lshl_add_u64 v[230:231], v[202:203], 0, s[36:37]
	s_mov_b32 m0, s96
	s_nop 0
	global_load_lds_dwordx4 v[230:231], off
	v_lshl_add_u64 v[230:231], v[202:203], 0, s[64:65]
	s_mov_b32 m0, s95
	s_nop 0
	global_load_lds_dwordx4 v[230:231], off
	v_lshl_add_u64 v[230:231], v[202:203], 0, s[8:9]
	s_mov_b32 m0, s94
	s_nop 0
	global_load_lds_dwordx4 v[230:231], off
	v_lshl_add_u64 v[230:231], s[76:77], 0, v[130:131]
	s_mov_b32 m0, s22
	v_lshl_add_u64 v[232:233], v[230:231], 0, s[36:37]
	global_load_lds_dwordx4 v[230:231], off
	s_mov_b32 m0, s88
	s_nop 0
	global_load_lds_dwordx4 v[232:233], off
	s_waitcnt vmcnt(8)
	s_waitcnt lgkmcnt(0)
	s_barrier
	s_setprio 1
	s_waitcnt lgkmcnt(0)
	v_mfma_f32_16x16x32_bf16 v[62:65], v[136:139], v[186:189], v[62:65]
	v_mfma_f32_16x16x32_bf16 v[62:65], v[140:143], v[190:193], v[62:65]
	v_mfma_f32_16x16x32_bf16 v[54:57], v[136:139], v[194:197], v[54:57]
	v_mfma_f32_16x16x32_bf16 v[54:57], v[140:143], v[198:201], v[54:57]
	v_mfma_f32_16x16x32_bf16 v[38:41], v[136:139], v[214:217], v[38:41]
	v_mfma_f32_16x16x32_bf16 v[38:41], v[140:143], v[218:221], v[38:41]
	v_mfma_f32_16x16x32_bf16 v[22:25], v[136:139], v[222:225], v[22:25]
	v_mfma_f32_16x16x32_bf16 v[22:25], v[140:143], v[226:229], v[22:25]
	v_mfma_f32_16x16x32_bf16 v[58:61], v[144:147], v[186:189], v[58:61]
	v_mfma_f32_16x16x32_bf16 v[58:61], v[148:151], v[190:193], v[58:61]
	v_mfma_f32_16x16x32_bf16 v[46:49], v[144:147], v[194:197], v[46:49]
	v_mfma_f32_16x16x32_bf16 v[46:49], v[148:151], v[198:201], v[46:49]
	v_mfma_f32_16x16x32_bf16 v[30:33], v[144:147], v[214:217], v[30:33]
	v_mfma_f32_16x16x32_bf16 v[30:33], v[148:151], v[218:221], v[30:33]
	v_mfma_f32_16x16x32_bf16 v[14:17], v[144:147], v[222:225], v[14:17]
	v_mfma_f32_16x16x32_bf16 v[14:17], v[148:151], v[226:229], v[14:17]
	s_setprio 0
	s_setprio 1
	v_mfma_f32_16x16x32_bf16 v[50:53], v[152:155], v[186:189], v[50:53]
	v_mfma_f32_16x16x32_bf16 v[50:53], v[156:159], v[190:193], v[50:53]
	v_mfma_f32_16x16x32_bf16 v[34:37], v[152:155], v[194:197], v[34:37]
	v_mfma_f32_16x16x32_bf16 v[34:37], v[156:159], v[198:201], v[34:37]
	v_mfma_f32_16x16x32_bf16 v[18:21], v[152:155], v[214:217], v[18:21]
	v_mfma_f32_16x16x32_bf16 v[18:21], v[156:159], v[218:221], v[18:21]
	v_mfma_f32_16x16x32_bf16 v[6:9], v[152:155], v[222:225], v[6:9]
	v_mfma_f32_16x16x32_bf16 v[6:9], v[156:159], v[226:229], v[6:9]
	v_mfma_f32_16x16x32_bf16 v[42:45], v[160:163], v[186:189], v[42:45]
	v_mfma_f32_16x16x32_bf16 v[42:45], v[182:185], v[190:193], v[42:45]
	v_mfma_f32_16x16x32_bf16 v[26:29], v[160:163], v[194:197], v[26:29]
	v_mfma_f32_16x16x32_bf16 v[26:29], v[182:185], v[198:201], v[26:29]
	v_mfma_f32_16x16x32_bf16 v[10:13], v[160:163], v[214:217], v[10:13]
	v_mfma_f32_16x16x32_bf16 v[10:13], v[182:185], v[218:221], v[10:13]
	v_mfma_f32_16x16x32_bf16 v[2:5], v[160:163], v[222:225], v[2:5]
	v_mfma_f32_16x16x32_bf16 v[2:5], v[182:185], v[226:229], v[2:5]
	s_setprio 0
	s_barrier
	v_add_u32_e32 v148, s93, v133
	v_add_u32_e32 v182, s69, v133
	ds_read_b128 v[136:139], v148
	ds_read_b128 v[140:143], v148 offset:1024
	ds_read_b128 v[144:147], v148 offset:2048
	ds_read_b128 v[148:151], v148 offset:3072
	ds_read_b128 v[152:155], v182
	ds_read_b128 v[156:159], v182 offset:1024
	ds_read_b128 v[160:163], v182 offset:2048
	ds_read_b128 v[182:185], v182 offset:3072
	s_mov_b32 m0, s89
	v_lshl_add_u64 v[232:233], v[230:231], 0, s[64:65]
	ds_read_b128 v[186:189], v135 offset:32768
	ds_read_b128 v[190:193], v135 offset:33792
	ds_read_b128 v[194:197], v135 offset:34816
	ds_read_b128 v[198:201], v135 offset:35840
	ds_read_b128 v[214:217], v135 offset:36864
	ds_read_b128 v[218:221], v135 offset:37888
	ds_read_b128 v[222:225], v135 offset:38912
	ds_read_b128 v[226:229], v135 offset:39936
	global_load_lds_dwordx4 v[232:233], off
	v_lshl_add_u64 v[232:233], v[230:231], 0, s[8:9]
	s_mov_b32 m0, s90
	s_nop 0
	global_load_lds_dwordx4 v[232:233], off
	s_waitcnt vmcnt(8)
	s_waitcnt lgkmcnt(0)
	s_barrier
	s_setprio 1
	s_waitcnt lgkmcnt(0)
	v_mfma_f32_16x16x32_bf16 v[126:129], v[136:139], v[186:189], v[126:129]
	v_mfma_f32_16x16x32_bf16 v[126:129], v[140:143], v[190:193], v[126:129]
	v_mfma_f32_16x16x32_bf16 v[118:121], v[136:139], v[194:197], v[118:121]
	v_mfma_f32_16x16x32_bf16 v[118:121], v[140:143], v[198:201], v[118:121]
	v_mfma_f32_16x16x32_bf16 v[102:105], v[136:139], v[214:217], v[102:105]
	v_mfma_f32_16x16x32_bf16 v[102:105], v[140:143], v[218:221], v[102:105]
	v_mfma_f32_16x16x32_bf16 v[86:89], v[136:139], v[222:225], v[86:89]
	v_mfma_f32_16x16x32_bf16 v[86:89], v[140:143], v[226:229], v[86:89]
	v_mfma_f32_16x16x32_bf16 v[122:125], v[144:147], v[186:189], v[122:125]
	v_mfma_f32_16x16x32_bf16 v[122:125], v[148:151], v[190:193], v[122:125]
	v_mfma_f32_16x16x32_bf16 v[110:113], v[144:147], v[194:197], v[110:113]
	v_mfma_f32_16x16x32_bf16 v[110:113], v[148:151], v[198:201], v[110:113]
	v_mfma_f32_16x16x32_bf16 v[94:97], v[144:147], v[214:217], v[94:97]
	v_mfma_f32_16x16x32_bf16 v[94:97], v[148:151], v[218:221], v[94:97]
	v_mfma_f32_16x16x32_bf16 v[78:81], v[144:147], v[222:225], v[78:81]
	v_mfma_f32_16x16x32_bf16 v[78:81], v[148:151], v[226:229], v[78:81]
	s_setprio 0
	s_setprio 1
	v_mfma_f32_16x16x32_bf16 v[114:117], v[152:155], v[186:189], v[114:117]
	v_mfma_f32_16x16x32_bf16 v[114:117], v[156:159], v[190:193], v[114:117]
	v_mfma_f32_16x16x32_bf16 v[98:101], v[152:155], v[194:197], v[98:101]
	v_mfma_f32_16x16x32_bf16 v[98:101], v[156:159], v[198:201], v[98:101]
	v_mfma_f32_16x16x32_bf16 v[82:85], v[152:155], v[214:217], v[82:85]
	v_mfma_f32_16x16x32_bf16 v[82:85], v[156:159], v[218:221], v[82:85]
	v_mfma_f32_16x16x32_bf16 v[70:73], v[152:155], v[222:225], v[70:73]
	v_mfma_f32_16x16x32_bf16 v[70:73], v[156:159], v[226:229], v[70:73]
	v_mfma_f32_16x16x32_bf16 v[106:109], v[160:163], v[186:189], v[106:109]
	v_mfma_f32_16x16x32_bf16 v[106:109], v[182:185], v[190:193], v[106:109]
	v_mfma_f32_16x16x32_bf16 v[90:93], v[160:163], v[194:197], v[90:93]
	v_mfma_f32_16x16x32_bf16 v[90:93], v[182:185], v[198:201], v[90:93]
	v_mfma_f32_16x16x32_bf16 v[74:77], v[160:163], v[214:217], v[74:77]
	v_mfma_f32_16x16x32_bf16 v[74:77], v[182:185], v[218:221], v[74:77]
	v_mfma_f32_16x16x32_bf16 v[66:69], v[160:163], v[222:225], v[66:69]
	v_mfma_f32_16x16x32_bf16 v[66:69], v[182:185], v[226:229], v[66:69]
	s_setprio 0
	s_barrier
	s_mov_b32 m0, s20
	v_lshl_add_u64 v[232:233], v[202:203], 0, s[34:35]
	ds_read_b128 v[186:189], v135 offset:49152
	ds_read_b128 v[190:193], v135 offset:50176
	ds_read_b128 v[194:197], v135 offset:51200
	ds_read_b128 v[198:201], v135 offset:52224
	ds_read_b128 v[214:217], v135 offset:53248
	ds_read_b128 v[218:221], v135 offset:54272
	ds_read_b128 v[222:225], v135 offset:55296
	ds_read_b128 v[226:229], v135 offset:56320
	global_load_lds_dwordx4 v[232:233], off
	v_lshl_add_u64 v[232:233], v[202:203], 0, s[70:71]
	s_mov_b32 m0, s68
	s_nop 0
	global_load_lds_dwordx4 v[232:233], off
	v_lshl_add_u64 v[232:233], v[202:203], 0, s[80:81]
	s_mov_b32 m0, vcc_hi
	v_lshl_add_u64 v[202:203], v[202:203], 0, s[30:31]
	global_load_lds_dwordx4 v[232:233], off
	s_mov_b32 m0, vcc_lo
	s_nop 0
	global_load_lds_dwordx4 v[202:203], off
	v_lshl_add_u64 v[202:203], v[230:231], 0, s[34:35]
	s_mov_b32 m0, s91
	s_nop 0
	global_load_lds_dwordx4 v[202:203], off
	v_lshl_add_u64 v[202:203], v[230:231], 0, s[70:71]
	s_mov_b32 m0, s92
	s_nop 0
	global_load_lds_dwordx4 v[202:203], off
	s_waitcnt vmcnt(8)
	s_waitcnt lgkmcnt(0)
	s_barrier
	s_setprio 1
	s_waitcnt lgkmcnt(0)
	v_mfma_f32_16x16x32_bf16 v[62:65], v[136:139], v[186:189], v[62:65]
	v_mfma_f32_16x16x32_bf16 v[62:65], v[140:143], v[190:193], v[62:65]
	v_mfma_f32_16x16x32_bf16 v[54:57], v[136:139], v[194:197], v[54:57]
	v_mfma_f32_16x16x32_bf16 v[54:57], v[140:143], v[198:201], v[54:57]
	v_mfma_f32_16x16x32_bf16 v[38:41], v[136:139], v[214:217], v[38:41]
	v_mfma_f32_16x16x32_bf16 v[38:41], v[140:143], v[218:221], v[38:41]
	v_mfma_f32_16x16x32_bf16 v[22:25], v[136:139], v[222:225], v[22:25]
	v_mfma_f32_16x16x32_bf16 v[22:25], v[140:143], v[226:229], v[22:25]
	v_mfma_f32_16x16x32_bf16 v[58:61], v[144:147], v[186:189], v[58:61]
	v_mfma_f32_16x16x32_bf16 v[58:61], v[148:151], v[190:193], v[58:61]
	v_mfma_f32_16x16x32_bf16 v[46:49], v[144:147], v[194:197], v[46:49]
	v_mfma_f32_16x16x32_bf16 v[46:49], v[148:151], v[198:201], v[46:49]
	v_mfma_f32_16x16x32_bf16 v[30:33], v[144:147], v[214:217], v[30:33]
	v_mfma_f32_16x16x32_bf16 v[30:33], v[148:151], v[218:221], v[30:33]
	v_mfma_f32_16x16x32_bf16 v[14:17], v[144:147], v[222:225], v[14:17]
	v_mfma_f32_16x16x32_bf16 v[14:17], v[148:151], v[226:229], v[14:17]
	s_setprio 0
	s_setprio 1
	v_mfma_f32_16x16x32_bf16 v[50:53], v[152:155], v[186:189], v[50:53]
	v_mfma_f32_16x16x32_bf16 v[50:53], v[156:159], v[190:193], v[50:53]
	v_mfma_f32_16x16x32_bf16 v[34:37], v[152:155], v[194:197], v[34:37]
	v_mfma_f32_16x16x32_bf16 v[34:37], v[156:159], v[198:201], v[34:37]
	v_mfma_f32_16x16x32_bf16 v[18:21], v[152:155], v[214:217], v[18:21]
	v_mfma_f32_16x16x32_bf16 v[18:21], v[156:159], v[218:221], v[18:21]
	v_mfma_f32_16x16x32_bf16 v[6:9], v[152:155], v[222:225], v[6:9]
	v_mfma_f32_16x16x32_bf16 v[6:9], v[156:159], v[226:229], v[6:9]
	v_mfma_f32_16x16x32_bf16 v[42:45], v[160:163], v[186:189], v[42:45]
	v_mfma_f32_16x16x32_bf16 v[42:45], v[182:185], v[190:193], v[42:45]
	v_mfma_f32_16x16x32_bf16 v[26:29], v[160:163], v[194:197], v[26:29]
	v_mfma_f32_16x16x32_bf16 v[26:29], v[182:185], v[198:201], v[26:29]
	v_mfma_f32_16x16x32_bf16 v[10:13], v[160:163], v[214:217], v[10:13]
	v_mfma_f32_16x16x32_bf16 v[10:13], v[182:185], v[218:221], v[10:13]
	v_mfma_f32_16x16x32_bf16 v[2:5], v[160:163], v[222:225], v[2:5]
	v_mfma_f32_16x16x32_bf16 v[2:5], v[182:185], v[226:229], v[2:5]
	s_setprio 0
	s_barrier
	s_andn2_b64 vcc, exec, s[60:61]
	s_mov_b64 s[62:63], -1
	s_mov_b64 s[60:61], 0
	s_mov_b64 s[68:69], 0x100
	s_cbranch_vccz .LBB0_1052
	s_and_b64 vcc, exec, s[6:7]
	s_cbranch_vccz .LBB0_1055
	s_barrier
